# write-through (sc0 sc1) stores in the P0 prologue (bf16 weights, xb, rstd, dt) on top of the stacked variant, so barrier 0's L2 writeback has less to flush
# speedup vs baseline: 1.0330x; 1.0330x over previous
.LBB0_23:
	s_waitcnt vmcnt(0)
	v_pk_mul_f32 v[0:1], v[0:1], v[8:9] op_sel_hi:[1,0]
	v_add_u32_e32 v4, 0x1040, v17
	ds_write2_b32 v4, v0, v1 offset1:1
	v_pk_mul_f32 v[0:1], v[2:3], v[8:9] op_sel_hi:[1,0]
	v_add_u32_e32 v2, 0x1048, v17
	ds_write2_b32 v2, v0, v1 offset1:1
	s_waitcnt lgkmcnt(0)
	v_or_b32_e32 v8, v96, v113
	ds_read2_b32 v[0:1], v114 offset1:65
	v_ashrrev_i32_e32 v9, 31, v8
	s_waitcnt lgkmcnt(0)
	v_cvt_pk_bf16_f32 v0, v0, v1
	ds_read2_b32 v[2:3], v114 offset0:130 offset1:195
	v_lshl_add_u64 v[6:7], v[98:99], 1, v[78:79]
	v_lshlrev_b64 v[8:9], 12, v[8:9]
	s_waitcnt lgkmcnt(0)
	v_cvt_pk_bf16_f32 v1, v2, v3
	ds_read2_b32 v[2:3], v124 offset0:4 offset1:69
	v_lshl_add_u64 v[8:9], v[6:7], 0, v[8:9]
	s_waitcnt lgkmcnt(0)
	v_cvt_pk_bf16_f32 v2, v2, v3
	ds_read2_b32 v[4:5], v124 offset0:134 offset1:199
	s_waitcnt lgkmcnt(0)
	v_cvt_pk_bf16_f32 v3, v4, v5
	global_store_dwordx4 v[8:9], v[0:3], off sc0 sc1
	v_or_b32_e32 v8, v96, v115
	v_ashrrev_i32_e32 v9, 31, v8
	ds_read2_b32 v[4:5], v114 offset0:8 offset1:73
	s_waitcnt lgkmcnt(0)
	v_cvt_pk_bf16_f32 v0, v4, v5
	ds_read2_b32 v[2:3], v114 offset0:138 offset1:203
	v_lshlrev_b64 v[8:9], 12, v[8:9]
	s_waitcnt lgkmcnt(0)
	v_cvt_pk_bf16_f32 v1, v2, v3
	ds_read2_b32 v[2:3], v124 offset0:12 offset1:77
	v_lshl_add_u64 v[8:9], v[6:7], 0, v[8:9]
	s_waitcnt lgkmcnt(0)
	v_cvt_pk_bf16_f32 v2, v2, v3
	ds_read2_b32 v[4:5], v124 offset0:142 offset1:207
	s_waitcnt lgkmcnt(0)
	v_cvt_pk_bf16_f32 v3, v4, v5
	global_store_dwordx4 v[8:9], v[0:3], off sc0 sc1
	v_or_b32_e32 v8, v96, v116
	v_ashrrev_i32_e32 v9, 31, v8
	ds_read2_b32 v[4:5], v114 offset0:16 offset1:81
	s_waitcnt lgkmcnt(0)
	v_cvt_pk_bf16_f32 v0, v4, v5
	ds_read2_b32 v[2:3], v114 offset0:146 offset1:211
	v_lshlrev_b64 v[8:9], 12, v[8:9]
	s_waitcnt lgkmcnt(0)
	v_cvt_pk_bf16_f32 v1, v2, v3
	ds_read2_b32 v[2:3], v124 offset0:20 offset1:85
	v_lshl_add_u64 v[8:9], v[6:7], 0, v[8:9]
	s_waitcnt lgkmcnt(0)
	v_cvt_pk_bf16_f32 v2, v2, v3
	ds_read2_b32 v[4:5], v124 offset0:150 offset1:215
	s_waitcnt lgkmcnt(0)
	v_cvt_pk_bf16_f32 v3, v4, v5
	global_store_dwordx4 v[8:9], v[0:3], off sc0 sc1
	v_or_b32_e32 v8, v96, v117
	v_ashrrev_i32_e32 v9, 31, v8
	ds_read2_b32 v[4:5], v114 offset0:24 offset1:89
	s_waitcnt lgkmcnt(0)
	v_cvt_pk_bf16_f32 v0, v4, v5
	ds_read2_b32 v[2:3], v114 offset0:154 offset1:219
	v_lshlrev_b64 v[8:9], 12, v[8:9]
	s_waitcnt lgkmcnt(0)
	v_cvt_pk_bf16_f32 v1, v2, v3
	ds_read2_b32 v[2:3], v124 offset0:28 offset1:93
	v_lshl_add_u64 v[8:9], v[6:7], 0, v[8:9]
	s_waitcnt lgkmcnt(0)
	v_cvt_pk_bf16_f32 v2, v2, v3
	ds_read2_b32 v[4:5], v124 offset0:158 offset1:223
	s_waitcnt lgkmcnt(0)
	v_cvt_pk_bf16_f32 v3, v4, v5
	global_store_dwordx4 v[8:9], v[0:3], off sc0 sc1
	v_or_b32_e32 v8, v96, v118
	v_ashrrev_i32_e32 v9, 31, v8
	ds_read2_b32 v[4:5], v114 offset0:32 offset1:97
	s_waitcnt lgkmcnt(0)
	v_cvt_pk_bf16_f32 v0, v4, v5
	ds_read2_b32 v[2:3], v114 offset0:162 offset1:227
	v_lshlrev_b64 v[8:9], 12, v[8:9]
	s_waitcnt lgkmcnt(0)
	v_cvt_pk_bf16_f32 v1, v2, v3
	ds_read2_b32 v[2:3], v124 offset0:36 offset1:101
	v_lshl_add_u64 v[8:9], v[6:7], 0, v[8:9]
	s_waitcnt lgkmcnt(0)
	v_cvt_pk_bf16_f32 v2, v2, v3
	ds_read2_b32 v[4:5], v124 offset0:166 offset1:231
	s_waitcnt lgkmcnt(0)
	v_cvt_pk_bf16_f32 v3, v4, v5
	global_store_dwordx4 v[8:9], v[0:3], off sc0 sc1
	v_or_b32_e32 v8, v96, v119
	v_ashrrev_i32_e32 v9, 31, v8
	ds_read2_b32 v[4:5], v114 offset0:40 offset1:105
	s_waitcnt lgkmcnt(0)
	v_cvt_pk_bf16_f32 v0, v4, v5
	ds_read2_b32 v[2:3], v114 offset0:170 offset1:235
	v_lshlrev_b64 v[8:9], 12, v[8:9]
	s_waitcnt lgkmcnt(0)
	v_cvt_pk_bf16_f32 v1, v2, v3
	ds_read2_b32 v[2:3], v124 offset0:44 offset1:109
	v_lshl_add_u64 v[8:9], v[6:7], 0, v[8:9]
	s_waitcnt lgkmcnt(0)
	v_cvt_pk_bf16_f32 v2, v2, v3
	ds_read2_b32 v[4:5], v124 offset0:174 offset1:239
	s_waitcnt lgkmcnt(0)
	v_cvt_pk_bf16_f32 v3, v4, v5
	global_store_dwordx4 v[8:9], v[0:3], off sc0 sc1
	v_or_b32_e32 v8, v96, v120
	ds_read2_b32 v[4:5], v114 offset0:48 offset1:113
	s_waitcnt lgkmcnt(0)
	v_cvt_pk_bf16_f32 v0, v4, v5
	ds_read2_b32 v[2:3], v114 offset0:178 offset1:243
	v_ashrrev_i32_e32 v9, 31, v8
	s_waitcnt lgkmcnt(0)
	v_cvt_pk_bf16_f32 v1, v2, v3
	ds_read2_b32 v[2:3], v124 offset0:52 offset1:117
	v_lshlrev_b64 v[8:9], 12, v[8:9]
	s_waitcnt lgkmcnt(0)
	v_cvt_pk_bf16_f32 v2, v2, v3
	ds_read2_b32 v[4:5], v124 offset0:182 offset1:247
	s_waitcnt lgkmcnt(0)
	v_cvt_pk_bf16_f32 v3, v4, v5
	v_lshl_add_u64 v[8:9], v[6:7], 0, v[8:9]
	ds_read2_b32 v[4:5], v114 offset0:56 offset1:121
	global_store_dwordx4 v[8:9], v[0:3], off sc0 sc1
	v_or_b32_e32 v8, v96, v121
	v_ashrrev_i32_e32 v9, 31, v8
	s_waitcnt lgkmcnt(0)
	v_cvt_pk_bf16_f32 v0, v4, v5
	ds_read2_b32 v[2:3], v114 offset0:186 offset1:251
	s_waitcnt lgkmcnt(0)
	v_cvt_pk_bf16_f32 v1, v2, v3
	ds_read2_b32 v[2:3], v124 offset0:60 offset1:125
	s_waitcnt lgkmcnt(0)
	v_cvt_pk_bf16_f32 v2, v2, v3
	ds_read2_b32 v[4:5], v124 offset0:190 offset1:255
	v_lshlrev_b64 v[8:9], 12, v[8:9]
	s_waitcnt lgkmcnt(0)
	v_cvt_pk_bf16_f32 v3, v4, v5
	v_lshl_add_u64 v[4:5], v[6:7], 0, v[8:9]
	global_store_dwordx4 v[4:5], v[0:3], off sc0 sc1
	s_waitcnt lgkmcnt(0)

.LBB0_59:
	s_waitcnt vmcnt(0)
	v_pk_mul_f32 v[0:1], v[0:1], v[8:9] op_sel_hi:[1,0]
	v_add_u32_e32 v4, 0x1040, v17
	ds_write2_b32 v4, v0, v1 offset1:1
	v_pk_mul_f32 v[0:1], v[2:3], v[8:9] op_sel_hi:[1,0]
	v_add_u32_e32 v2, 0x1048, v17
	ds_write2_b32 v2, v0, v1 offset1:1
	s_waitcnt lgkmcnt(0)
	ds_read2_b32 v[0:1], v114 offset1:65
	s_waitcnt lgkmcnt(0)
	v_cvt_pk_bf16_f32 v0, v0, v1
	ds_read2_b32 v[2:3], v114 offset0:130 offset1:195
	v_add_u32_e32 v10, 0x400, v114
	s_waitcnt lgkmcnt(0)
	v_cvt_pk_bf16_f32 v1, v2, v3
	ds_read2_b32 v[2:3], v10 offset0:4 offset1:69
	s_waitcnt lgkmcnt(0)
	v_cvt_pk_bf16_f32 v2, v2, v3
	v_and_b32_e32 v3, 0x3c0, v96
	v_add_u32_e32 v11, v123, v3
	v_add_u32_e32 v8, v11, v113
	v_ashrrev_i32_e32 v9, 31, v8
	v_lshl_add_u64 v[6:7], v[98:99], 1, v[70:71]
	v_lshlrev_b64 v[8:9], 12, v[8:9]
	v_lshl_add_u64 v[8:9], v[6:7], 0, v[8:9]
	ds_read2_b32 v[4:5], v10 offset0:134 offset1:199
	s_waitcnt lgkmcnt(0)
	v_cvt_pk_bf16_f32 v3, v4, v5
	global_store_dwordx4 v[8:9], v[0:3], off sc0 sc1
	v_add_u32_e32 v8, v11, v115
	v_ashrrev_i32_e32 v9, 31, v8
	ds_read2_b32 v[4:5], v114 offset0:8 offset1:73
	s_waitcnt lgkmcnt(0)
	v_cvt_pk_bf16_f32 v0, v4, v5
	ds_read2_b32 v[2:3], v114 offset0:138 offset1:203
	v_lshlrev_b64 v[8:9], 12, v[8:9]
	s_waitcnt lgkmcnt(0)
	v_cvt_pk_bf16_f32 v1, v2, v3
	ds_read2_b32 v[2:3], v10 offset0:12 offset1:77
	v_lshl_add_u64 v[8:9], v[6:7], 0, v[8:9]
	s_waitcnt lgkmcnt(0)
	v_cvt_pk_bf16_f32 v2, v2, v3
	ds_read2_b32 v[4:5], v10 offset0:142 offset1:207
	s_waitcnt lgkmcnt(0)
	v_cvt_pk_bf16_f32 v3, v4, v5
	global_store_dwordx4 v[8:9], v[0:3], off sc0 sc1
	v_add_u32_e32 v8, v11, v116
	v_ashrrev_i32_e32 v9, 31, v8
	ds_read2_b32 v[4:5], v114 offset0:16 offset1:81
	s_waitcnt lgkmcnt(0)
	v_cvt_pk_bf16_f32 v0, v4, v5
	ds_read2_b32 v[2:3], v114 offset0:146 offset1:211
	v_lshlrev_b64 v[8:9], 12, v[8:9]
	s_waitcnt lgkmcnt(0)
	v_cvt_pk_bf16_f32 v1, v2, v3
	ds_read2_b32 v[2:3], v10 offset0:20 offset1:85
	v_lshl_add_u64 v[8:9], v[6:7], 0, v[8:9]
	s_waitcnt lgkmcnt(0)
	v_cvt_pk_bf16_f32 v2, v2, v3
	ds_read2_b32 v[4:5], v10 offset0:150 offset1:215
	s_waitcnt lgkmcnt(0)
	v_cvt_pk_bf16_f32 v3, v4, v5
	global_store_dwordx4 v[8:9], v[0:3], off sc0 sc1
	v_add_u32_e32 v8, v11, v117
	v_ashrrev_i32_e32 v9, 31, v8
	ds_read2_b32 v[4:5], v114 offset0:24 offset1:89
	s_waitcnt lgkmcnt(0)
	v_cvt_pk_bf16_f32 v0, v4, v5
	ds_read2_b32 v[2:3], v114 offset0:154 offset1:219
	v_lshlrev_b64 v[8:9], 12, v[8:9]
	s_waitcnt lgkmcnt(0)
	v_cvt_pk_bf16_f32 v1, v2, v3
	ds_read2_b32 v[2:3], v10 offset0:28 offset1:93
	v_lshl_add_u64 v[8:9], v[6:7], 0, v[8:9]
	s_waitcnt lgkmcnt(0)
	v_cvt_pk_bf16_f32 v2, v2, v3
	ds_read2_b32 v[4:5], v10 offset0:158 offset1:223
	s_waitcnt lgkmcnt(0)
	v_cvt_pk_bf16_f32 v3, v4, v5
	global_store_dwordx4 v[8:9], v[0:3], off sc0 sc1
	v_add_u32_e32 v8, v11, v118
	v_ashrrev_i32_e32 v9, 31, v8
	ds_read2_b32 v[4:5], v114 offset0:32 offset1:97
	s_waitcnt lgkmcnt(0)
	v_cvt_pk_bf16_f32 v0, v4, v5
	ds_read2_b32 v[2:3], v114 offset0:162 offset1:227
	v_lshlrev_b64 v[8:9], 12, v[8:9]
	s_waitcnt lgkmcnt(0)
	v_cvt_pk_bf16_f32 v1, v2, v3
	ds_read2_b32 v[2:3], v10 offset0:36 offset1:101
	v_lshl_add_u64 v[8:9], v[6:7], 0, v[8:9]
	s_waitcnt lgkmcnt(0)
	v_cvt_pk_bf16_f32 v2, v2, v3
	ds_read2_b32 v[4:5], v10 offset0:166 offset1:231
	s_waitcnt lgkmcnt(0)
	v_cvt_pk_bf16_f32 v3, v4, v5
	global_store_dwordx4 v[8:9], v[0:3], off sc0 sc1
	v_add_u32_e32 v8, v11, v119
	v_ashrrev_i32_e32 v9, 31, v8
	ds_read2_b32 v[4:5], v114 offset0:40 offset1:105
	s_waitcnt lgkmcnt(0)
	v_cvt_pk_bf16_f32 v0, v4, v5
	ds_read2_b32 v[2:3], v114 offset0:170 offset1:235
	v_lshlrev_b64 v[8:9], 12, v[8:9]
	s_waitcnt lgkmcnt(0)
	v_cvt_pk_bf16_f32 v1, v2, v3
	ds_read2_b32 v[2:3], v10 offset0:44 offset1:109
	v_lshl_add_u64 v[8:9], v[6:7], 0, v[8:9]
	s_waitcnt lgkmcnt(0)
	v_cvt_pk_bf16_f32 v2, v2, v3
	ds_read2_b32 v[4:5], v10 offset0:174 offset1:239
	s_waitcnt lgkmcnt(0)
	v_cvt_pk_bf16_f32 v3, v4, v5
	global_store_dwordx4 v[8:9], v[0:3], off sc0 sc1
	v_add_u32_e32 v8, v11, v120
	ds_read2_b32 v[4:5], v114 offset0:48 offset1:113
	s_waitcnt lgkmcnt(0)
	v_cvt_pk_bf16_f32 v0, v4, v5
	ds_read2_b32 v[2:3], v114 offset0:178 offset1:243
	v_ashrrev_i32_e32 v9, 31, v8
	s_waitcnt lgkmcnt(0)
	v_cvt_pk_bf16_f32 v1, v2, v3
	ds_read2_b32 v[2:3], v10 offset0:52 offset1:117
	v_lshlrev_b64 v[8:9], 12, v[8:9]
	s_waitcnt lgkmcnt(0)
	v_cvt_pk_bf16_f32 v2, v2, v3
	ds_read2_b32 v[4:5], v10 offset0:182 offset1:247
	s_waitcnt lgkmcnt(0)
	v_cvt_pk_bf16_f32 v3, v4, v5
	v_lshl_add_u64 v[8:9], v[6:7], 0, v[8:9]
	ds_read2_b32 v[4:5], v114 offset0:56 offset1:121
	global_store_dwordx4 v[8:9], v[0:3], off sc0 sc1
	v_add_u32_e32 v8, v11, v121
	v_ashrrev_i32_e32 v9, 31, v8
	s_waitcnt lgkmcnt(0)
	v_cvt_pk_bf16_f32 v0, v4, v5
	ds_read2_b32 v[2:3], v114 offset0:186 offset1:251
	s_waitcnt lgkmcnt(0)
	v_cvt_pk_bf16_f32 v1, v2, v3
	ds_read2_b32 v[2:3], v10 offset0:60 offset1:125
	s_waitcnt lgkmcnt(0)
	v_cvt_pk_bf16_f32 v2, v2, v3
	ds_read2_b32 v[4:5], v10 offset0:190 offset1:255
	v_lshlrev_b64 v[8:9], 12, v[8:9]
	s_waitcnt lgkmcnt(0)
	v_cvt_pk_bf16_f32 v3, v4, v5
	v_lshl_add_u64 v[4:5], v[6:7], 0, v[8:9]
	global_store_dwordx4 v[4:5], v[0:3], off sc0 sc1
	s_waitcnt lgkmcnt(0)
	v_mov_b32_e32 v123, v94
	s_or_b64 exec, exec, s[18:19]
	s_and_saveexec_b64 s[18:19], s[0:1]
	s_cbranch_execz .LBB0_24

.LBB0_66:
	v_ashrrev_i32_e32 v0, 31, v123
	v_lshrrev_b32_e32 v0, 27, v0
	v_add_u32_e32 v1, v123, v0
	v_and_b32_e32 v0, 0x3ffffe0, v1
	v_lshlrev_b32_e32 v1, 1, v1
	v_and_b32_e32 v62, 0xffffffc0, v1
	v_sub_u32_e32 v0, v123, v0
	v_or_b32_e32 v96, v62, v66
	v_lshlrev_b32_e32 v0, 6, v0
	v_or_b32_e32 v4, 4, v96
	v_ashrrev_i32_e32 v1, 31, v0
	v_ashrrev_i32_e32 v97, 31, v96
	v_ashrrev_i32_e32 v5, 31, v4
	v_lshl_add_u64 v[98:99], v[0:1], 2, v[82:83]
	v_lshlrev_b64 v[2:3], 13, v[96:97]
	v_lshlrev_b64 v[4:5], 13, v[4:5]
	v_lshl_add_u64 v[2:3], v[98:99], 0, v[2:3]
	v_lshl_add_u64 v[6:7], v[98:99], 0, v[4:5]
	v_or_b32_e32 v10, 8, v96
	v_or_b32_e32 v12, 12, v96
	global_load_dwordx4 v[2:5], v[2:3], off nt
	s_nop 0
	global_load_dwordx4 v[6:9], v[6:7], off nt
	v_ashrrev_i32_e32 v11, 31, v10
	v_ashrrev_i32_e32 v13, 31, v12
	v_lshlrev_b64 v[10:11], 13, v[10:11]
	v_lshlrev_b64 v[12:13], 13, v[12:13]
	v_lshl_add_u64 v[10:11], v[98:99], 0, v[10:11]
	v_lshl_add_u64 v[14:15], v[98:99], 0, v[12:13]
	global_load_dwordx4 v[10:13], v[10:11], off nt
	s_nop 0
	global_load_dwordx4 v[14:17], v[14:15], off nt
	v_or_b32_e32 v18, 16, v96
	v_or_b32_e32 v20, 20, v96
	v_ashrrev_i32_e32 v19, 31, v18
	v_ashrrev_i32_e32 v21, 31, v20
	v_lshlrev_b64 v[18:19], 13, v[18:19]
	v_lshlrev_b64 v[20:21], 13, v[20:21]
	v_lshl_add_u64 v[18:19], v[98:99], 0, v[18:19]
	v_lshl_add_u64 v[22:23], v[98:99], 0, v[20:21]
	global_load_dwordx4 v[18:21], v[18:19], off nt
	s_nop 0
	global_load_dwordx4 v[22:25], v[22:23], off nt
	v_or_b32_e32 v26, 24, v96
	v_or_b32_e32 v28, 28, v96
	v_ashrrev_i32_e32 v27, 31, v26
	v_ashrrev_i32_e32 v29, 31, v28
	v_lshlrev_b64 v[26:27], 13, v[26:27]
	v_lshlrev_b64 v[28:29], 13, v[28:29]
	v_lshl_add_u64 v[26:27], v[98:99], 0, v[26:27]
	v_lshl_add_u64 v[30:31], v[98:99], 0, v[28:29]
	global_load_dwordx4 v[26:29], v[26:27], off nt
	s_nop 0
	global_load_dwordx4 v[30:33], v[30:31], off nt
	v_or_b32_e32 v34, 32, v96
	v_or_b32_e32 v36, 36, v96
	v_ashrrev_i32_e32 v35, 31, v34
	v_ashrrev_i32_e32 v37, 31, v36
	v_lshlrev_b64 v[34:35], 13, v[34:35]
	v_lshlrev_b64 v[36:37], 13, v[36:37]
	v_lshl_add_u64 v[34:35], v[98:99], 0, v[34:35]
	v_lshl_add_u64 v[38:39], v[98:99], 0, v[36:37]
	global_load_dwordx4 v[34:37], v[34:35], off nt
	s_nop 0
	global_load_dwordx4 v[38:41], v[38:39], off nt
	v_or_b32_e32 v42, 40, v96
	v_or_b32_e32 v44, 44, v96
	v_ashrrev_i32_e32 v43, 31, v42
	v_ashrrev_i32_e32 v45, 31, v44
	v_lshlrev_b64 v[42:43], 13, v[42:43]
	v_lshlrev_b64 v[44:45], 13, v[44:45]
	v_lshl_add_u64 v[42:43], v[98:99], 0, v[42:43]
	v_lshl_add_u64 v[46:47], v[98:99], 0, v[44:45]
	v_or_b32_e32 v50, 48, v96
	global_load_dwordx4 v[42:45], v[42:43], off nt
	s_nop 0
	global_load_dwordx4 v[46:49], v[46:47], off nt
	v_ashrrev_i32_e32 v51, 31, v50
	v_lshlrev_b64 v[50:51], 13, v[50:51]
	v_or_b32_e32 v54, 52, v96
	v_lshl_add_u64 v[50:51], v[98:99], 0, v[50:51]
	v_ashrrev_i32_e32 v55, 31, v54
	global_load_dwordx4 v[50:53], v[50:51], off nt
	v_lshlrev_b64 v[54:55], 13, v[54:55]
	v_or_b32_e32 v58, 56, v96
	v_lshl_add_u64 v[54:55], v[98:99], 0, v[54:55]
	v_ashrrev_i32_e32 v59, 31, v58
	global_load_dwordx4 v[54:57], v[54:55], off nt
	v_lshlrev_b64 v[58:59], 13, v[58:59]
	v_or_b32_e32 v96, 60, v96
	v_lshl_add_u64 v[58:59], v[98:99], 0, v[58:59]
	v_ashrrev_i32_e32 v97, 31, v96
	global_load_dwordx4 v[58:61], v[58:59], off nt
	v_lshlrev_b64 v[96:97], 13, v[96:97]
	v_lshl_add_u64 v[96:97], v[98:99], 0, v[96:97]
	global_load_dwordx4 v[96:99], v[96:97], off nt
	v_add_u32_e32 v1, 0x410, v95
	v_ashrrev_i32_e32 v63, 31, v62
	s_waitcnt vmcnt(15)
	ds_write2_b32 v95, v2, v3 offset1:1
	ds_write2_b32 v95, v4, v5 offset0:2 offset1:3
	s_waitcnt vmcnt(14)
	ds_write2_b32 v1, v6, v7 offset1:1
	v_add_u32_e32 v1, 0x418, v95
	ds_write2_b32 v1, v8, v9 offset1:1
	v_add_u32_e32 v1, 0x820, v95
	v_lshl_add_u64 v[8:9], v[62:63], 1, v[68:69]
	s_waitcnt vmcnt(13)
	ds_write2_b32 v1, v10, v11 offset1:1
	v_add_u32_e32 v1, 0x828, v95
	ds_write2_b32 v1, v12, v13 offset1:1
	v_add_u32_e32 v1, 0xc30, v95
	s_waitcnt vmcnt(12)
	ds_write2_b32 v1, v14, v15 offset1:1
	v_add_u32_e32 v1, 0xc38, v95
	ds_write2_b32 v1, v16, v17 offset1:1
	v_add_u32_e32 v1, 0x1040, v95
	s_waitcnt vmcnt(11)
	ds_write2_b32 v1, v18, v19 offset1:1
	v_add_u32_e32 v1, 0x1048, v95
	ds_write2_b32 v1, v20, v21 offset1:1
	v_add_u32_e32 v1, 0x1450, v95
	s_waitcnt vmcnt(10)
	ds_write2_b32 v1, v22, v23 offset1:1
	v_add_u32_e32 v1, 0x1458, v95
	ds_write2_b32 v1, v24, v25 offset1:1
	v_add_u32_e32 v1, 0x1860, v95
	s_waitcnt vmcnt(9)
	ds_write2_b32 v1, v26, v27 offset1:1
	v_add_u32_e32 v1, 0x1868, v95
	ds_write2_b32 v1, v28, v29 offset1:1
	v_add_u32_e32 v1, 0x1c70, v95
	s_waitcnt vmcnt(8)
	ds_write2_b32 v1, v30, v31 offset1:1
	v_add_u32_e32 v1, 0x1c78, v95
	ds_write2_b32 v1, v32, v33 offset1:1
	v_add_u32_e32 v1, 0x2080, v95
	s_waitcnt vmcnt(7)
	ds_write2_b32 v1, v34, v35 offset1:1
	v_add_u32_e32 v1, 0x2088, v95
	ds_write2_b32 v1, v36, v37 offset1:1
	v_add_u32_e32 v1, 0x2490, v95
	s_waitcnt vmcnt(6)
	ds_write2_b32 v1, v38, v39 offset1:1
	v_add_u32_e32 v1, 0x2498, v95
	ds_write2_b32 v1, v40, v41 offset1:1
	v_add_u32_e32 v1, 0x28a0, v95
	s_waitcnt vmcnt(5)
	ds_write2_b32 v1, v42, v43 offset1:1
	v_add_u32_e32 v1, 0x28a8, v95
	ds_write2_b32 v1, v44, v45 offset1:1
	v_add_u32_e32 v1, 0x2cb0, v95
	s_waitcnt vmcnt(4)
	ds_write2_b32 v1, v46, v47 offset1:1
	v_add_u32_e32 v1, 0x2cb8, v95
	ds_write2_b32 v1, v48, v49 offset1:1
	v_add_u32_e32 v1, 0x30c0, v95
	s_waitcnt vmcnt(3)
	ds_write2_b32 v1, v50, v51 offset1:1
	v_add_u32_e32 v1, 0x30c8, v95
	ds_write2_b32 v1, v52, v53 offset1:1
	v_add_u32_e32 v1, 0x34d0, v95
	s_waitcnt vmcnt(2)
	ds_write2_b32 v1, v54, v55 offset1:1
	v_add_u32_e32 v1, 0x34d8, v95
	ds_write2_b32 v1, v56, v57 offset1:1
	v_add_u32_e32 v1, 0x38e0, v95
	s_waitcnt vmcnt(1)
	ds_write2_b32 v1, v58, v59 offset1:1
	v_add_u32_e32 v1, 0x38e8, v95
	ds_write2_b32 v1, v60, v61 offset1:1
	v_add_u32_e32 v1, 0x3cf0, v95
	s_waitcnt vmcnt(0)
	ds_write2_b32 v1, v96, v97 offset1:1
	v_add_u32_e32 v1, 0x3cf8, v95
	ds_write2_b32 v1, v98, v99 offset1:1
	s_waitcnt lgkmcnt(0)
	ds_read2_b32 v[2:3], v114 offset1:65
	s_waitcnt lgkmcnt(0)
	v_cvt_pk_bf16_f32 v2, v2, v3
	ds_read2_b32 v[4:5], v114 offset0:130 offset1:195
	v_add_u32_e32 v1, 0x400, v114
	s_waitcnt lgkmcnt(0)
	v_cvt_pk_bf16_f32 v3, v4, v5
	ds_read2_b32 v[4:5], v1 offset0:4 offset1:69
	s_waitcnt lgkmcnt(0)
	v_cvt_pk_bf16_f32 v4, v4, v5
	ds_read2_b32 v[6:7], v1 offset0:134 offset1:199
	s_waitcnt lgkmcnt(0)
	v_cvt_pk_bf16_f32 v5, v6, v7
	v_or_b32_e32 v6, 0, v254
	v_or_b32_e32 v6, v0, v6
	v_ashrrev_i32_e32 v7, 31, v6
	v_lshlrev_b64 v[6:7], 12, v[6:7]
	v_lshl_add_u64 v[6:7], v[8:9], 0, v[6:7]
	ds_read2_b32 v[10:11], v114 offset0:8 offset1:73
	global_store_dwordx4 v[6:7], v[2:5], off sc0 sc1
	s_waitcnt lgkmcnt(0)
	s_nop 0
	v_cvt_pk_bf16_f32 v2, v10, v11
	ds_read2_b32 v[4:5], v114 offset0:138 offset1:203
	s_waitcnt lgkmcnt(0)
	v_cvt_pk_bf16_f32 v3, v4, v5
	ds_read2_b32 v[4:5], v1 offset0:12 offset1:77
	s_waitcnt lgkmcnt(0)
	v_cvt_pk_bf16_f32 v4, v4, v5
	ds_read2_b32 v[6:7], v1 offset0:142 offset1:207
	s_waitcnt lgkmcnt(0)
	v_cvt_pk_bf16_f32 v5, v6, v7
	v_or_b32_e32 v6, 4, v254
	v_or_b32_e32 v6, v0, v6
	v_ashrrev_i32_e32 v7, 31, v6
	v_lshlrev_b64 v[6:7], 12, v[6:7]
	v_lshl_add_u64 v[6:7], v[8:9], 0, v[6:7]
	ds_read2_b32 v[10:11], v114 offset0:16 offset1:81
	global_store_dwordx4 v[6:7], v[2:5], off sc0 sc1
	s_waitcnt lgkmcnt(0)
	s_nop 0
	v_cvt_pk_bf16_f32 v2, v10, v11
	ds_read2_b32 v[4:5], v114 offset0:146 offset1:211
	s_waitcnt lgkmcnt(0)
	v_cvt_pk_bf16_f32 v3, v4, v5
	ds_read2_b32 v[4:5], v1 offset0:20 offset1:85
	s_waitcnt lgkmcnt(0)
	v_cvt_pk_bf16_f32 v4, v4, v5
	ds_read2_b32 v[6:7], v1 offset0:150 offset1:215
	s_waitcnt lgkmcnt(0)
	v_cvt_pk_bf16_f32 v5, v6, v7
	v_or_b32_e32 v6, 8, v254
	v_or_b32_e32 v6, v0, v6
	v_ashrrev_i32_e32 v7, 31, v6
	v_lshlrev_b64 v[6:7], 12, v[6:7]
	v_lshl_add_u64 v[6:7], v[8:9], 0, v[6:7]
	ds_read2_b32 v[10:11], v114 offset0:24 offset1:89
	global_store_dwordx4 v[6:7], v[2:5], off sc0 sc1
	s_waitcnt lgkmcnt(0)
	s_nop 0
	v_cvt_pk_bf16_f32 v2, v10, v11
	ds_read2_b32 v[4:5], v114 offset0:154 offset1:219
	s_waitcnt lgkmcnt(0)
	v_cvt_pk_bf16_f32 v3, v4, v5
	ds_read2_b32 v[4:5], v1 offset0:28 offset1:93
	s_waitcnt lgkmcnt(0)
	v_cvt_pk_bf16_f32 v4, v4, v5
	ds_read2_b32 v[6:7], v1 offset0:158 offset1:223
	s_waitcnt lgkmcnt(0)
	v_cvt_pk_bf16_f32 v5, v6, v7
	v_or_b32_e32 v6, 12, v254
	v_or_b32_e32 v6, v0, v6
	v_ashrrev_i32_e32 v7, 31, v6
	v_lshlrev_b64 v[6:7], 12, v[6:7]
	v_lshl_add_u64 v[6:7], v[8:9], 0, v[6:7]
	ds_read2_b32 v[10:11], v114 offset0:32 offset1:97
	global_store_dwordx4 v[6:7], v[2:5], off sc0 sc1
	s_waitcnt lgkmcnt(0)
	s_nop 0
	v_cvt_pk_bf16_f32 v2, v10, v11
	ds_read2_b32 v[4:5], v114 offset0:162 offset1:227
	s_waitcnt lgkmcnt(0)
	v_cvt_pk_bf16_f32 v3, v4, v5
	ds_read2_b32 v[4:5], v1 offset0:36 offset1:101
	s_waitcnt lgkmcnt(0)
	v_cvt_pk_bf16_f32 v4, v4, v5
	ds_read2_b32 v[6:7], v1 offset0:166 offset1:231
	s_waitcnt lgkmcnt(0)
	v_cvt_pk_bf16_f32 v5, v6, v7
	v_or_b32_e32 v6, 32, v254
	v_or_b32_e32 v6, v0, v6
	v_ashrrev_i32_e32 v7, 31, v6
	v_lshlrev_b64 v[6:7], 12, v[6:7]
	v_lshl_add_u64 v[6:7], v[8:9], 0, v[6:7]
	ds_read2_b32 v[10:11], v114 offset0:40 offset1:105
	global_store_dwordx4 v[6:7], v[2:5], off sc0 sc1
	s_waitcnt lgkmcnt(0)
	s_nop 0
	v_cvt_pk_bf16_f32 v2, v10, v11
	ds_read2_b32 v[4:5], v114 offset0:170 offset1:235
	s_waitcnt lgkmcnt(0)
	v_cvt_pk_bf16_f32 v3, v4, v5
	ds_read2_b32 v[4:5], v1 offset0:44 offset1:109
	s_waitcnt lgkmcnt(0)
	v_cvt_pk_bf16_f32 v4, v4, v5
	ds_read2_b32 v[6:7], v1 offset0:174 offset1:239
	s_waitcnt lgkmcnt(0)
	v_cvt_pk_bf16_f32 v5, v6, v7
	v_or_b32_e32 v6, 36, v254
	v_or_b32_e32 v6, v0, v6
	v_ashrrev_i32_e32 v7, 31, v6
	v_lshlrev_b64 v[6:7], 12, v[6:7]
	v_lshl_add_u64 v[6:7], v[8:9], 0, v[6:7]
	ds_read2_b32 v[10:11], v114 offset0:48 offset1:113
	global_store_dwordx4 v[6:7], v[2:5], off sc0 sc1
	s_waitcnt lgkmcnt(0)
	s_nop 0
	v_cvt_pk_bf16_f32 v2, v10, v11
	ds_read2_b32 v[4:5], v114 offset0:178 offset1:243
	s_waitcnt lgkmcnt(0)
	v_cvt_pk_bf16_f32 v3, v4, v5
	ds_read2_b32 v[4:5], v1 offset0:52 offset1:117
	s_waitcnt lgkmcnt(0)
	v_cvt_pk_bf16_f32 v4, v4, v5
	ds_read2_b32 v[6:7], v1 offset0:182 offset1:247
	s_waitcnt lgkmcnt(0)
	v_cvt_pk_bf16_f32 v5, v6, v7
	v_or_b32_e32 v6, 40, v254
	v_or_b32_e32 v6, v0, v6
	v_ashrrev_i32_e32 v7, 31, v6
	v_lshlrev_b64 v[6:7], 12, v[6:7]
	v_lshl_add_u64 v[6:7], v[8:9], 0, v[6:7]
	ds_read2_b32 v[10:11], v114 offset0:56 offset1:121
	global_store_dwordx4 v[6:7], v[2:5], off sc0 sc1
	v_or_b32_e32 v255, 44, v254
	v_or_b32_e32 v0, v0, v255
	s_waitcnt lgkmcnt(0)
	v_cvt_pk_bf16_f32 v2, v10, v11
	ds_read2_b32 v[4:5], v114 offset0:186 offset1:251
	s_waitcnt lgkmcnt(0)
	v_cvt_pk_bf16_f32 v3, v4, v5
	ds_read2_b32 v[4:5], v1 offset0:60 offset1:125
	s_waitcnt lgkmcnt(0)
	v_cvt_pk_bf16_f32 v4, v4, v5
	ds_read2_b32 v[6:7], v1 offset0:190 offset1:255
	v_ashrrev_i32_e32 v1, 31, v0
	v_lshlrev_b64 v[0:1], 12, v[0:1]
	v_lshl_add_u64 v[0:1], v[8:9], 0, v[0:1]
	s_waitcnt lgkmcnt(0)
	v_cvt_pk_bf16_f32 v5, v6, v7
	global_store_dwordx4 v[0:1], v[2:5], off sc0 sc1
	s_waitcnt lgkmcnt(0)
	s_or_b64 exec, exec, s[0:1]
	s_and_b64 exec, exec, vcc
	s_cbranch_execz .LBB0_24

.LBB0_95:
	s_waitcnt vmcnt(0)
	v_pk_mul_f32 v[0:1], v[0:1], v[8:9] op_sel_hi:[1,0]
	v_add_u32_e32 v4, 0x1040, v17
	ds_write2_b32 v4, v0, v1 offset1:1
	v_pk_mul_f32 v[0:1], v[2:3], v[8:9] op_sel_hi:[1,0]
	v_add_u32_e32 v2, 0x1048, v17
	ds_write2_b32 v2, v0, v1 offset1:1
	s_waitcnt lgkmcnt(0)
	v_or_b32_e32 v8, v96, v113
	ds_read2_b32 v[0:1], v114 offset1:65
	v_ashrrev_i32_e32 v9, 31, v8
	s_waitcnt lgkmcnt(0)
	v_cvt_pk_bf16_f32 v0, v0, v1
	ds_read2_b32 v[2:3], v114 offset0:130 offset1:195
	v_add_u32_e32 v10, 0x400, v114
	v_lshl_add_u64 v[6:7], v[98:99], 1, v[72:73]
	v_lshlrev_b64 v[8:9], 12, v[8:9]
	s_waitcnt lgkmcnt(0)
	v_cvt_pk_bf16_f32 v1, v2, v3
	ds_read2_b32 v[2:3], v10 offset0:4 offset1:69
	v_lshl_add_u64 v[8:9], v[6:7], 0, v[8:9]
	s_waitcnt lgkmcnt(0)
	v_cvt_pk_bf16_f32 v2, v2, v3
	ds_read2_b32 v[4:5], v10 offset0:134 offset1:199
	s_waitcnt lgkmcnt(0)
	v_cvt_pk_bf16_f32 v3, v4, v5
	global_store_dwordx4 v[8:9], v[0:3], off sc0 sc1
	v_or_b32_e32 v8, v96, v115
	v_ashrrev_i32_e32 v9, 31, v8
	ds_read2_b32 v[4:5], v114 offset0:8 offset1:73
	s_waitcnt lgkmcnt(0)
	v_cvt_pk_bf16_f32 v0, v4, v5
	ds_read2_b32 v[2:3], v114 offset0:138 offset1:203
	v_lshlrev_b64 v[8:9], 12, v[8:9]
	s_waitcnt lgkmcnt(0)
	v_cvt_pk_bf16_f32 v1, v2, v3
	ds_read2_b32 v[2:3], v10 offset0:12 offset1:77
	v_lshl_add_u64 v[8:9], v[6:7], 0, v[8:9]
	s_waitcnt lgkmcnt(0)
	v_cvt_pk_bf16_f32 v2, v2, v3
	ds_read2_b32 v[4:5], v10 offset0:142 offset1:207
	s_waitcnt lgkmcnt(0)
	v_cvt_pk_bf16_f32 v3, v4, v5
	global_store_dwordx4 v[8:9], v[0:3], off sc0 sc1
	v_or_b32_e32 v8, v96, v116
	v_ashrrev_i32_e32 v9, 31, v8
	ds_read2_b32 v[4:5], v114 offset0:16 offset1:81
	s_waitcnt lgkmcnt(0)
	v_cvt_pk_bf16_f32 v0, v4, v5
	ds_read2_b32 v[2:3], v114 offset0:146 offset1:211
	v_lshlrev_b64 v[8:9], 12, v[8:9]
	s_waitcnt lgkmcnt(0)
	v_cvt_pk_bf16_f32 v1, v2, v3
	ds_read2_b32 v[2:3], v10 offset0:20 offset1:85
	v_lshl_add_u64 v[8:9], v[6:7], 0, v[8:9]
	s_waitcnt lgkmcnt(0)
	v_cvt_pk_bf16_f32 v2, v2, v3
	ds_read2_b32 v[4:5], v10 offset0:150 offset1:215
	s_waitcnt lgkmcnt(0)
	v_cvt_pk_bf16_f32 v3, v4, v5
	global_store_dwordx4 v[8:9], v[0:3], off sc0 sc1
	v_or_b32_e32 v8, v96, v117
	v_ashrrev_i32_e32 v9, 31, v8
	ds_read2_b32 v[4:5], v114 offset0:24 offset1:89
	s_waitcnt lgkmcnt(0)
	v_cvt_pk_bf16_f32 v0, v4, v5
	ds_read2_b32 v[2:3], v114 offset0:154 offset1:219
	v_lshlrev_b64 v[8:9], 12, v[8:9]
	s_waitcnt lgkmcnt(0)
	v_cvt_pk_bf16_f32 v1, v2, v3
	ds_read2_b32 v[2:3], v10 offset0:28 offset1:93
	v_lshl_add_u64 v[8:9], v[6:7], 0, v[8:9]
	s_waitcnt lgkmcnt(0)
	v_cvt_pk_bf16_f32 v2, v2, v3
	ds_read2_b32 v[4:5], v10 offset0:158 offset1:223
	s_waitcnt lgkmcnt(0)
	v_cvt_pk_bf16_f32 v3, v4, v5
	global_store_dwordx4 v[8:9], v[0:3], off sc0 sc1
	v_or_b32_e32 v8, v96, v118
	v_ashrrev_i32_e32 v9, 31, v8
	ds_read2_b32 v[4:5], v114 offset0:32 offset1:97
	s_waitcnt lgkmcnt(0)
	v_cvt_pk_bf16_f32 v0, v4, v5
	ds_read2_b32 v[2:3], v114 offset0:162 offset1:227
	v_lshlrev_b64 v[8:9], 12, v[8:9]
	s_waitcnt lgkmcnt(0)
	v_cvt_pk_bf16_f32 v1, v2, v3
	ds_read2_b32 v[2:3], v10 offset0:36 offset1:101
	v_lshl_add_u64 v[8:9], v[6:7], 0, v[8:9]
	s_waitcnt lgkmcnt(0)
	v_cvt_pk_bf16_f32 v2, v2, v3
	ds_read2_b32 v[4:5], v10 offset0:166 offset1:231
	s_waitcnt lgkmcnt(0)
	v_cvt_pk_bf16_f32 v3, v4, v5
	global_store_dwordx4 v[8:9], v[0:3], off sc0 sc1
	v_or_b32_e32 v8, v96, v119
	v_ashrrev_i32_e32 v9, 31, v8
	ds_read2_b32 v[4:5], v114 offset0:40 offset1:105
	s_waitcnt lgkmcnt(0)
	v_cvt_pk_bf16_f32 v0, v4, v5
	ds_read2_b32 v[2:3], v114 offset0:170 offset1:235
	v_lshlrev_b64 v[8:9], 12, v[8:9]
	s_waitcnt lgkmcnt(0)
	v_cvt_pk_bf16_f32 v1, v2, v3
	ds_read2_b32 v[2:3], v10 offset0:44 offset1:109
	v_lshl_add_u64 v[8:9], v[6:7], 0, v[8:9]
	s_waitcnt lgkmcnt(0)
	v_cvt_pk_bf16_f32 v2, v2, v3
	ds_read2_b32 v[4:5], v10 offset0:174 offset1:239
	s_waitcnt lgkmcnt(0)
	v_cvt_pk_bf16_f32 v3, v4, v5
	global_store_dwordx4 v[8:9], v[0:3], off sc0 sc1
	v_or_b32_e32 v8, v96, v120
	ds_read2_b32 v[4:5], v114 offset0:48 offset1:113
	s_waitcnt lgkmcnt(0)
	v_cvt_pk_bf16_f32 v0, v4, v5
	ds_read2_b32 v[2:3], v114 offset0:178 offset1:243
	v_ashrrev_i32_e32 v9, 31, v8
	s_waitcnt lgkmcnt(0)
	v_cvt_pk_bf16_f32 v1, v2, v3
	ds_read2_b32 v[2:3], v10 offset0:52 offset1:117
	v_lshlrev_b64 v[8:9], 12, v[8:9]
	s_waitcnt lgkmcnt(0)
	v_cvt_pk_bf16_f32 v2, v2, v3
	ds_read2_b32 v[4:5], v10 offset0:182 offset1:247
	s_waitcnt lgkmcnt(0)
	v_cvt_pk_bf16_f32 v3, v4, v5
	v_lshl_add_u64 v[8:9], v[6:7], 0, v[8:9]
	ds_read2_b32 v[4:5], v114 offset0:56 offset1:121
	global_store_dwordx4 v[8:9], v[0:3], off sc0 sc1
	v_or_b32_e32 v8, v96, v121
	v_ashrrev_i32_e32 v9, 31, v8
	s_waitcnt lgkmcnt(0)
	v_cvt_pk_bf16_f32 v0, v4, v5
	ds_read2_b32 v[2:3], v114 offset0:186 offset1:251
	s_waitcnt lgkmcnt(0)
	v_cvt_pk_bf16_f32 v1, v2, v3
	ds_read2_b32 v[2:3], v10 offset0:60 offset1:125
	s_waitcnt lgkmcnt(0)
	v_cvt_pk_bf16_f32 v2, v2, v3
	ds_read2_b32 v[4:5], v10 offset0:190 offset1:255
	v_lshlrev_b64 v[8:9], 12, v[8:9]
	s_waitcnt lgkmcnt(0)
	v_cvt_pk_bf16_f32 v3, v4, v5
	v_lshl_add_u64 v[4:5], v[6:7], 0, v[8:9]
	global_store_dwordx4 v[4:5], v[0:3], off sc0 sc1
	s_waitcnt lgkmcnt(0)
	s_or_b64 exec, exec, s[20:21]
	s_and_b64 exec, exec, s[0:1]
	s_cbranch_execz .LBB0_24

.LBB0_132:
	s_waitcnt vmcnt(0)
	v_pk_mul_f32 v[0:1], v[0:1], v[8:9] op_sel_hi:[1,0]
	v_add_u32_e32 v4, 0x1040, v17
	ds_write2_b32 v4, v0, v1 offset1:1
	v_pk_mul_f32 v[0:1], v[2:3], v[8:9] op_sel_hi:[1,0]
	v_add_u32_e32 v2, 0x1048, v17
	ds_write2_b32 v2, v0, v1 offset1:1
	s_waitcnt lgkmcnt(0)
	v_or_b32_e32 v8, v96, v113
	ds_read2_b32 v[0:1], v114 offset1:65
	v_ashrrev_i32_e32 v9, 31, v8
	s_waitcnt lgkmcnt(0)
	v_cvt_pk_bf16_f32 v0, v0, v1
	ds_read2_b32 v[2:3], v114 offset0:130 offset1:195
	v_add_u32_e32 v10, 0x400, v114
	v_lshl_add_u64 v[6:7], v[98:99], 1, v[74:75]
	v_lshlrev_b64 v[8:9], 12, v[8:9]
	s_waitcnt lgkmcnt(0)
	v_cvt_pk_bf16_f32 v1, v2, v3
	ds_read2_b32 v[2:3], v10 offset0:4 offset1:69
	v_lshl_add_u64 v[8:9], v[6:7], 0, v[8:9]
	s_waitcnt lgkmcnt(0)
	v_cvt_pk_bf16_f32 v2, v2, v3
	ds_read2_b32 v[4:5], v10 offset0:134 offset1:199
	s_waitcnt lgkmcnt(0)
	v_cvt_pk_bf16_f32 v3, v4, v5
	global_store_dwordx4 v[8:9], v[0:3], off sc0 sc1
	v_or_b32_e32 v8, v96, v115
	v_ashrrev_i32_e32 v9, 31, v8
	ds_read2_b32 v[4:5], v114 offset0:8 offset1:73
	s_waitcnt lgkmcnt(0)
	v_cvt_pk_bf16_f32 v0, v4, v5
	ds_read2_b32 v[2:3], v114 offset0:138 offset1:203
	v_lshlrev_b64 v[8:9], 12, v[8:9]
	s_waitcnt lgkmcnt(0)
	v_cvt_pk_bf16_f32 v1, v2, v3
	ds_read2_b32 v[2:3], v10 offset0:12 offset1:77
	v_lshl_add_u64 v[8:9], v[6:7], 0, v[8:9]
	s_waitcnt lgkmcnt(0)
	v_cvt_pk_bf16_f32 v2, v2, v3
	ds_read2_b32 v[4:5], v10 offset0:142 offset1:207
	s_waitcnt lgkmcnt(0)
	v_cvt_pk_bf16_f32 v3, v4, v5
	global_store_dwordx4 v[8:9], v[0:3], off sc0 sc1
	v_or_b32_e32 v8, v96, v116
	v_ashrrev_i32_e32 v9, 31, v8
	ds_read2_b32 v[4:5], v114 offset0:16 offset1:81
	s_waitcnt lgkmcnt(0)
	v_cvt_pk_bf16_f32 v0, v4, v5
	ds_read2_b32 v[2:3], v114 offset0:146 offset1:211
	v_lshlrev_b64 v[8:9], 12, v[8:9]
	s_waitcnt lgkmcnt(0)
	v_cvt_pk_bf16_f32 v1, v2, v3
	ds_read2_b32 v[2:3], v10 offset0:20 offset1:85
	v_lshl_add_u64 v[8:9], v[6:7], 0, v[8:9]
	s_waitcnt lgkmcnt(0)
	v_cvt_pk_bf16_f32 v2, v2, v3
	ds_read2_b32 v[4:5], v10 offset0:150 offset1:215
	s_waitcnt lgkmcnt(0)
	v_cvt_pk_bf16_f32 v3, v4, v5
	global_store_dwordx4 v[8:9], v[0:3], off sc0 sc1
	v_or_b32_e32 v8, v96, v117
	v_ashrrev_i32_e32 v9, 31, v8
	ds_read2_b32 v[4:5], v114 offset0:24 offset1:89
	s_waitcnt lgkmcnt(0)
	v_cvt_pk_bf16_f32 v0, v4, v5
	ds_read2_b32 v[2:3], v114 offset0:154 offset1:219
	v_lshlrev_b64 v[8:9], 12, v[8:9]
	s_waitcnt lgkmcnt(0)
	v_cvt_pk_bf16_f32 v1, v2, v3
	ds_read2_b32 v[2:3], v10 offset0:28 offset1:93
	v_lshl_add_u64 v[8:9], v[6:7], 0, v[8:9]
	s_waitcnt lgkmcnt(0)
	v_cvt_pk_bf16_f32 v2, v2, v3
	ds_read2_b32 v[4:5], v10 offset0:158 offset1:223
	s_waitcnt lgkmcnt(0)
	v_cvt_pk_bf16_f32 v3, v4, v5
	global_store_dwordx4 v[8:9], v[0:3], off sc0 sc1
	v_or_b32_e32 v8, v96, v118
	v_ashrrev_i32_e32 v9, 31, v8
	ds_read2_b32 v[4:5], v114 offset0:32 offset1:97
	s_waitcnt lgkmcnt(0)
	v_cvt_pk_bf16_f32 v0, v4, v5
	ds_read2_b32 v[2:3], v114 offset0:162 offset1:227
	v_lshlrev_b64 v[8:9], 12, v[8:9]
	s_waitcnt lgkmcnt(0)
	v_cvt_pk_bf16_f32 v1, v2, v3
	ds_read2_b32 v[2:3], v10 offset0:36 offset1:101
	v_lshl_add_u64 v[8:9], v[6:7], 0, v[8:9]
	s_waitcnt lgkmcnt(0)
	v_cvt_pk_bf16_f32 v2, v2, v3
	ds_read2_b32 v[4:5], v10 offset0:166 offset1:231
	s_waitcnt lgkmcnt(0)
	v_cvt_pk_bf16_f32 v3, v4, v5
	global_store_dwordx4 v[8:9], v[0:3], off sc0 sc1
	v_or_b32_e32 v8, v96, v119
	v_ashrrev_i32_e32 v9, 31, v8
	ds_read2_b32 v[4:5], v114 offset0:40 offset1:105
	s_waitcnt lgkmcnt(0)
	v_cvt_pk_bf16_f32 v0, v4, v5
	ds_read2_b32 v[2:3], v114 offset0:170 offset1:235
	v_lshlrev_b64 v[8:9], 12, v[8:9]
	s_waitcnt lgkmcnt(0)
	v_cvt_pk_bf16_f32 v1, v2, v3
	ds_read2_b32 v[2:3], v10 offset0:44 offset1:109
	v_lshl_add_u64 v[8:9], v[6:7], 0, v[8:9]
	s_waitcnt lgkmcnt(0)
	v_cvt_pk_bf16_f32 v2, v2, v3
	ds_read2_b32 v[4:5], v10 offset0:174 offset1:239
	s_waitcnt lgkmcnt(0)
	v_cvt_pk_bf16_f32 v3, v4, v5
	global_store_dwordx4 v[8:9], v[0:3], off sc0 sc1
	v_or_b32_e32 v8, v96, v120
	ds_read2_b32 v[4:5], v114 offset0:48 offset1:113
	s_waitcnt lgkmcnt(0)
	v_cvt_pk_bf16_f32 v0, v4, v5
	ds_read2_b32 v[2:3], v114 offset0:178 offset1:243
	v_ashrrev_i32_e32 v9, 31, v8
	s_waitcnt lgkmcnt(0)
	v_cvt_pk_bf16_f32 v1, v2, v3
	ds_read2_b32 v[2:3], v10 offset0:52 offset1:117
	v_lshlrev_b64 v[8:9], 12, v[8:9]
	s_waitcnt lgkmcnt(0)
	v_cvt_pk_bf16_f32 v2, v2, v3
	ds_read2_b32 v[4:5], v10 offset0:182 offset1:247
	s_waitcnt lgkmcnt(0)
	v_cvt_pk_bf16_f32 v3, v4, v5
	v_lshl_add_u64 v[8:9], v[6:7], 0, v[8:9]
	ds_read2_b32 v[4:5], v114 offset0:56 offset1:121
	global_store_dwordx4 v[8:9], v[0:3], off sc0 sc1
	v_or_b32_e32 v8, v96, v121
	v_ashrrev_i32_e32 v9, 31, v8
	s_waitcnt lgkmcnt(0)
	v_cvt_pk_bf16_f32 v0, v4, v5
	ds_read2_b32 v[2:3], v114 offset0:186 offset1:251
	s_waitcnt lgkmcnt(0)
	v_cvt_pk_bf16_f32 v1, v2, v3
	ds_read2_b32 v[2:3], v10 offset0:60 offset1:125
	s_waitcnt lgkmcnt(0)
	v_cvt_pk_bf16_f32 v2, v2, v3
	ds_read2_b32 v[4:5], v10 offset0:190 offset1:255
	v_lshlrev_b64 v[8:9], 12, v[8:9]
	s_waitcnt lgkmcnt(0)
	v_cvt_pk_bf16_f32 v3, v4, v5
	v_lshl_add_u64 v[4:5], v[6:7], 0, v[8:9]
	global_store_dwordx4 v[4:5], v[0:3], off sc0 sc1
	s_waitcnt lgkmcnt(0)
	s_or_b64 exec, exec, s[20:21]
	s_and_b64 exec, exec, s[0:1]
	s_cbranch_execz .LBB0_24

.LBB0_137:
	v_ashrrev_i32_e32 v0, 31, v123
	v_lshrrev_b32_e32 v0, 27, v0
	v_add_u32_e32 v1, v123, v0
	v_and_b32_e32 v0, 0x3ffffe0, v1
	v_lshlrev_b32_e32 v1, 1, v1
	v_and_b32_e32 v62, 0xffffffc0, v1
	v_sub_u32_e32 v0, v123, v0
	v_or_b32_e32 v96, v62, v66
	v_lshlrev_b32_e32 v0, 6, v0
	v_or_b32_e32 v4, 4, v96
	v_ashrrev_i32_e32 v1, 31, v0
	v_ashrrev_i32_e32 v97, 31, v96
	v_ashrrev_i32_e32 v5, 31, v4
	v_lshl_add_u64 v[98:99], v[0:1], 2, v[88:89]
	v_lshlrev_b64 v[2:3], 13, v[96:97]
	v_lshlrev_b64 v[4:5], 13, v[4:5]
	v_lshl_add_u64 v[2:3], v[98:99], 0, v[2:3]
	v_lshl_add_u64 v[6:7], v[98:99], 0, v[4:5]
	v_or_b32_e32 v10, 8, v96
	v_or_b32_e32 v12, 12, v96
	global_load_dwordx4 v[2:5], v[2:3], off nt
	s_nop 0
	global_load_dwordx4 v[6:9], v[6:7], off nt
	v_ashrrev_i32_e32 v11, 31, v10
	v_ashrrev_i32_e32 v13, 31, v12
	v_lshlrev_b64 v[10:11], 13, v[10:11]
	v_lshlrev_b64 v[12:13], 13, v[12:13]
	v_lshl_add_u64 v[10:11], v[98:99], 0, v[10:11]
	v_lshl_add_u64 v[14:15], v[98:99], 0, v[12:13]
	global_load_dwordx4 v[10:13], v[10:11], off nt
	s_nop 0
	global_load_dwordx4 v[14:17], v[14:15], off nt
	v_or_b32_e32 v18, 16, v96
	v_or_b32_e32 v20, 20, v96
	v_ashrrev_i32_e32 v19, 31, v18
	v_ashrrev_i32_e32 v21, 31, v20
	v_lshlrev_b64 v[18:19], 13, v[18:19]
	v_lshlrev_b64 v[20:21], 13, v[20:21]
	v_lshl_add_u64 v[18:19], v[98:99], 0, v[18:19]
	v_lshl_add_u64 v[22:23], v[98:99], 0, v[20:21]
	global_load_dwordx4 v[18:21], v[18:19], off nt
	s_nop 0
	global_load_dwordx4 v[22:25], v[22:23], off nt
	v_or_b32_e32 v26, 24, v96
	v_or_b32_e32 v28, 28, v96
	v_ashrrev_i32_e32 v27, 31, v26
	v_ashrrev_i32_e32 v29, 31, v28
	v_lshlrev_b64 v[26:27], 13, v[26:27]
	v_lshlrev_b64 v[28:29], 13, v[28:29]
	v_lshl_add_u64 v[26:27], v[98:99], 0, v[26:27]
	v_lshl_add_u64 v[30:31], v[98:99], 0, v[28:29]
	global_load_dwordx4 v[26:29], v[26:27], off nt
	s_nop 0
	global_load_dwordx4 v[30:33], v[30:31], off nt
	v_or_b32_e32 v34, 32, v96
	v_or_b32_e32 v36, 36, v96
	v_ashrrev_i32_e32 v35, 31, v34
	v_ashrrev_i32_e32 v37, 31, v36
	v_lshlrev_b64 v[34:35], 13, v[34:35]
	v_lshlrev_b64 v[36:37], 13, v[36:37]
	v_lshl_add_u64 v[34:35], v[98:99], 0, v[34:35]
	v_lshl_add_u64 v[38:39], v[98:99], 0, v[36:37]
	global_load_dwordx4 v[34:37], v[34:35], off nt
	s_nop 0
	global_load_dwordx4 v[38:41], v[38:39], off nt
	v_or_b32_e32 v42, 40, v96
	v_or_b32_e32 v44, 44, v96
	v_ashrrev_i32_e32 v43, 31, v42
	v_ashrrev_i32_e32 v45, 31, v44
	v_lshlrev_b64 v[42:43], 13, v[42:43]
	v_lshlrev_b64 v[44:45], 13, v[44:45]
	v_lshl_add_u64 v[42:43], v[98:99], 0, v[42:43]
	v_lshl_add_u64 v[46:47], v[98:99], 0, v[44:45]
	v_or_b32_e32 v50, 48, v96
	global_load_dwordx4 v[42:45], v[42:43], off nt
	s_nop 0
	global_load_dwordx4 v[46:49], v[46:47], off nt
	v_ashrrev_i32_e32 v51, 31, v50
	v_lshlrev_b64 v[50:51], 13, v[50:51]
	v_or_b32_e32 v54, 52, v96
	v_lshl_add_u64 v[50:51], v[98:99], 0, v[50:51]
	v_ashrrev_i32_e32 v55, 31, v54
	global_load_dwordx4 v[50:53], v[50:51], off nt
	v_lshlrev_b64 v[54:55], 13, v[54:55]
	v_or_b32_e32 v58, 56, v96
	v_lshl_add_u64 v[54:55], v[98:99], 0, v[54:55]
	v_ashrrev_i32_e32 v59, 31, v58
	global_load_dwordx4 v[54:57], v[54:55], off nt
	v_lshlrev_b64 v[58:59], 13, v[58:59]
	v_or_b32_e32 v96, 60, v96
	v_lshl_add_u64 v[58:59], v[98:99], 0, v[58:59]
	v_ashrrev_i32_e32 v97, 31, v96
	global_load_dwordx4 v[58:61], v[58:59], off nt
	v_lshlrev_b64 v[96:97], 13, v[96:97]
	v_lshl_add_u64 v[96:97], v[98:99], 0, v[96:97]
	global_load_dwordx4 v[96:99], v[96:97], off nt
	v_add_u32_e32 v1, 0x410, v95
	v_ashrrev_i32_e32 v63, 31, v62
	s_waitcnt vmcnt(15)
	ds_write2_b32 v95, v2, v3 offset1:1
	ds_write2_b32 v95, v4, v5 offset0:2 offset1:3
	s_waitcnt vmcnt(14)
	ds_write2_b32 v1, v6, v7 offset1:1
	v_add_u32_e32 v1, 0x418, v95
	ds_write2_b32 v1, v8, v9 offset1:1
	v_add_u32_e32 v1, 0x820, v95
	v_lshl_add_u64 v[8:9], v[62:63], 1, v[76:77]
	s_waitcnt vmcnt(13)
	ds_write2_b32 v1, v10, v11 offset1:1
	v_add_u32_e32 v1, 0x828, v95
	ds_write2_b32 v1, v12, v13 offset1:1
	v_add_u32_e32 v1, 0xc30, v95
	s_waitcnt vmcnt(12)
	ds_write2_b32 v1, v14, v15 offset1:1
	v_add_u32_e32 v1, 0xc38, v95
	ds_write2_b32 v1, v16, v17 offset1:1
	v_add_u32_e32 v1, 0x1040, v95
	s_waitcnt vmcnt(11)
	ds_write2_b32 v1, v18, v19 offset1:1
	v_add_u32_e32 v1, 0x1048, v95
	ds_write2_b32 v1, v20, v21 offset1:1
	v_add_u32_e32 v1, 0x1450, v95
	s_waitcnt vmcnt(10)
	ds_write2_b32 v1, v22, v23 offset1:1
	v_add_u32_e32 v1, 0x1458, v95
	ds_write2_b32 v1, v24, v25 offset1:1
	v_add_u32_e32 v1, 0x1860, v95
	s_waitcnt vmcnt(9)
	ds_write2_b32 v1, v26, v27 offset1:1
	v_add_u32_e32 v1, 0x1868, v95
	ds_write2_b32 v1, v28, v29 offset1:1
	v_add_u32_e32 v1, 0x1c70, v95
	s_waitcnt vmcnt(8)
	ds_write2_b32 v1, v30, v31 offset1:1
	v_add_u32_e32 v1, 0x1c78, v95
	ds_write2_b32 v1, v32, v33 offset1:1
	v_add_u32_e32 v1, 0x2080, v95
	s_waitcnt vmcnt(7)
	ds_write2_b32 v1, v34, v35 offset1:1
	v_add_u32_e32 v1, 0x2088, v95
	ds_write2_b32 v1, v36, v37 offset1:1
	v_add_u32_e32 v1, 0x2490, v95
	s_waitcnt vmcnt(6)
	ds_write2_b32 v1, v38, v39 offset1:1
	v_add_u32_e32 v1, 0x2498, v95
	ds_write2_b32 v1, v40, v41 offset1:1
	v_add_u32_e32 v1, 0x28a0, v95
	s_waitcnt vmcnt(5)
	ds_write2_b32 v1, v42, v43 offset1:1
	v_add_u32_e32 v1, 0x28a8, v95
	ds_write2_b32 v1, v44, v45 offset1:1
	v_add_u32_e32 v1, 0x2cb0, v95
	s_waitcnt vmcnt(4)
	ds_write2_b32 v1, v46, v47 offset1:1
	v_add_u32_e32 v1, 0x2cb8, v95
	ds_write2_b32 v1, v48, v49 offset1:1
	v_add_u32_e32 v1, 0x30c0, v95
	s_waitcnt vmcnt(3)
	ds_write2_b32 v1, v50, v51 offset1:1
	v_add_u32_e32 v1, 0x30c8, v95
	ds_write2_b32 v1, v52, v53 offset1:1
	v_add_u32_e32 v1, 0x34d0, v95
	s_waitcnt vmcnt(2)
	ds_write2_b32 v1, v54, v55 offset1:1
	v_add_u32_e32 v1, 0x34d8, v95
	ds_write2_b32 v1, v56, v57 offset1:1
	v_add_u32_e32 v1, 0x38e0, v95
	s_waitcnt vmcnt(1)
	ds_write2_b32 v1, v58, v59 offset1:1
	v_add_u32_e32 v1, 0x38e8, v95
	ds_write2_b32 v1, v60, v61 offset1:1
	v_add_u32_e32 v1, 0x3cf0, v95
	s_waitcnt vmcnt(0)
	ds_write2_b32 v1, v96, v97 offset1:1
	v_add_u32_e32 v1, 0x3cf8, v95
	ds_write2_b32 v1, v98, v99 offset1:1
	s_waitcnt lgkmcnt(0)
	ds_read2_b32 v[2:3], v114 offset1:65
	s_waitcnt lgkmcnt(0)
	v_cvt_pk_bf16_f32 v2, v2, v3
	ds_read2_b32 v[4:5], v114 offset0:130 offset1:195
	s_waitcnt lgkmcnt(0)
	v_cvt_pk_bf16_f32 v3, v4, v5
	ds_read2_b32 v[4:5], v124 offset0:4 offset1:69
	s_waitcnt lgkmcnt(0)
	v_cvt_pk_bf16_f32 v4, v4, v5
	ds_read2_b32 v[6:7], v124 offset0:134 offset1:199
	s_waitcnt lgkmcnt(0)
	v_cvt_pk_bf16_f32 v5, v6, v7
	v_or_b32_e32 v6, 0, v254
	v_or_b32_e32 v6, v0, v6
	v_ashrrev_i32_e32 v7, 31, v6
	v_lshlrev_b64 v[6:7], 10, v[6:7]
	v_lshl_add_u64 v[6:7], v[8:9], 0, v[6:7]
	ds_read2_b32 v[10:11], v114 offset0:8 offset1:73
	global_store_dwordx4 v[6:7], v[2:5], off sc0 sc1
	s_waitcnt lgkmcnt(0)
	s_nop 0
	v_cvt_pk_bf16_f32 v2, v10, v11
	ds_read2_b32 v[4:5], v114 offset0:138 offset1:203
	s_waitcnt lgkmcnt(0)
	v_cvt_pk_bf16_f32 v3, v4, v5
	ds_read2_b32 v[4:5], v124 offset0:12 offset1:77
	s_waitcnt lgkmcnt(0)
	v_cvt_pk_bf16_f32 v4, v4, v5
	ds_read2_b32 v[6:7], v124 offset0:142 offset1:207
	s_waitcnt lgkmcnt(0)
	v_cvt_pk_bf16_f32 v5, v6, v7
	v_or_b32_e32 v6, 4, v254
	v_or_b32_e32 v6, v0, v6
	v_ashrrev_i32_e32 v7, 31, v6
	v_lshlrev_b64 v[6:7], 10, v[6:7]
	v_lshl_add_u64 v[6:7], v[8:9], 0, v[6:7]
	ds_read2_b32 v[10:11], v114 offset0:16 offset1:81
	global_store_dwordx4 v[6:7], v[2:5], off sc0 sc1
	s_waitcnt lgkmcnt(0)
	s_nop 0
	v_cvt_pk_bf16_f32 v2, v10, v11
	ds_read2_b32 v[4:5], v114 offset0:146 offset1:211
	s_waitcnt lgkmcnt(0)
	v_cvt_pk_bf16_f32 v3, v4, v5
	ds_read2_b32 v[4:5], v124 offset0:20 offset1:85
	s_waitcnt lgkmcnt(0)
	v_cvt_pk_bf16_f32 v4, v4, v5
	ds_read2_b32 v[6:7], v124 offset0:150 offset1:215
	s_waitcnt lgkmcnt(0)
	v_cvt_pk_bf16_f32 v5, v6, v7
	v_or_b32_e32 v6, 8, v254
	v_or_b32_e32 v6, v0, v6
	v_ashrrev_i32_e32 v7, 31, v6
	v_lshlrev_b64 v[6:7], 10, v[6:7]
	v_lshl_add_u64 v[6:7], v[8:9], 0, v[6:7]
	ds_read2_b32 v[10:11], v114 offset0:24 offset1:89
	global_store_dwordx4 v[6:7], v[2:5], off sc0 sc1
	s_waitcnt lgkmcnt(0)
	s_nop 0
	v_cvt_pk_bf16_f32 v2, v10, v11
	ds_read2_b32 v[4:5], v114 offset0:154 offset1:219
	s_waitcnt lgkmcnt(0)
	v_cvt_pk_bf16_f32 v3, v4, v5
	ds_read2_b32 v[4:5], v124 offset0:28 offset1:93
	s_waitcnt lgkmcnt(0)
	v_cvt_pk_bf16_f32 v4, v4, v5
	ds_read2_b32 v[6:7], v124 offset0:158 offset1:223
	s_waitcnt lgkmcnt(0)
	v_cvt_pk_bf16_f32 v5, v6, v7
	v_or_b32_e32 v6, 12, v254
	v_or_b32_e32 v6, v0, v6
	v_ashrrev_i32_e32 v7, 31, v6
	v_lshlrev_b64 v[6:7], 10, v[6:7]
	v_lshl_add_u64 v[6:7], v[8:9], 0, v[6:7]
	ds_read2_b32 v[10:11], v114 offset0:32 offset1:97
	global_store_dwordx4 v[6:7], v[2:5], off sc0 sc1
	s_waitcnt lgkmcnt(0)
	s_nop 0
	v_cvt_pk_bf16_f32 v2, v10, v11
	ds_read2_b32 v[4:5], v114 offset0:162 offset1:227
	s_waitcnt lgkmcnt(0)
	v_cvt_pk_bf16_f32 v3, v4, v5
	ds_read2_b32 v[4:5], v124 offset0:36 offset1:101
	s_waitcnt lgkmcnt(0)
	v_cvt_pk_bf16_f32 v4, v4, v5
	ds_read2_b32 v[6:7], v124 offset0:166 offset1:231
	s_waitcnt lgkmcnt(0)
	v_cvt_pk_bf16_f32 v5, v6, v7
	v_or_b32_e32 v6, 32, v254
	v_or_b32_e32 v6, v0, v6
	v_ashrrev_i32_e32 v7, 31, v6
	v_lshlrev_b64 v[6:7], 10, v[6:7]
	v_lshl_add_u64 v[6:7], v[8:9], 0, v[6:7]
	ds_read2_b32 v[10:11], v114 offset0:40 offset1:105
	global_store_dwordx4 v[6:7], v[2:5], off sc0 sc1
	s_waitcnt lgkmcnt(0)
	s_nop 0
	v_cvt_pk_bf16_f32 v2, v10, v11
	ds_read2_b32 v[4:5], v114 offset0:170 offset1:235
	s_waitcnt lgkmcnt(0)
	v_cvt_pk_bf16_f32 v3, v4, v5
	ds_read2_b32 v[4:5], v124 offset0:44 offset1:109
	s_waitcnt lgkmcnt(0)
	v_cvt_pk_bf16_f32 v4, v4, v5
	ds_read2_b32 v[6:7], v124 offset0:174 offset1:239
	s_waitcnt lgkmcnt(0)
	v_cvt_pk_bf16_f32 v5, v6, v7
	v_or_b32_e32 v6, 36, v254
	v_or_b32_e32 v6, v0, v6
	v_ashrrev_i32_e32 v7, 31, v6
	v_lshlrev_b64 v[6:7], 10, v[6:7]
	v_lshl_add_u64 v[6:7], v[8:9], 0, v[6:7]
	ds_read2_b32 v[10:11], v114 offset0:48 offset1:113
	global_store_dwordx4 v[6:7], v[2:5], off sc0 sc1
	s_waitcnt lgkmcnt(0)
	s_nop 0
	v_cvt_pk_bf16_f32 v2, v10, v11
	ds_read2_b32 v[4:5], v114 offset0:178 offset1:243
	s_waitcnt lgkmcnt(0)
	v_cvt_pk_bf16_f32 v3, v4, v5
	ds_read2_b32 v[4:5], v124 offset0:52 offset1:117
	s_waitcnt lgkmcnt(0)
	v_cvt_pk_bf16_f32 v4, v4, v5
	ds_read2_b32 v[6:7], v124 offset0:182 offset1:247
	s_waitcnt lgkmcnt(0)
	v_cvt_pk_bf16_f32 v5, v6, v7
	v_or_b32_e32 v6, 40, v254
	v_or_b32_e32 v6, v0, v6
	v_ashrrev_i32_e32 v7, 31, v6
	v_lshlrev_b64 v[6:7], 10, v[6:7]
	v_or_b32_e32 v255, 44, v254
	v_or_b32_e32 v0, v0, v255
	v_lshl_add_u64 v[6:7], v[8:9], 0, v[6:7]
	v_ashrrev_i32_e32 v1, 31, v0
	ds_read2_b32 v[10:11], v114 offset0:56 offset1:121
	global_store_dwordx4 v[6:7], v[2:5], off sc0 sc1
	v_lshlrev_b64 v[0:1], 10, v[0:1]
	v_lshl_add_u64 v[0:1], v[8:9], 0, v[0:1]
	s_waitcnt lgkmcnt(0)
	v_cvt_pk_bf16_f32 v2, v10, v11
	ds_read2_b32 v[4:5], v114 offset0:186 offset1:251
	s_waitcnt lgkmcnt(0)
	v_cvt_pk_bf16_f32 v3, v4, v5
	ds_read2_b32 v[4:5], v124 offset0:60 offset1:125
	s_waitcnt lgkmcnt(0)
	v_cvt_pk_bf16_f32 v4, v4, v5
	ds_read2_b32 v[6:7], v124 offset0:190 offset1:255
	s_waitcnt lgkmcnt(0)
	v_cvt_pk_bf16_f32 v5, v6, v7
	global_store_dwordx4 v[0:1], v[2:5], off sc0 sc1
	s_waitcnt lgkmcnt(0)
	s_or_b64 exec, exec, s[0:1]
	s_and_b64 exec, exec, vcc
	s_cbranch_execz .LBB0_24

.LBB0_189:
	v_add_u32_e32 v7, -2, v7
	v_ashrrev_i32_e32 v9, 31, v3
	v_mov_b32_e32 v8, v3
	v_ashrrev_i32_e32 v11, 31, v2
	v_mov_b32_e32 v10, v2
	v_cmp_eq_u32_e32 vcc, 0, v7
	v_add_u32_e32 v3, s10, v3
	v_add_u32_e32 v2, s5, v2
	v_lshl_add_u64 v[10:11], v[10:11], 2, s[6:7]
	v_lshl_add_u64 v[8:9], v[8:9], 2, s[6:7]
	s_or_b64 s[8:9], vcc, s[8:9]
	global_store_dword v[10:11], v6, off sc0 sc1
	global_store_dword v[8:9], v6, off sc0 sc1
	s_andn2_b64 exec, exec, s[8:9]
	s_cbranch_execnz .LBB0_189
	s_or_b64 exec, exec, s[8:9]
	v_mad_u64_u32 v[0:1], s[6:7], v5, s4, v[0:1]
	v_cmp_ne_u32_e32 vcc, v4, v5
	s_orn2_b64 s[6:7], vcc, exec

.LBB0_193:
	v_add_u32_e32 v0, s4, v0
	v_cmp_lt_i32_e32 vcc, s5, v0
	global_store_dword v[2:3], v1, off sc0 sc1
	s_or_b64 s[6:7], vcc, s[6:7]
	v_lshl_add_u64 v[2:3], v[2:3], 0, s[0:1]
	s_andn2_b64 exec, exec, s[6:7]
	s_cbranch_execnz .LBB0_193

.LBB0_199:
	global_load_dwordx4 v[28:31], v[38:39], off offset:-4096 nt
	global_load_dwordx4 v[24:27], v[38:39], off offset:-3072 nt
	global_load_dwordx4 v[20:23], v[38:39], off offset:-2048 nt
	global_load_dwordx4 v[16:19], v[38:39], off offset:-1024 nt
	global_load_dwordx4 v[12:15], v[38:39], off nt
	global_load_dwordx4 v[8:11], v[38:39], off offset:1024 nt
	global_load_dwordx4 v[4:7], v[38:39], off offset:2048 nt
	s_waitcnt lgkmcnt(0)
	global_load_dwordx4 v[0:3], v[38:39], off offset:3072 nt
	v_lshl_add_u64 v[44:45], s[84:85], 0, v[40:41]
	v_add_co_u32_e64 v44, s[10:11], s30, v44
	s_waitcnt vmcnt(7)
	v_cvt_pk_bf16_f32 v46, v28, v29
	s_nop 0
	v_addc_co_u32_e64 v45, s[10:11], 0, v45, s[10:11]
	v_cvt_pk_bf16_f32 v47, v30, v31
	global_store_dwordx2 v[44:45], v[46:47], off sc0 sc1
	s_waitcnt vmcnt(7)
	v_cvt_pk_bf16_f32 v46, v24, v25
	v_cvt_pk_bf16_f32 v47, v26, v27
	global_store_dwordx2 v[44:45], v[46:47], off offset:512 sc0 sc1
	s_waitcnt vmcnt(7)
	v_cvt_pk_bf16_f32 v46, v20, v21
	v_cvt_pk_bf16_f32 v47, v22, v23
	global_store_dwordx2 v[44:45], v[46:47], off offset:1024 sc0 sc1
	s_waitcnt vmcnt(7)
	v_cvt_pk_bf16_f32 v46, v16, v17
	v_cvt_pk_bf16_f32 v47, v18, v19
	global_store_dwordx2 v[44:45], v[46:47], off offset:1536 sc0 sc1
	s_waitcnt vmcnt(7)
	v_cvt_pk_bf16_f32 v46, v12, v13
	v_cvt_pk_bf16_f32 v47, v14, v15
	global_store_dwordx2 v[44:45], v[46:47], off offset:2048 sc0 sc1
	s_waitcnt vmcnt(7)
	v_cvt_pk_bf16_f32 v46, v8, v9
	v_cvt_pk_bf16_f32 v47, v10, v11
	global_store_dwordx2 v[44:45], v[46:47], off offset:2560 sc0 sc1
	s_waitcnt vmcnt(7)
	v_cvt_pk_bf16_f32 v46, v4, v5
	v_cvt_pk_bf16_f32 v47, v6, v7
	global_store_dwordx2 v[44:45], v[46:47], off offset:3072 sc0 sc1
	s_waitcnt vmcnt(7)
	v_cvt_pk_bf16_f32 v46, v0, v1
	v_cvt_pk_bf16_f32 v47, v2, v3
	ds_read_b128 v[130:133], v54
	ds_read_b128 v[134:137], v54 offset:4096
	ds_read_b128 v[138:141], v55
	ds_read_b128 v[142:145], v55 offset:4096
	ds_read_b128 v[146:149], v56
	ds_read_b128 v[150:153], v56 offset:4096
	ds_read_b128 v[154:157], v57
	ds_read_b128 v[160:163], v57 offset:4096
	ds_read_b128 v[164:167], v54 offset:8192
	ds_read_b128 v[168:171], v54 offset:12288
	ds_read_b128 v[172:175], v55 offset:8192
	ds_read_b128 v[176:179], v55 offset:12288
	ds_read_b128 v[180:183], v56 offset:8192
	ds_read_b128 v[184:187], v56 offset:12288
	ds_read_b128 v[188:191], v57 offset:8192
	ds_read_b128 v[192:195], v57 offset:12288
	ds_read_b128 v[196:199], v54 offset:16384
	ds_read_b128 v[200:203], v54 offset:20480
	ds_read_b128 v[204:207], v55 offset:16384
	ds_read_b128 v[208:211], v55 offset:20480
	ds_read_b128 v[212:215], v56 offset:16384
	ds_read_b128 v[216:219], v56 offset:20480
	ds_read_b128 v[220:223], v57 offset:16384
	s_waitcnt lgkmcnt(14)
	v_pk_fma_f32 v[130:131], v[28:29], v[130:131], 0 op_sel_hi:[0,1,0]
	v_pk_fma_f32 v[132:133], v[28:29], v[132:133], 0 op_sel_hi:[0,1,0]
	v_pk_fma_f32 v[130:131], v[28:29], v[134:135], v[130:131] op_sel:[1,0,0]
	v_pk_fma_f32 v[132:133], v[28:29], v[136:137], v[132:133] op_sel:[1,0,0]
	v_mov_b32_e32 v224, v31
	v_pk_fma_f32 v[130:131], v[30:31], v[164:165], v[130:131] op_sel_hi:[0,1,1]
	v_pk_fma_f32 v[132:133], v[30:31], v[166:167], v[132:133] op_sel_hi:[0,1,1]
	v_pk_fma_f32 v[138:139], v[28:29], v[138:139], 0 op_sel_hi:[0,1,0]
	v_pk_fma_f32 v[140:141], v[28:29], v[140:141], 0 op_sel_hi:[0,1,0]
	v_pk_fma_f32 v[146:147], v[28:29], v[146:147], 0 op_sel_hi:[0,1,0]
	v_pk_fma_f32 v[148:149], v[28:29], v[148:149], 0 op_sel_hi:[0,1,0]
	s_waitcnt lgkmcnt(13)
	v_pk_fma_f32 v[130:131], v[224:225], v[168:169], v[130:131] op_sel_hi:[0,1,1]
	v_pk_fma_f32 v[132:133], v[224:225], v[170:171], v[132:133] op_sel_hi:[0,1,1]
	v_pk_fma_f32 v[154:155], v[28:29], v[154:155], 0 op_sel_hi:[0,1,0]
	v_pk_fma_f32 v[156:157], v[28:29], v[156:157], 0 op_sel_hi:[0,1,0]
	v_pk_fma_f32 v[134:135], v[28:29], v[142:143], v[138:139] op_sel:[1,0,0]
	v_pk_fma_f32 v[136:137], v[28:29], v[144:145], v[140:141] op_sel:[1,0,0]
	v_pk_fma_f32 v[138:139], v[28:29], v[150:151], v[146:147] op_sel:[1,0,0]
	v_pk_fma_f32 v[140:141], v[28:29], v[152:153], v[148:149] op_sel:[1,0,0]
	s_waitcnt lgkmcnt(6)
	v_pk_fma_f32 v[146:147], v[24:25], v[196:197], v[130:131] op_sel_hi:[0,1,1]
	v_pk_fma_f32 v[148:149], v[24:25], v[198:199], v[132:133] op_sel_hi:[0,1,1]
	ds_read_b128 v[130:133], v57 offset:20480
	v_pk_fma_f32 v[142:143], v[28:29], v[160:161], v[154:155] op_sel:[1,0,0]
	v_pk_fma_f32 v[144:145], v[28:29], v[162:163], v[156:157] op_sel:[1,0,0]
	v_pk_fma_f32 v[134:135], v[30:31], v[172:173], v[134:135] op_sel_hi:[0,1,1]
	v_pk_fma_f32 v[136:137], v[30:31], v[174:175], v[136:137] op_sel_hi:[0,1,1]
	v_pk_fma_f32 v[138:139], v[30:31], v[180:181], v[138:139] op_sel_hi:[0,1,1]
	v_pk_fma_f32 v[140:141], v[30:31], v[182:183], v[140:141] op_sel_hi:[0,1,1]
	v_pk_fma_f32 v[142:143], v[30:31], v[188:189], v[142:143] op_sel_hi:[0,1,1]
	v_pk_fma_f32 v[144:145], v[30:31], v[190:191], v[144:145] op_sel_hi:[0,1,1]
	v_pk_fma_f32 v[134:135], v[224:225], v[176:177], v[134:135] op_sel_hi:[0,1,1]
	v_pk_fma_f32 v[136:137], v[224:225], v[178:179], v[136:137] op_sel_hi:[0,1,1]
	v_pk_fma_f32 v[138:139], v[224:225], v[184:185], v[138:139] op_sel_hi:[0,1,1]
	v_pk_fma_f32 v[140:141], v[224:225], v[186:187], v[140:141] op_sel_hi:[0,1,1]
	v_pk_fma_f32 v[142:143], v[224:225], v[192:193], v[142:143] op_sel_hi:[0,1,1]
	v_pk_fma_f32 v[144:145], v[224:225], v[194:195], v[144:145] op_sel_hi:[0,1,1]
	s_waitcnt lgkmcnt(5)
	v_pk_fma_f32 v[134:135], v[24:25], v[204:205], v[134:135] op_sel_hi:[0,1,1]
	v_pk_fma_f32 v[136:137], v[24:25], v[206:207], v[136:137] op_sel_hi:[0,1,1]
	s_waitcnt lgkmcnt(3)
	v_pk_fma_f32 v[138:139], v[24:25], v[212:213], v[138:139] op_sel_hi:[0,1,1]
	v_pk_fma_f32 v[140:141], v[24:25], v[214:215], v[140:141] op_sel_hi:[0,1,1]
	s_waitcnt lgkmcnt(1)
	v_pk_fma_f32 v[142:143], v[24:25], v[220:221], v[142:143] op_sel_hi:[0,1,1]
	v_pk_fma_f32 v[144:145], v[24:25], v[222:223], v[144:145] op_sel_hi:[0,1,1]
	v_pk_fma_f32 v[150:151], v[24:25], v[208:209], v[134:135] op_sel:[1,0,0]
	v_pk_fma_f32 v[152:153], v[24:25], v[210:211], v[136:137] op_sel:[1,0,0]
	v_pk_fma_f32 v[154:155], v[24:25], v[216:217], v[138:139] op_sel:[1,0,0]
	v_pk_fma_f32 v[156:157], v[24:25], v[218:219], v[140:141] op_sel:[1,0,0]
	ds_read_b128 v[134:137], v54 offset:24576
	s_waitcnt lgkmcnt(1)
	v_pk_fma_f32 v[160:161], v[24:25], v[130:131], v[142:143] op_sel:[1,0,0]
	v_pk_fma_f32 v[162:163], v[24:25], v[132:133], v[144:145] op_sel:[1,0,0]
	ds_read_b128 v[130:133], v54 offset:28672
	ds_read_b128 v[138:141], v55 offset:24576
	v_pk_fma_f32 v[146:147], v[24:25], v[200:201], v[146:147] op_sel:[1,0,0]
	v_pk_fma_f32 v[148:149], v[24:25], v[202:203], v[148:149] op_sel:[1,0,0]
	s_waitcnt lgkmcnt(2)
	v_pk_fma_f32 v[164:165], v[26:27], v[134:135], v[146:147] op_sel_hi:[0,1,1]
	v_pk_fma_f32 v[166:167], v[26:27], v[136:137], v[148:149] op_sel_hi:[0,1,1]
	ds_read_b128 v[134:137], v55 offset:28672
	ds_read_b128 v[142:145], v56 offset:24576
	s_waitcnt lgkmcnt(2)
	v_pk_fma_f32 v[150:151], v[26:27], v[138:139], v[150:151] op_sel_hi:[0,1,1]
	v_pk_fma_f32 v[152:153], v[26:27], v[140:141], v[152:153] op_sel_hi:[0,1,1]
	ds_read_b128 v[138:141], v57 offset:24576
	ds_read_b128 v[146:149], v56 offset:28672
	v_mul_f32_e32 v168, v17, v17
	s_waitcnt lgkmcnt(2)
	v_pk_fma_f32 v[154:155], v[26:27], v[142:143], v[154:155] op_sel_hi:[0,1,1]
	v_pk_fma_f32 v[156:157], v[26:27], v[144:145], v[156:157] op_sel_hi:[0,1,1]
	s_waitcnt lgkmcnt(1)
	v_pk_fma_f32 v[138:139], v[26:27], v[138:139], v[160:161] op_sel_hi:[0,1,1]
	v_mov_b32_e32 v160, v27
	ds_read_b128 v[142:145], v57 offset:28672
	v_pk_fma_f32 v[140:141], v[26:27], v[140:141], v[162:163] op_sel_hi:[0,1,1]
	v_pk_fma_f32 v[162:163], v[160:161], v[130:131], v[164:165] op_sel_hi:[0,1,1]
	v_pk_fma_f32 v[164:165], v[160:161], v[132:133], v[166:167] op_sel_hi:[0,1,1]
	ds_read_b128 v[130:133], v54 offset:32768
	v_pk_fma_f32 v[150:151], v[160:161], v[134:135], v[150:151] op_sel_hi:[0,1,1]
	v_pk_fma_f32 v[152:153], v[160:161], v[136:137], v[152:153] op_sel_hi:[0,1,1]
	s_waitcnt lgkmcnt(2)
	v_pk_fma_f32 v[154:155], v[160:161], v[146:147], v[154:155] op_sel_hi:[0,1,1]
	v_pk_fma_f32 v[156:157], v[160:161], v[148:149], v[156:157] op_sel_hi:[0,1,1]
	s_waitcnt lgkmcnt(1)
	v_pk_fma_f32 v[166:167], v[160:161], v[142:143], v[138:139] op_sel_hi:[0,1,1]
	v_pk_fma_f32 v[160:161], v[160:161], v[144:145], v[140:141] op_sel_hi:[0,1,1]
	ds_read_b128 v[134:137], v54 offset:36864
	ds_read_b128 v[138:141], v55 offset:32768
	s_waitcnt lgkmcnt(2)
	v_pk_fma_f32 v[162:163], v[20:21], v[130:131], v[162:163] op_sel_hi:[0,1,1]
	v_pk_fma_f32 v[164:165], v[20:21], v[132:133], v[164:165] op_sel_hi:[0,1,1]
	ds_read_b128 v[130:133], v55 offset:36864
	ds_read_b128 v[142:145], v56 offset:32768
	s_waitcnt lgkmcnt(2)
	v_pk_fma_f32 v[150:151], v[20:21], v[138:139], v[150:151] op_sel_hi:[0,1,1]
	v_pk_fma_f32 v[152:153], v[20:21], v[140:141], v[152:153] op_sel_hi:[0,1,1]
	ds_read_b128 v[138:141], v57 offset:32768
	ds_read_b128 v[146:149], v56 offset:36864
	s_waitcnt lgkmcnt(2)
	v_pk_fma_f32 v[154:155], v[20:21], v[142:143], v[154:155] op_sel_hi:[0,1,1]
	v_pk_fma_f32 v[156:157], v[20:21], v[144:145], v[156:157] op_sel_hi:[0,1,1]
	ds_read_b128 v[142:145], v57 offset:36864
	s_waitcnt lgkmcnt(2)
	v_pk_fma_f32 v[138:139], v[20:21], v[138:139], v[166:167] op_sel_hi:[0,1,1]
	v_pk_fma_f32 v[140:141], v[20:21], v[140:141], v[160:161] op_sel_hi:[0,1,1]
	v_pk_fma_f32 v[150:151], v[20:21], v[130:131], v[150:151] op_sel:[1,0,0]
	v_pk_fma_f32 v[152:153], v[20:21], v[132:133], v[152:153] op_sel:[1,0,0]
	ds_read_b128 v[130:133], v54 offset:40960
	v_pk_fma_f32 v[160:161], v[20:21], v[134:135], v[162:163] op_sel:[1,0,0]
	v_pk_fma_f32 v[162:163], v[20:21], v[136:137], v[164:165] op_sel:[1,0,0]
	s_waitcnt lgkmcnt(1)
	v_pk_fma_f32 v[164:165], v[20:21], v[142:143], v[138:139] op_sel:[1,0,0]
	v_pk_fma_f32 v[166:167], v[20:21], v[144:145], v[140:141] op_sel:[1,0,0]
	ds_read_b128 v[134:137], v54 offset:45056
	ds_read_b128 v[138:141], v55 offset:40960
	s_waitcnt lgkmcnt(2)
	v_pk_fma_f32 v[160:161], v[22:23], v[130:131], v[160:161] op_sel_hi:[0,1,1]
	v_pk_fma_f32 v[162:163], v[22:23], v[132:133], v[162:163] op_sel_hi:[0,1,1]
	ds_read_b128 v[130:133], v55 offset:45056
	ds_read_b128 v[142:145], v56 offset:40960
	v_pk_fma_f32 v[154:155], v[20:21], v[146:147], v[154:155] op_sel:[1,0,0]
	v_pk_fma_f32 v[156:157], v[20:21], v[148:149], v[156:157] op_sel:[1,0,0]
	s_waitcnt lgkmcnt(2)
	v_pk_fma_f32 v[150:151], v[22:23], v[138:139], v[150:151] op_sel_hi:[0,1,1]
	v_pk_fma_f32 v[152:153], v[22:23], v[140:141], v[152:153] op_sel_hi:[0,1,1]
	ds_read_b128 v[138:141], v57 offset:40960
	ds_read_b128 v[146:149], v56 offset:45056
	s_waitcnt lgkmcnt(2)
	v_pk_fma_f32 v[154:155], v[22:23], v[142:143], v[154:155] op_sel_hi:[0,1,1]
	v_pk_fma_f32 v[156:157], v[22:23], v[144:145], v[156:157] op_sel_hi:[0,1,1]
	ds_read_b128 v[142:145], v57 offset:45056
	s_waitcnt lgkmcnt(2)
	v_pk_fma_f32 v[138:139], v[22:23], v[138:139], v[164:165] op_sel_hi:[0,1,1]
	v_mov_b32_e32 v164, v23
	v_pk_fma_f32 v[134:135], v[164:165], v[134:135], v[160:161] op_sel_hi:[0,1,1]
	v_pk_fma_f32 v[136:137], v[164:165], v[136:137], v[162:163] op_sel_hi:[0,1,1]
	s_waitcnt lgkmcnt(1)
	v_pk_fma_f32 v[146:147], v[164:165], v[146:147], v[154:155] op_sel_hi:[0,1,1]
	v_pk_fma_f32 v[148:149], v[164:165], v[148:149], v[156:157] op_sel_hi:[0,1,1]
	v_mov_b32_e32 v154, v28
	v_mov_b32_e32 v156, v29
	v_mov_b32_e32 v160, v30
	v_mov_b32_e32 v162, v31
	ds_read_b128 v[28:31], v54 offset:49152
	v_pk_fma_f32 v[140:141], v[22:23], v[140:141], v[166:167] op_sel_hi:[0,1,1]
	v_pk_fma_f32 v[150:151], v[164:165], v[130:131], v[150:151] op_sel_hi:[0,1,1]
	v_pk_fma_f32 v[152:153], v[164:165], v[132:133], v[152:153] op_sel_hi:[0,1,1]
	s_waitcnt lgkmcnt(1)
	v_pk_fma_f32 v[142:143], v[164:165], v[142:143], v[138:139] op_sel_hi:[0,1,1]
	v_pk_fma_f32 v[144:145], v[164:165], v[144:145], v[140:141] op_sel_hi:[0,1,1]
	v_mov_b32_e32 v155, v24
	v_mov_b32_e32 v157, v25
	v_mov_b32_e32 v161, v26
	v_mov_b32_e32 v163, v27
	ds_read_b128 v[24:27], v54 offset:53248
	ds_read_b128 v[130:133], v55 offset:49152
	s_waitcnt lgkmcnt(2)
	v_pk_fma_f32 v[164:165], v[16:17], v[28:29], v[134:135] op_sel_hi:[0,1,1]
	v_pk_fma_f32 v[166:167], v[16:17], v[30:31], v[136:137] op_sel_hi:[0,1,1]
	ds_read_b128 v[28:31], v55 offset:53248
	ds_read_b128 v[134:137], v56 offset:49152
	v_pk_mul_f32 v[156:157], v[156:157], v[156:157]
	s_waitcnt lgkmcnt(2)
	v_pk_fma_f32 v[150:151], v[16:17], v[130:131], v[150:151] op_sel_hi:[0,1,1]
	v_pk_fma_f32 v[152:153], v[16:17], v[132:133], v[152:153] op_sel_hi:[0,1,1]
	ds_read_b128 v[130:133], v57 offset:49152
	ds_read_b128 v[138:141], v56 offset:53248
	s_waitcnt lgkmcnt(2)
	v_pk_fma_f32 v[146:147], v[16:17], v[134:135], v[146:147] op_sel_hi:[0,1,1]
	v_pk_fma_f32 v[148:149], v[16:17], v[136:137], v[148:149] op_sel_hi:[0,1,1]
	ds_read_b128 v[134:137], v57 offset:53248
	v_pk_fma_f32 v[154:155], v[154:155], v[154:155], v[156:157]
	v_pk_mul_f32 v[156:157], v[162:163], v[162:163]
	v_pk_mul_f32 v[22:23], v[22:23], v[22:23]
	v_pk_fma_f32 v[156:157], v[160:161], v[160:161], v[156:157]
	v_pk_mul_f32 v[20:21], v[20:21], v[20:21]
	s_waitcnt lgkmcnt(2)
	v_pk_fma_f32 v[130:131], v[16:17], v[130:131], v[142:143] op_sel_hi:[0,1,1]
	v_pk_fma_f32 v[132:133], v[16:17], v[132:133], v[144:145] op_sel_hi:[0,1,1]
	v_pk_add_f32 v[154:155], v[154:155], v[156:157]
	v_pk_mov_b32 v[156:157], v[20:21], v[22:23] op_sel:[1,0]
	v_mov_b32_e32 v21, v23
	v_pk_fma_f32 v[142:143], v[16:17], v[24:25], v[164:165] op_sel:[1,0,0]
	v_pk_fma_f32 v[144:145], v[16:17], v[26:27], v[166:167] op_sel:[1,0,0]
	v_pk_fma_f32 v[150:151], v[16:17], v[28:29], v[150:151] op_sel:[1,0,0]
	v_pk_fma_f32 v[152:153], v[16:17], v[30:31], v[152:153] op_sel:[1,0,0]
	s_waitcnt lgkmcnt(1)
	v_pk_fma_f32 v[146:147], v[16:17], v[138:139], v[146:147] op_sel:[1,0,0]
	v_pk_fma_f32 v[148:149], v[16:17], v[140:141], v[148:149] op_sel:[1,0,0]
	ds_read_b128 v[24:27], v54 offset:57344
	s_waitcnt lgkmcnt(1)
	v_pk_fma_f32 v[164:165], v[16:17], v[134:135], v[130:131] op_sel:[1,0,0]
	v_pk_fma_f32 v[166:167], v[16:17], v[136:137], v[132:133] op_sel:[1,0,0]
	v_pk_fma_f32 v[16:17], v[16:17], v[16:17], v[168:169] op_sel_hi:[1,1,0]
	v_mul_f32_e32 v168, v19, v19
	v_pk_add_f32 v[20:21], v[156:157], v[20:21]
	v_pk_fma_f32 v[168:169], v[18:19], v[18:19], v[168:169] op_sel_hi:[1,1,0]
	v_pk_add_f32 v[22:23], v[154:155], v[154:155] op_sel:[0,1] op_sel_hi:[1,0]
	v_pk_add_f32 v[20:21], v[20:21], v[20:21] op_sel:[0,1] op_sel_hi:[1,0]
	v_mul_f32_e32 v23, v12, v12
	v_mul_f32_e32 v21, v13, v13
	v_mul_f32_e32 v17, v14, v14
	v_mul_f32_e32 v169, v15, v15
	v_pk_add_f32 v[20:21], v[22:23], v[20:21]
	v_pk_add_f32 v[16:17], v[16:17], v[168:169]
	v_pk_mul_f32 v[22:23], v[8:9], v[8:9]
	v_pk_add_f32 v[16:17], v[20:21], v[16:17]
	v_pk_mul_f32 v[20:21], v[10:11], v[10:11]
	v_pk_add_f32 v[16:17], v[16:17], v[16:17] op_sel:[0,1] op_sel_hi:[1,0]
	v_pk_mov_b32 v[154:155], v[22:23], v[20:21] op_sel:[1,0]
	v_mov_b32_e32 v23, v21
	v_pk_add_f32 v[20:21], v[154:155], v[22:23]
	v_mul_f32_e32 v17, v0, v0
	v_pk_add_f32 v[20:21], v[20:21], v[20:21] op_sel:[0,1] op_sel_hi:[1,0]
	v_mul_f32_e32 v22, v7, v7
	v_mul_f32_e32 v21, v1, v1
	v_pk_add_f32 v[16:17], v[16:17], v[20:21]
	v_mul_f32_e32 v20, v5, v5
	v_pk_fma_f32 v[20:21], v[4:5], v[4:5], v[20:21] op_sel_hi:[1,1,0]
	v_pk_fma_f32 v[22:23], v[6:7], v[6:7], v[22:23] op_sel_hi:[1,1,0]
	v_mul_f32_e32 v21, v2, v2
	v_mul_f32_e32 v23, v3, v3
	v_pk_add_f32 v[20:21], v[20:21], v[22:23]
	ds_read_b128 v[28:31], v55 offset:57344
	ds_read_b128 v[130:133], v54 offset:61440
	v_pk_add_f32 v[16:17], v[16:17], v[20:21]
	s_waitcnt lgkmcnt(2)
	v_pk_fma_f32 v[142:143], v[18:19], v[24:25], v[142:143] op_sel_hi:[0,1,1]
	v_add_f32_e32 v43, v16, v17
	ds_bpermute_b32 v129, v48, v43
	v_pk_fma_f32 v[144:145], v[18:19], v[26:27], v[144:145] op_sel_hi:[0,1,1]
	ds_read_b128 v[24:27], v55 offset:61440
	s_waitcnt lgkmcnt(3)
	v_pk_fma_f32 v[150:151], v[18:19], v[28:29], v[150:151] op_sel_hi:[0,1,1]
	v_pk_fma_f32 v[152:153], v[18:19], v[30:31], v[152:153] op_sel_hi:[0,1,1]
	s_waitcnt lgkmcnt(1)
	v_add_f32_e32 v43, v43, v129
	ds_read_b128 v[28:31], v56 offset:57344
	ds_read_b128 v[134:137], v56 offset:61440
	ds_read_b128 v[138:141], v57 offset:57344
	ds_bpermute_b32 v129, v49, v43
	ds_read_b128 v[20:23], v57 offset:61440
	s_waitcnt lgkmcnt(4)
	v_pk_fma_f32 v[16:17], v[18:19], v[28:29], v[146:147] op_sel_hi:[0,1,1]
	v_pk_fma_f32 v[28:29], v[18:19], v[30:31], v[148:149] op_sel_hi:[0,1,1]
	s_waitcnt lgkmcnt(2)
	v_pk_fma_f32 v[30:31], v[18:19], v[138:139], v[164:165] op_sel_hi:[0,1,1]
	v_pk_fma_f32 v[138:139], v[18:19], v[140:141], v[166:167] op_sel_hi:[0,1,1]
	s_waitcnt lgkmcnt(1)
	v_add_f32_e32 v18, v43, v129
	v_mov_b32_e32 v140, v19
	ds_bpermute_b32 v19, v50, v18
	v_pk_fma_f32 v[130:131], v[140:141], v[130:131], v[142:143] op_sel_hi:[0,1,1]
	v_pk_fma_f32 v[142:143], v[140:141], v[24:25], v[150:151] op_sel_hi:[0,1,1]
	v_pk_fma_f32 v[134:135], v[140:141], v[134:135], v[16:17] op_sel_hi:[0,1,1]
	v_pk_fma_f32 v[28:29], v[140:141], v[136:137], v[28:29] op_sel_hi:[0,1,1]
	s_waitcnt lgkmcnt(0)
	v_add_f32_e32 v24, v18, v19
	ds_bpermute_b32 v25, v51, v24
	ds_read_b128 v[16:19], v58
	v_pk_fma_f32 v[30:31], v[140:141], v[20:21], v[30:31] op_sel_hi:[0,1,1]
	v_pk_fma_f32 v[136:137], v[140:141], v[22:23], v[138:139] op_sel_hi:[0,1,1]
	ds_read_b128 v[20:23], v59
	v_pk_fma_f32 v[132:133], v[140:141], v[132:133], v[144:145] op_sel_hi:[0,1,1]
	v_pk_fma_f32 v[144:145], v[140:141], v[26:27], v[152:153] op_sel_hi:[0,1,1]
	s_waitcnt lgkmcnt(2)
	v_add_f32_e32 v43, v24, v25
	ds_read_b128 v[24:27], v60
	s_waitcnt lgkmcnt(2)
	v_pk_fma_f32 v[130:131], v[12:13], v[16:17], v[130:131] op_sel_hi:[0,1,1]
	v_pk_fma_f32 v[132:133], v[12:13], v[18:19], v[132:133] op_sel_hi:[0,1,1]
	s_waitcnt lgkmcnt(1)
	v_pk_fma_f32 v[138:139], v[12:13], v[20:21], v[142:143] op_sel_hi:[0,1,1]
	ds_read_b128 v[16:19], v61
	v_pk_fma_f32 v[140:141], v[12:13], v[22:23], v[144:145] op_sel_hi:[0,1,1]
	ds_read_b128 v[20:23], v62
	s_waitcnt lgkmcnt(2)
	v_pk_fma_f32 v[134:135], v[12:13], v[24:25], v[134:135] op_sel_hi:[0,1,1]
	v_pk_fma_f32 v[28:29], v[12:13], v[26:27], v[28:29] op_sel_hi:[0,1,1]
	ds_read_b128 v[24:27], v63
	s_waitcnt lgkmcnt(2)
	v_pk_fma_f32 v[30:31], v[12:13], v[16:17], v[30:31] op_sel_hi:[0,1,1]
	v_pk_fma_f32 v[136:137], v[12:13], v[18:19], v[136:137] op_sel_hi:[0,1,1]
	s_waitcnt lgkmcnt(1)
	v_pk_fma_f32 v[130:131], v[12:13], v[20:21], v[130:131] op_sel:[1,0,0]
	ds_read_b128 v[16:19], v66
	v_pk_fma_f32 v[132:133], v[12:13], v[22:23], v[132:133] op_sel:[1,0,0]
	ds_read_b128 v[20:23], v67
	s_waitcnt lgkmcnt(2)
	v_pk_fma_f32 v[138:139], v[12:13], v[24:25], v[138:139] op_sel:[1,0,0]
	v_pk_fma_f32 v[140:141], v[12:13], v[26:27], v[140:141] op_sel:[1,0,0]
	ds_read_b128 v[24:27], v68
	s_waitcnt lgkmcnt(2)
	v_pk_fma_f32 v[134:135], v[12:13], v[16:17], v[134:135] op_sel:[1,0,0]
	v_pk_fma_f32 v[28:29], v[12:13], v[18:19], v[28:29] op_sel:[1,0,0]
	s_waitcnt lgkmcnt(1)
	v_pk_fma_f32 v[30:31], v[12:13], v[20:21], v[30:31] op_sel:[1,0,0]
	ds_read_b128 v[16:19], v69
	v_pk_fma_f32 v[12:13], v[12:13], v[22:23], v[136:137] op_sel:[1,0,0]
	ds_read_b128 v[20:23], v70
	s_waitcnt lgkmcnt(2)
	v_pk_fma_f32 v[130:131], v[14:15], v[24:25], v[130:131] op_sel_hi:[0,1,1]
	v_pk_fma_f32 v[132:133], v[14:15], v[26:27], v[132:133] op_sel_hi:[0,1,1]
	ds_read_b128 v[24:27], v71
	s_waitcnt lgkmcnt(2)
	v_pk_fma_f32 v[136:137], v[14:15], v[16:17], v[138:139] op_sel_hi:[0,1,1]
	v_pk_fma_f32 v[138:139], v[14:15], v[18:19], v[140:141] op_sel_hi:[0,1,1]
	s_waitcnt lgkmcnt(1)
	v_pk_fma_f32 v[134:135], v[14:15], v[20:21], v[134:135] op_sel_hi:[0,1,1]
	v_pk_fma_f32 v[28:29], v[14:15], v[22:23], v[28:29] op_sel_hi:[0,1,1]
	ds_read_b128 v[16:19], v72
	ds_read_b128 v[20:23], v73
	s_waitcnt lgkmcnt(2)
	v_pk_fma_f32 v[24:25], v[14:15], v[24:25], v[30:31] op_sel_hi:[0,1,1]
	v_mov_b32_e32 v30, v15
	v_pk_fma_f32 v[26:27], v[14:15], v[26:27], v[12:13] op_sel_hi:[0,1,1]
	s_waitcnt lgkmcnt(1)
	v_pk_fma_f32 v[130:131], v[30:31], v[16:17], v[130:131] op_sel_hi:[0,1,1]
	v_pk_fma_f32 v[132:133], v[30:31], v[18:19], v[132:133] op_sel_hi:[0,1,1]
	ds_read_b128 v[12:15], v74
	s_waitcnt lgkmcnt(1)
	v_pk_fma_f32 v[136:137], v[30:31], v[20:21], v[136:137] op_sel_hi:[0,1,1]
	ds_read_b128 v[16:19], v75
	ds_bpermute_b32 v20, v52, v43
	v_pk_fma_f32 v[138:139], v[30:31], v[22:23], v[138:139] op_sel_hi:[0,1,1]
	s_waitcnt lgkmcnt(2)
	v_pk_fma_f32 v[134:135], v[30:31], v[12:13], v[134:135] op_sel_hi:[0,1,1]
	v_pk_fma_f32 v[28:29], v[30:31], v[14:15], v[28:29] op_sel_hi:[0,1,1]
	ds_read_b128 v[12:15], v76
	s_waitcnt lgkmcnt(2)
	v_pk_fma_f32 v[24:25], v[30:31], v[16:17], v[24:25] op_sel_hi:[0,1,1]
	v_pk_fma_f32 v[26:27], v[30:31], v[18:19], v[26:27] op_sel_hi:[0,1,1]
	ds_read_b128 v[16:19], v77
	s_waitcnt lgkmcnt(2)
	v_add_f32_e32 v43, v43, v20
	ds_read_b128 v[20:23], v78
	s_waitcnt lgkmcnt(2)
	v_pk_fma_f32 v[30:31], v[8:9], v[12:13], v[130:131] op_sel_hi:[0,1,1]
	v_pk_fma_f32 v[130:131], v[8:9], v[14:15], v[132:133] op_sel_hi:[0,1,1]
	s_waitcnt lgkmcnt(1)
	v_pk_fma_f32 v[132:133], v[8:9], v[16:17], v[136:137] op_sel_hi:[0,1,1]
	ds_read_b128 v[12:15], v79
	v_pk_fma_f32 v[136:137], v[8:9], v[18:19], v[138:139] op_sel_hi:[0,1,1]
	s_waitcnt lgkmcnt(1)
	v_pk_fma_f32 v[134:135], v[8:9], v[20:21], v[134:135] op_sel_hi:[0,1,1]
	ds_read_b128 v[16:19], v80
	v_pk_fma_f32 v[28:29], v[8:9], v[22:23], v[28:29] op_sel_hi:[0,1,1]
	ds_read_b128 v[20:23], v81
	s_waitcnt lgkmcnt(2)
	v_pk_fma_f32 v[24:25], v[8:9], v[12:13], v[24:25] op_sel_hi:[0,1,1]
	v_pk_fma_f32 v[26:27], v[8:9], v[14:15], v[26:27] op_sel_hi:[0,1,1]
	s_waitcnt lgkmcnt(1)
	v_pk_fma_f32 v[30:31], v[8:9], v[16:17], v[30:31] op_sel:[1,0,0]
	ds_read_b128 v[12:15], v82
	v_pk_fma_f32 v[130:131], v[8:9], v[18:19], v[130:131] op_sel:[1,0,0]
	s_waitcnt lgkmcnt(1)
	v_pk_fma_f32 v[132:133], v[8:9], v[20:21], v[132:133] op_sel:[1,0,0]
	ds_read_b128 v[16:19], v83
	v_pk_fma_f32 v[136:137], v[8:9], v[22:23], v[136:137] op_sel:[1,0,0]
	ds_read_b128 v[20:23], v84
	s_waitcnt lgkmcnt(2)
	v_pk_fma_f32 v[134:135], v[8:9], v[12:13], v[134:135] op_sel:[1,0,0]
	v_pk_fma_f32 v[28:29], v[8:9], v[14:15], v[28:29] op_sel:[1,0,0]
	s_waitcnt lgkmcnt(1)
	v_pk_fma_f32 v[24:25], v[8:9], v[16:17], v[24:25] op_sel:[1,0,0]
	ds_read_b128 v[12:15], v85
	v_pk_fma_f32 v[8:9], v[8:9], v[18:19], v[26:27] op_sel:[1,0,0]
	s_waitcnt lgkmcnt(1)
	v_pk_fma_f32 v[26:27], v[10:11], v[20:21], v[30:31] op_sel_hi:[0,1,1]
	ds_read_b128 v[16:19], v86
	v_pk_fma_f32 v[30:31], v[10:11], v[22:23], v[130:131] op_sel_hi:[0,1,1]
	ds_read_b128 v[20:23], v87
	s_waitcnt lgkmcnt(2)
	v_pk_fma_f32 v[130:131], v[10:11], v[12:13], v[132:133] op_sel_hi:[0,1,1]
	v_pk_fma_f32 v[132:133], v[10:11], v[14:15], v[136:137] op_sel_hi:[0,1,1]
	s_waitcnt lgkmcnt(1)
	v_pk_fma_f32 v[134:135], v[10:11], v[16:17], v[134:135] op_sel_hi:[0,1,1]
	v_pk_fma_f32 v[28:29], v[10:11], v[18:19], v[28:29] op_sel_hi:[0,1,1]
	ds_read_b128 v[12:15], v88
	s_waitcnt lgkmcnt(1)
	v_pk_fma_f32 v[20:21], v[10:11], v[20:21], v[24:25] op_sel_hi:[0,1,1]
	v_pk_fma_f32 v[22:23], v[10:11], v[22:23], v[8:9] op_sel_hi:[0,1,1]
	ds_read_b128 v[16:19], v89
	v_mov_b32_e32 v24, v11
	ds_read_b128 v[8:11], v90
	s_waitcnt lgkmcnt(2)
	v_pk_fma_f32 v[26:27], v[24:25], v[12:13], v[26:27] op_sel_hi:[0,1,1]
	v_pk_fma_f32 v[30:31], v[24:25], v[14:15], v[30:31] op_sel_hi:[0,1,1]
	s_waitcnt lgkmcnt(1)
	v_pk_fma_f32 v[130:131], v[24:25], v[16:17], v[130:131] op_sel_hi:[0,1,1]
	ds_read_b128 v[12:15], v91
	v_pk_fma_f32 v[132:133], v[24:25], v[18:19], v[132:133] op_sel_hi:[0,1,1]
	s_waitcnt lgkmcnt(1)
	v_pk_fma_f32 v[134:135], v[24:25], v[8:9], v[134:135] op_sel_hi:[0,1,1]
	ds_read_b128 v[16:19], v92
	v_pk_fma_f32 v[28:29], v[24:25], v[10:11], v[28:29] op_sel_hi:[0,1,1]
	ds_read_b128 v[8:11], v94
	s_waitcnt lgkmcnt(2)
	v_pk_fma_f32 v[20:21], v[24:25], v[12:13], v[20:21] op_sel_hi:[0,1,1]
	v_pk_fma_f32 v[22:23], v[24:25], v[14:15], v[22:23] op_sel_hi:[0,1,1]
	s_waitcnt lgkmcnt(1)
	v_pk_fma_f32 v[24:25], v[4:5], v[16:17], v[26:27] op_sel_hi:[0,1,1]
	ds_read_b128 v[12:15], v95
	v_pk_fma_f32 v[26:27], v[4:5], v[18:19], v[30:31] op_sel_hi:[0,1,1]
	s_waitcnt lgkmcnt(1)
	v_pk_fma_f32 v[30:31], v[4:5], v[8:9], v[130:131] op_sel_hi:[0,1,1]
	ds_read_b128 v[16:19], v96
	v_pk_fma_f32 v[130:131], v[4:5], v[10:11], v[132:133] op_sel_hi:[0,1,1]
	ds_read_b128 v[8:11], v97
	s_waitcnt lgkmcnt(2)
	v_pk_fma_f32 v[132:133], v[4:5], v[12:13], v[134:135] op_sel_hi:[0,1,1]
	v_pk_fma_f32 v[28:29], v[4:5], v[14:15], v[28:29] op_sel_hi:[0,1,1]
	s_waitcnt lgkmcnt(1)
	v_pk_fma_f32 v[20:21], v[4:5], v[16:17], v[20:21] op_sel_hi:[0,1,1]
	ds_read_b128 v[12:15], v98
	v_pk_fma_f32 v[22:23], v[4:5], v[18:19], v[22:23] op_sel_hi:[0,1,1]
	s_waitcnt lgkmcnt(1)
	v_pk_fma_f32 v[24:25], v[4:5], v[8:9], v[24:25] op_sel:[1,0,0]
	ds_read_b128 v[16:19], v99
	v_pk_fma_f32 v[26:27], v[4:5], v[10:11], v[26:27] op_sel:[1,0,0]
	ds_read_b128 v[8:11], v100
	s_waitcnt lgkmcnt(2)
	v_pk_fma_f32 v[30:31], v[4:5], v[12:13], v[30:31] op_sel:[1,0,0]
	v_pk_fma_f32 v[130:131], v[4:5], v[14:15], v[130:131] op_sel:[1,0,0]
	s_waitcnt lgkmcnt(1)
	v_pk_fma_f32 v[132:133], v[4:5], v[16:17], v[132:133] op_sel:[1,0,0]
	ds_read_b128 v[12:15], v101
	v_pk_fma_f32 v[28:29], v[4:5], v[18:19], v[28:29] op_sel:[1,0,0]
	s_waitcnt lgkmcnt(1)
	v_pk_fma_f32 v[20:21], v[4:5], v[8:9], v[20:21] op_sel:[1,0,0]
	ds_read_b128 v[16:19], v102
	v_pk_fma_f32 v[4:5], v[4:5], v[10:11], v[22:23] op_sel:[1,0,0]
	ds_read_b128 v[8:11], v103
	s_waitcnt lgkmcnt(2)
	v_pk_fma_f32 v[22:23], v[6:7], v[12:13], v[24:25] op_sel_hi:[0,1,1]
	v_pk_fma_f32 v[24:25], v[6:7], v[14:15], v[26:27] op_sel_hi:[0,1,1]
	ds_read_b128 v[12:15], v104
	s_waitcnt lgkmcnt(2)
	v_pk_fma_f32 v[18:19], v[6:7], v[18:19], v[130:131] op_sel_hi:[0,1,1]
	s_waitcnt lgkmcnt(1)
	v_pk_fma_f32 v[26:27], v[6:7], v[8:9], v[132:133] op_sel_hi:[0,1,1]
	v_pk_fma_f32 v[28:29], v[6:7], v[10:11], v[28:29] op_sel_hi:[0,1,1]
	ds_read_b128 v[8:11], v105
	v_mov_b32_e32 v130, v7
	v_pk_fma_f32 v[16:17], v[6:7], v[16:17], v[30:31] op_sel_hi:[0,1,1]
	s_waitcnt lgkmcnt(1)
	v_pk_fma_f32 v[20:21], v[6:7], v[12:13], v[20:21] op_sel_hi:[0,1,1]
	v_pk_fma_f32 v[30:31], v[6:7], v[14:15], v[4:5] op_sel_hi:[0,1,1]
	ds_read_b128 v[12:15], v106
	ds_read_b128 v[4:7], v107
	s_waitcnt lgkmcnt(2)
	v_pk_fma_f32 v[22:23], v[130:131], v[8:9], v[22:23] op_sel_hi:[0,1,1]
	v_pk_fma_f32 v[24:25], v[130:131], v[10:11], v[24:25] op_sel_hi:[0,1,1]
	ds_read_b128 v[8:11], v108
	s_waitcnt lgkmcnt(2)
	v_pk_fma_f32 v[16:17], v[130:131], v[12:13], v[16:17] op_sel_hi:[0,1,1]
	v_pk_fma_f32 v[18:19], v[130:131], v[14:15], v[18:19] op_sel_hi:[0,1,1]
	s_waitcnt lgkmcnt(1)
	v_pk_fma_f32 v[26:27], v[130:131], v[4:5], v[26:27] op_sel_hi:[0,1,1]
	ds_read_b128 v[12:15], v109
	v_pk_fma_f32 v[28:29], v[130:131], v[6:7], v[28:29] op_sel_hi:[0,1,1]
	s_waitcnt lgkmcnt(1)
	v_pk_fma_f32 v[20:21], v[130:131], v[8:9], v[20:21] op_sel_hi:[0,1,1]
	ds_read_b128 v[4:7], v110
	v_pk_fma_f32 v[30:31], v[130:131], v[10:11], v[30:31] op_sel_hi:[0,1,1]
	ds_read_b128 v[8:11], v111
	s_waitcnt lgkmcnt(2)
	v_pk_fma_f32 v[22:23], v[0:1], v[12:13], v[22:23] op_sel_hi:[0,1,1]
	v_pk_fma_f32 v[24:25], v[0:1], v[14:15], v[24:25] op_sel_hi:[0,1,1]
	s_waitcnt lgkmcnt(1)
	v_pk_fma_f32 v[16:17], v[0:1], v[4:5], v[16:17] op_sel_hi:[0,1,1]
	ds_read_b128 v[12:15], v112
	v_pk_fma_f32 v[18:19], v[0:1], v[6:7], v[18:19] op_sel_hi:[0,1,1]
	s_waitcnt lgkmcnt(1)
	v_pk_fma_f32 v[26:27], v[0:1], v[8:9], v[26:27] op_sel_hi:[0,1,1]
	ds_read_b128 v[4:7], v113
	v_pk_fma_f32 v[28:29], v[0:1], v[10:11], v[28:29] op_sel_hi:[0,1,1]
	ds_read_b128 v[8:11], v114
	s_waitcnt lgkmcnt(2)
	v_pk_fma_f32 v[20:21], v[0:1], v[12:13], v[20:21] op_sel_hi:[0,1,1]
	v_pk_fma_f32 v[30:31], v[0:1], v[14:15], v[30:31] op_sel_hi:[0,1,1]
	s_waitcnt lgkmcnt(1)
	v_pk_fma_f32 v[22:23], v[0:1], v[4:5], v[22:23] op_sel:[1,0,0]
	ds_read_b128 v[12:15], v115
	v_pk_fma_f32 v[24:25], v[0:1], v[6:7], v[24:25] op_sel:[1,0,0]
	s_waitcnt lgkmcnt(1)
	v_pk_fma_f32 v[16:17], v[0:1], v[8:9], v[16:17] op_sel:[1,0,0]
	ds_read_b128 v[4:7], v116
	v_pk_fma_f32 v[18:19], v[0:1], v[10:11], v[18:19] op_sel:[1,0,0]
	ds_read_b128 v[8:11], v117
	s_waitcnt lgkmcnt(2)
	v_pk_fma_f32 v[26:27], v[0:1], v[12:13], v[26:27] op_sel:[1,0,0]
	v_pk_fma_f32 v[28:29], v[0:1], v[14:15], v[28:29] op_sel:[1,0,0]
	s_waitcnt lgkmcnt(1)
	v_pk_fma_f32 v[20:21], v[0:1], v[4:5], v[20:21] op_sel:[1,0,0]
	ds_read_b128 v[12:15], v118
	v_pk_fma_f32 v[0:1], v[0:1], v[6:7], v[30:31] op_sel:[1,0,0]
	s_waitcnt lgkmcnt(1)
	v_pk_fma_f32 v[22:23], v[2:3], v[8:9], v[22:23] op_sel_hi:[0,1,1]
	ds_read_b128 v[4:7], v119
	v_pk_fma_f32 v[24:25], v[2:3], v[10:11], v[24:25] op_sel_hi:[0,1,1]
	ds_read_b128 v[8:11], v120
	s_waitcnt lgkmcnt(2)
	v_pk_fma_f32 v[12:13], v[2:3], v[12:13], v[16:17] op_sel_hi:[0,1,1]
	v_pk_fma_f32 v[14:15], v[2:3], v[14:15], v[18:19] op_sel_hi:[0,1,1]
	s_waitcnt lgkmcnt(1)
	v_pk_fma_f32 v[16:17], v[2:3], v[4:5], v[26:27] op_sel_hi:[0,1,1]
	v_pk_fma_f32 v[18:19], v[2:3], v[6:7], v[28:29] op_sel_hi:[0,1,1]
	ds_read_b128 v[4:7], v121
	s_waitcnt lgkmcnt(1)
	v_pk_fma_f32 v[20:21], v[2:3], v[8:9], v[20:21] op_sel_hi:[0,1,1]
	v_pk_fma_f32 v[26:27], v[2:3], v[10:11], v[0:1] op_sel_hi:[0,1,1]
	v_mov_b32_e32 v28, v3
	ds_read_b128 v[0:3], v122
	ds_read_b128 v[8:11], v123
	s_waitcnt lgkmcnt(2)
	v_pk_fma_f32 v[22:23], v[28:29], v[4:5], v[22:23] op_sel_hi:[0,1,1]
	v_pk_fma_f32 v[24:25], v[28:29], v[6:7], v[24:25] op_sel_hi:[0,1,1]
	ds_read_b128 v[4:7], v124
	s_waitcnt lgkmcnt(2)
	v_pk_fma_f32 v[0:1], v[28:29], v[0:1], v[12:13] op_sel_hi:[0,1,1]
	s_waitcnt lgkmcnt(1)
	v_pk_fma_f32 v[8:9], v[28:29], v[8:9], v[16:17] op_sel_hi:[0,1,1]
	v_cndmask_b32_e32 v13, v23, v9, vcc
	ds_bpermute_b32 v13, v53, v13
	v_pk_fma_f32 v[10:11], v[28:29], v[10:11], v[18:19] op_sel_hi:[0,1,1]
	s_waitcnt lgkmcnt(1)
	v_pk_fma_f32 v[4:5], v[28:29], v[4:5], v[20:21] op_sel_hi:[0,1,1]
	v_cndmask_b32_e32 v9, v9, v23, vcc
	v_pk_fma_f32 v[2:3], v[28:29], v[2:3], v[14:15] op_sel_hi:[0,1,1]
	v_cndmask_b32_e32 v12, v8, v22, vcc
	v_cndmask_b32_e32 v8, v22, v8, vcc
	v_cndmask_b32_e32 v14, v24, v10, vcc
	s_waitcnt lgkmcnt(0)
	v_add_f32_e32 v9, v9, v13
	v_cndmask_b32_e32 v13, v0, v4, vcc
	ds_bpermute_b32 v8, v53, v8
	ds_bpermute_b32 v14, v53, v14
	ds_bpermute_b32 v13, v53, v13
	v_pk_fma_f32 v[6:7], v[28:29], v[6:7], v[26:27] op_sel_hi:[0,1,1]
	v_cndmask_b32_e32 v10, v10, v24, vcc
	v_cndmask_b32_e32 v0, v4, v0, vcc
	s_waitcnt lgkmcnt(2)
	v_add_f32_e32 v8, v12, v8
	s_waitcnt lgkmcnt(1)
	v_add_f32_e32 v10, v10, v14
	v_cndmask_b32_e32 v12, v11, v25, vcc
	v_cndmask_b32_e32 v11, v25, v11, vcc
	v_cndmask_b32_e32 v14, v1, v5, vcc
	s_waitcnt lgkmcnt(0)
	v_add_f32_e32 v0, v0, v13
	v_cndmask_b32_e32 v1, v5, v1, vcc
	v_cndmask_b32_e32 v4, v6, v2, vcc
	v_cndmask_b32_e32 v2, v2, v6, vcc
	v_cndmask_b32_e32 v5, v3, v7, vcc
	ds_bpermute_b32 v11, v53, v11
	ds_bpermute_b32 v14, v53, v14
	ds_bpermute_b32 v2, v53, v2
	ds_bpermute_b32 v5, v53, v5
	v_cndmask_b32_e64 v6, v8, v0, s[0:1]
	ds_bpermute_b32 v6, v52, v6
	v_cndmask_b32_e32 v3, v7, v3, vcc
	s_waitcnt lgkmcnt(4)
	v_add_f32_e32 v11, v12, v11
	s_waitcnt lgkmcnt(3)
	v_add_f32_e32 v1, v1, v14
	s_waitcnt lgkmcnt(2)
	v_add_f32_e32 v2, v4, v2
	s_waitcnt lgkmcnt(1)
	v_add_f32_e32 v3, v3, v5
	v_cndmask_b32_e64 v0, v0, v8, s[0:1]
	s_waitcnt lgkmcnt(0)
	v_add_f32_e32 v0, v0, v6
	v_cndmask_b32_e64 v4, v1, v9, s[0:1]
	v_cndmask_b32_e64 v1, v9, v1, s[0:1]
	v_cndmask_b32_e64 v5, v10, v2, s[0:1]
	v_cndmask_b32_e64 v6, v11, v3, s[0:1]
	ds_bpermute_b32 v1, v52, v1
	ds_bpermute_b32 v5, v52, v5
	ds_bpermute_b32 v6, v52, v6
	v_cndmask_b32_e64 v2, v2, v10, s[0:1]
	v_cndmask_b32_e64 v3, v3, v11, s[0:1]
	s_waitcnt lgkmcnt(2)
	v_add_f32_e32 v1, v4, v1
	s_waitcnt lgkmcnt(1)
	v_add_f32_e32 v2, v2, v5
	s_waitcnt lgkmcnt(0)
	v_add_f32_e32 v3, v3, v6
	v_cndmask_b32_e64 v4, v0, v2, s[2:3]
	v_cndmask_b32_e64 v5, v1, v3, s[2:3]
	ds_bpermute_b32 v4, v51, v4
	ds_bpermute_b32 v5, v51, v5
	v_cndmask_b32_e64 v0, v2, v0, s[2:3]
	v_cndmask_b32_e64 v1, v3, v1, s[2:3]
	ds_bpermute_b32 v6, v53, v43
	s_waitcnt lgkmcnt(2)
	v_add_f32_e32 v0, v0, v4
	s_waitcnt lgkmcnt(1)
	v_add_f32_e32 v1, v1, v5
	v_cndmask_b32_e64 v2, v0, v1, s[4:5]
	ds_bpermute_b32 v2, v50, v2
	v_cndmask_b32_e64 v0, v1, v0, s[4:5]
	s_waitcnt lgkmcnt(1)
	v_add_f32_e32 v3, v43, v6
	v_fmamk_f32 v3, v3, 0x3a000000, v125
	v_cmp_gt_f32_e64 s[10:11], s13, v3
	s_waitcnt lgkmcnt(0)
	v_add_f32_e32 v0, v0, v2
	ds_bpermute_b32 v1, v49, v0
	v_mul_f32_e32 v2, 0x4b800000, v3
	v_cndmask_b32_e64 v2, v3, v2, s[10:11]
	v_rsq_f32_e32 v4, v2
	global_store_dwordx2 v[44:45], v[46:47], off offset:3584 sc0 sc1
	s_waitcnt lgkmcnt(0)
	v_add_f32_e32 v2, v0, v1
	ds_bpermute_b32 v3, v48, v2
	v_mul_f32_e32 v0, 0x45800000, v4
	v_cndmask_b32_e64 v0, v4, v0, s[10:11]
	s_and_saveexec_b64 s[26:27], s[6:7]
	s_cbranch_execz .LBB0_203
	global_load_dword v1, v[32:33], off
	s_waitcnt lgkmcnt(0)
	v_add_f32_e32 v2, v2, v3
	s_waitcnt vmcnt(0)
	v_fmac_f32_e32 v1, v0, v2
	v_cmp_nlt_f32_e64 s[10:11], s31, v1
	s_and_saveexec_b64 s[28:29], s[10:11]
	s_cbranch_execz .LBB0_202
	v_mul_f32_e32 v2, 0x3fb8aa3b, v1
	v_rndne_f32_e32 v3, v2
	v_sub_f32_e32 v4, v2, v3
	v_fma_f32 v2, v1, s34, -v2
	v_fmac_f32_e32 v2, 0x32a5705f, v1
	v_add_f32_e32 v2, v4, v2
	v_cvt_i32_f32_e32 v3, v3
	v_exp_f32_e32 v2, v2
	v_cmp_ngt_f32_e64 s[10:11], s35, v1
	v_ldexp_f32 v2, v2, v3
	s_nop 0
	v_cndmask_b32_e64 v2, 0, v2, s[10:11]
	v_cmp_nlt_f32_e64 s[10:11], s36, v1
	s_nop 1
	v_cndmask_b32_e64 v1, v127, v2, s[10:11]
	v_add_f32_e32 v4, 1.0, v1
	v_add_f32_e32 v2, -1.0, v4
	v_sub_f32_e32 v3, v2, v4
	v_add_f32_e32 v3, 1.0, v3
	v_sub_f32_e32 v2, v1, v2
	v_add_f32_e32 v5, v2, v3
	v_frexp_mant_f32_e32 v6, v4
	v_cvt_f64_f32_e32 v[2:3], v4
	v_frexp_exp_i32_f64_e32 v2, v[2:3]
	v_cmp_gt_f32_e64 s[10:11], s38, v6
	s_nop 1
	v_subbrev_co_u32_e64 v10, s[10:11], 0, v2, s[10:11]
	v_sub_u32_e32 v2, 0, v10
	v_ldexp_f32 v3, v4, v2
	v_add_f32_e32 v4, -1.0, v3
	v_add_f32_e32 v6, 1.0, v3
	v_ldexp_f32 v2, v5, v2
	v_add_f32_e32 v5, 1.0, v4
	v_add_f32_e32 v7, -1.0, v6
	v_sub_f32_e32 v5, v3, v5
	v_sub_f32_e32 v3, v3, v7
	v_add_f32_e32 v5, v2, v5
	v_add_f32_e32 v2, v2, v3
	v_add_f32_e32 v11, v6, v2
	v_rcp_f32_e32 v13, v11
	v_sub_f32_e32 v3, v6, v11
	v_add_f32_e32 v12, v2, v3
	v_add_f32_e32 v3, v4, v5
	v_mul_f32_e32 v15, v3, v13
	v_sub_f32_e32 v2, v4, v3
	v_mul_f32_e32 v4, v11, v15
	v_fma_f32 v6, v15, v11, -v4
	v_fmac_f32_e32 v6, v15, v12
	v_add_f32_e32 v14, v5, v2
	v_add_f32_e32 v2, v4, v6
	v_sub_f32_e32 v5, v3, v2
	v_pk_add_f32 v[8:9], v[2:3], v[4:5] neg_lo:[0,1] neg_hi:[0,1]
	v_mov_b32_e32 v7, v2
	v_pk_add_f32 v[2:3], v[8:9], v[6:7] neg_lo:[0,1] neg_hi:[0,1]
	v_cmp_neq_f32_e64 s[10:11], s37, v1
	v_add_f32_e32 v3, v14, v3
	v_add_f32_e32 v2, v2, v3
	v_add_f32_e32 v3, v5, v2
	v_mul_f32_e32 v14, v13, v3
	v_mul_f32_e32 v4, v11, v14
	v_fma_f32 v6, v14, v11, -v4
	v_fmac_f32_e32 v6, v14, v12
	v_sub_f32_e32 v5, v5, v3
	v_add_f32_e32 v11, v2, v5
	v_add_f32_e32 v2, v4, v6
	v_sub_f32_e32 v5, v3, v2
	v_pk_add_f32 v[8:9], v[2:3], v[4:5] neg_lo:[0,1] neg_hi:[0,1]
	v_mov_b32_e32 v7, v2
	v_pk_add_f32 v[2:3], v[8:9], v[6:7] neg_lo:[0,1] neg_hi:[0,1]
	s_nop 0
	v_add_f32_e32 v3, v11, v3
	v_add_f32_e32 v2, v2, v3
	v_add_f32_e32 v3, v15, v14
	v_add_f32_e32 v2, v5, v2
	v_sub_f32_e32 v4, v3, v15
	v_mul_f32_e32 v2, v13, v2
	v_sub_f32_e32 v4, v14, v4
	v_add_f32_e32 v4, v4, v2
	v_add_f32_e32 v6, v3, v4
	v_mul_f32_e32 v7, v6, v6
	v_fmamk_f32 v2, v7, 0x3e9b6dac, v126
	v_fmaak_f32 v43, v7, v2, 0x3f2aaada
	v_cvt_f32_i32_e32 v2, v10
	v_sub_f32_e32 v3, v6, v3
	v_sub_f32_e32 v3, v4, v3
	v_ldexp_f32 v8, v3, 1
	v_mul_f32_e32 v3, v6, v7
	v_ldexp_f32 v5, v6, 1
	v_pk_mul_f32 v[6:7], v[2:3], v[42:43]
	s_nop 0
	v_fma_f32 v4, v2, s39, -v6
	v_fmac_f32_e32 v4, 0xb102e308, v2
	v_pk_add_f32 v[2:3], v[6:7], v[4:5]
	s_nop 0
	v_sub_f32_e32 v5, v3, v5
	v_sub_f32_e32 v5, v7, v5
	v_add_f32_e32 v9, v8, v5
	v_mov_b32_e32 v8, v6
	v_pk_add_f32 v[6:7], v[2:3], v[6:7] neg_lo:[0,1] neg_hi:[0,1]
	v_pk_add_f32 v[10:11], v[2:3], v[8:9]
	v_mov_b32_e32 v5, v2
	v_mov_b32_e32 v7, v11
	v_pk_add_f32 v[12:13], v[4:5], v[6:7] neg_lo:[0,1] neg_hi:[0,1]
	v_pk_add_f32 v[4:5], v[4:5], v[6:7]
	v_mov_b32_e32 v8, v9
	v_pk_add_f32 v[6:7], v[4:5], v[2:3] op_sel:[1,0] op_sel_hi:[0,1] neg_lo:[0,1] neg_hi:[0,1]
	v_pk_add_f32 v[14:15], v[10:11], v[6:7] op_sel_hi:[1,0] neg_lo:[0,1] neg_hi:[0,1]
	v_mov_b32_e32 v10, v11
	v_mov_b32_e32 v11, v5
	v_pk_mov_b32 v[6:7], v[2:3], v[6:7] op_sel:[1,0]
	v_mov_b32_e32 v9, v2
	v_pk_add_f32 v[6:7], v[10:11], v[6:7] neg_lo:[0,1] neg_hi:[0,1]
	v_mov_b32_e32 v14, v12
	v_pk_add_f32 v[2:3], v[8:9], v[6:7] neg_lo:[0,1] neg_hi:[0,1]
	v_mov_b32_e32 v13, v5
	v_pk_add_f32 v[6:7], v[14:15], v[2:3]
	s_nop 0
	v_pk_add_f32 v[8:9], v[6:7], v[6:7] op_sel:[0,1] op_sel_hi:[1,0]
	s_nop 0
	v_pk_add_f32 v[4:5], v[4:5], v[8:9] op_sel:[1,0] op_sel_hi:[0,1]
	v_mov_b32_e32 v7, v4
	v_pk_add_f32 v[10:11], v[6:7], v[12:13] neg_lo:[0,1] neg_hi:[0,1]
	v_mov_b32_e32 v3, v8
	v_sub_f32_e32 v5, v6, v10
	v_pk_add_f32 v[2:3], v[2:3], v[10:11] neg_lo:[0,1] neg_hi:[0,1]
	v_sub_f32_e32 v5, v12, v5
	v_add_f32_e32 v2, v2, v5
	v_add_f32_e32 v2, v2, v3
	v_add_f32_e32 v2, v4, v2
	v_cndmask_b32_e64 v2, v127, v2, s[10:11]
	v_cmp_lt_f32_e64 s[10:11], |v1|, s40
	s_nop 1
	v_cndmask_b32_e64 v1, v2, v1, s[10:11]
.LBB0_202:
	s_or_b64 exec, exec, s[28:29]
	v_lshl_add_u64 v[2:3], s[84:85], 0, v[36:37]
	global_store_dword v[2:3], v1, off sc0 sc1
.LBB0_203:
	s_or_b64 exec, exec, s[26:27]
	s_and_saveexec_b64 s[10:11], s[8:9]
	s_cbranch_execz .LBB0_198
	s_waitcnt lgkmcnt(0)
	v_lshl_add_u64 v[2:3], s[84:85], 0, v[34:35]
	global_store_dword v[2:3], v0, off sc0 sc1
	s_branch .LBB0_198
.Lmy_partb4:
	s_waitcnt lgkmcnt(0)
	global_load_dword v253, v[32:33], off
	v_lshl_add_u64 v[8:9], v[38:39], 0, s[20:21]
	v_lshl_add_u64 v[10:11], v[8:9], 0, s[20:21]
	v_lshl_add_u64 v[12:13], v[10:11], 0, s[20:21]
	global_load_dwordx4 v[160:163], v[38:39], off offset:-4096 nt
	global_load_dwordx4 v[164:167], v[8:9], off offset:-4096 nt
	global_load_dwordx4 v[168:171], v[10:11], off offset:-4096 nt
	global_load_dwordx4 v[172:175], v[12:13], off offset:-4096 nt
	global_load_dwordx4 v[176:179], v[38:39], off offset:-3072 nt
	global_load_dwordx4 v[180:183], v[8:9], off offset:-3072 nt
	global_load_dwordx4 v[184:187], v[10:11], off offset:-3072 nt
	global_load_dwordx4 v[188:191], v[12:13], off offset:-3072 nt
	global_load_dwordx4 v[192:195], v[38:39], off offset:-2048 nt
	global_load_dwordx4 v[196:199], v[8:9], off offset:-2048 nt
	global_load_dwordx4 v[200:203], v[10:11], off offset:-2048 nt
	global_load_dwordx4 v[204:207], v[12:13], off offset:-2048 nt
	global_load_dwordx4 v[208:211], v[38:39], off offset:-1024 nt
	global_load_dwordx4 v[212:215], v[8:9], off offset:-1024 nt
	global_load_dwordx4 v[216:219], v[10:11], off offset:-1024 nt
	global_load_dwordx4 v[220:223], v[12:13], off offset:-1024 nt
	global_load_dwordx4 v[224:227], v[38:39], off nt
	global_load_dwordx4 v[228:231], v[8:9], off nt
	global_load_dwordx4 v[0:3], v[10:11], off nt
	global_load_dwordx4 v[4:7], v[12:13], off nt
	v_lshl_add_u64 v[14:15], s[84:85], 0, v[40:41]
	v_add_co_u32_e64 v14, s[10:11], s30, v14
	s_nop 1
	v_addc_co_u32_e64 v15, s[10:11], 0, v15, s[10:11]
	v_lshl_add_u64 v[16:17], v[14:15], 0, s[22:23]
	v_lshl_add_u64 v[18:19], v[16:17], 0, s[22:23]
	v_lshl_add_u64 v[20:21], v[18:19], 0, s[22:23]
	v_mov_b32_e32 v240, 0
	v_mov_b32_e32 v241, 0
	v_mov_b32_e32 v242, 0
	v_mov_b32_e32 v243, 0
	v_mov_b32_e32 v66, 0
	v_mov_b32_e32 v67, 0
	v_mov_b32_e32 v68, 0
	v_mov_b32_e32 v69, 0
	v_mov_b32_e32 v70, 0
	v_mov_b32_e32 v71, 0
	v_mov_b32_e32 v72, 0
	v_mov_b32_e32 v73, 0
	v_mov_b32_e32 v74, 0
	v_mov_b32_e32 v75, 0
	v_mov_b32_e32 v76, 0
	v_mov_b32_e32 v77, 0
	v_mov_b32_e32 v78, 0
	v_mov_b32_e32 v79, 0
	v_mov_b32_e32 v80, 0
	v_mov_b32_e32 v81, 0
	v_mov_b32_e32 v82, 0
	v_mov_b32_e32 v83, 0
	v_mov_b32_e32 v84, 0
	v_mov_b32_e32 v85, 0
	v_mov_b32_e32 v86, 0
	v_mov_b32_e32 v87, 0
	v_mov_b32_e32 v88, 0
	v_mov_b32_e32 v89, 0
	v_mov_b32_e32 v90, 0
	v_mov_b32_e32 v91, 0
	v_mov_b32_e32 v94, 0
	v_mov_b32_e32 v95, 0
	v_mov_b32_e32 v96, 0
	v_mov_b32_e32 v97, 0
	v_mov_b32_e32 v98, 0
	v_mov_b32_e32 v99, 0
	v_mov_b32_e32 v100, 0
	v_mov_b32_e32 v101, 0
	v_mov_b32_e32 v102, 0
	v_mov_b32_e32 v103, 0
	v_mov_b32_e32 v104, 0
	v_mov_b32_e32 v105, 0
	v_mov_b32_e32 v106, 0
	v_mov_b32_e32 v107, 0
	v_mov_b32_e32 v108, 0
	v_mov_b32_e32 v109, 0
	v_mov_b32_e32 v110, 0
	v_mov_b32_e32 v111, 0
	v_mov_b32_e32 v112, 0
	v_mov_b32_e32 v113, 0
	v_mov_b32_e32 v114, 0
	v_mov_b32_e32 v115, 0
	v_mov_b32_e32 v116, 0
	v_mov_b32_e32 v117, 0
	v_mov_b32_e32 v118, 0
	v_mov_b32_e32 v119, 0
	v_mov_b32_e32 v120, 0
	v_mov_b32_e32 v121, 0
	v_mov_b32_e32 v122, 0
	v_mov_b32_e32 v123, 0
	v_mov_b32_e32 v24, 0
	v_mov_b32_e32 v25, 0
	v_mov_b32_e32 v26, 0
	v_mov_b32_e32 v27, 0
	v_mov_b32_e32 v28, 0
	v_mov_b32_e32 v29, 0
	v_mov_b32_e32 v30, 0
	v_mov_b32_e32 v31, 0
	ds_read_b128 v[130:133], v54
	ds_read_b128 v[134:137], v55
	ds_read_b128 v[138:141], v56
	ds_read_b128 v[142:145], v57
	ds_read_b128 v[146:149], v54 offset:4096
	ds_read_b128 v[150:153], v55 offset:4096
	ds_read_b128 v[154:157], v56 offset:4096
	ds_read_b128 v[44:47], v57 offset:4096
	s_waitcnt vmcnt(19)
	v_cvt_pk_bf16_f32 v244, v160, v161
	v_cvt_pk_bf16_f32 v245, v162, v163
	global_store_dwordx2 v[14:15], v[244:245], off sc0 sc1
	v_pk_mul_f32 v[22:23], v[160:161], v[160:161]
	v_pk_fma_f32 v[22:23], v[162:163], v[162:163], v[22:23]
	v_add_f32_e32 v22, v22, v23
	v_add_f32_e32 v240, v240, v22
	s_waitcnt vmcnt(19)
	v_cvt_pk_bf16_f32 v246, v164, v165
	v_cvt_pk_bf16_f32 v247, v166, v167
	global_store_dwordx2 v[16:17], v[246:247], off sc0 sc1
	v_pk_mul_f32 v[22:23], v[164:165], v[164:165]
	v_pk_fma_f32 v[22:23], v[166:167], v[166:167], v[22:23]
	v_add_f32_e32 v22, v22, v23
	v_add_f32_e32 v241, v241, v22
	s_waitcnt vmcnt(19)
	v_cvt_pk_bf16_f32 v248, v168, v169
	v_cvt_pk_bf16_f32 v249, v170, v171
	global_store_dwordx2 v[18:19], v[248:249], off sc0 sc1
	v_pk_mul_f32 v[22:23], v[168:169], v[168:169]
	v_pk_fma_f32 v[22:23], v[170:171], v[170:171], v[22:23]
	v_add_f32_e32 v22, v22, v23
	v_add_f32_e32 v242, v242, v22
	s_waitcnt vmcnt(19)
	v_cvt_pk_bf16_f32 v232, v172, v173
	v_cvt_pk_bf16_f32 v233, v174, v175
	global_store_dwordx2 v[20:21], v[232:233], off sc0 sc1
	v_pk_mul_f32 v[22:23], v[172:173], v[172:173]
	v_pk_fma_f32 v[22:23], v[174:175], v[174:175], v[22:23]
	v_add_f32_e32 v22, v22, v23
	v_add_f32_e32 v243, v243, v22
	s_waitcnt lgkmcnt(7)
	v_pk_fma_f32 v[66:67], v[160:161], v[130:131], v[66:67] op_sel_hi:[0,1,1]
	v_pk_fma_f32 v[82:83], v[164:165], v[130:131], v[82:83] op_sel_hi:[0,1,1]
	v_pk_fma_f32 v[100:101], v[168:169], v[130:131], v[100:101] op_sel_hi:[0,1,1]
	v_pk_fma_f32 v[116:117], v[172:173], v[130:131], v[116:117] op_sel_hi:[0,1,1]
	v_pk_fma_f32 v[68:69], v[160:161], v[132:133], v[68:69] op_sel_hi:[0,1,1]
	v_pk_fma_f32 v[84:85], v[164:165], v[132:133], v[84:85] op_sel_hi:[0,1,1]
	v_pk_fma_f32 v[102:103], v[168:169], v[132:133], v[102:103] op_sel_hi:[0,1,1]
	v_pk_fma_f32 v[118:119], v[172:173], v[132:133], v[118:119] op_sel_hi:[0,1,1]
	ds_read_b128 v[130:133], v54 offset:8192
	s_waitcnt lgkmcnt(7)
	v_pk_fma_f32 v[70:71], v[160:161], v[134:135], v[70:71] op_sel_hi:[0,1,1]
	v_pk_fma_f32 v[86:87], v[164:165], v[134:135], v[86:87] op_sel_hi:[0,1,1]
	v_pk_fma_f32 v[104:105], v[168:169], v[134:135], v[104:105] op_sel_hi:[0,1,1]
	v_pk_fma_f32 v[120:121], v[172:173], v[134:135], v[120:121] op_sel_hi:[0,1,1]
	v_pk_fma_f32 v[72:73], v[160:161], v[136:137], v[72:73] op_sel_hi:[0,1,1]
	v_pk_fma_f32 v[88:89], v[164:165], v[136:137], v[88:89] op_sel_hi:[0,1,1]
	v_pk_fma_f32 v[106:107], v[168:169], v[136:137], v[106:107] op_sel_hi:[0,1,1]
	v_pk_fma_f32 v[122:123], v[172:173], v[136:137], v[122:123] op_sel_hi:[0,1,1]
	ds_read_b128 v[134:137], v55 offset:8192
	s_waitcnt lgkmcnt(7)
	v_pk_fma_f32 v[74:75], v[160:161], v[138:139], v[74:75] op_sel_hi:[0,1,1]
	v_pk_fma_f32 v[90:91], v[164:165], v[138:139], v[90:91] op_sel_hi:[0,1,1]
	v_pk_fma_f32 v[108:109], v[168:169], v[138:139], v[108:109] op_sel_hi:[0,1,1]
	v_pk_fma_f32 v[24:25], v[172:173], v[138:139], v[24:25] op_sel_hi:[0,1,1]
	v_pk_fma_f32 v[76:77], v[160:161], v[140:141], v[76:77] op_sel_hi:[0,1,1]
	v_pk_fma_f32 v[94:95], v[164:165], v[140:141], v[94:95] op_sel_hi:[0,1,1]
	v_pk_fma_f32 v[110:111], v[168:169], v[140:141], v[110:111] op_sel_hi:[0,1,1]
	v_pk_fma_f32 v[26:27], v[172:173], v[140:141], v[26:27] op_sel_hi:[0,1,1]
	ds_read_b128 v[138:141], v56 offset:8192
	s_waitcnt lgkmcnt(7)
	v_pk_fma_f32 v[78:79], v[160:161], v[142:143], v[78:79] op_sel_hi:[0,1,1]
	v_pk_fma_f32 v[96:97], v[164:165], v[142:143], v[96:97] op_sel_hi:[0,1,1]
	v_pk_fma_f32 v[112:113], v[168:169], v[142:143], v[112:113] op_sel_hi:[0,1,1]
	v_pk_fma_f32 v[28:29], v[172:173], v[142:143], v[28:29] op_sel_hi:[0,1,1]
	v_pk_fma_f32 v[80:81], v[160:161], v[144:145], v[80:81] op_sel_hi:[0,1,1]
	v_pk_fma_f32 v[98:99], v[164:165], v[144:145], v[98:99] op_sel_hi:[0,1,1]
	v_pk_fma_f32 v[114:115], v[168:169], v[144:145], v[114:115] op_sel_hi:[0,1,1]
	v_pk_fma_f32 v[30:31], v[172:173], v[144:145], v[30:31] op_sel_hi:[0,1,1]
	ds_read_b128 v[142:145], v57 offset:8192
	s_waitcnt lgkmcnt(7)
	v_pk_fma_f32 v[66:67], v[160:161], v[146:147], v[66:67] op_sel:[1,0,0]
	v_pk_fma_f32 v[82:83], v[164:165], v[146:147], v[82:83] op_sel:[1,0,0]
	v_pk_fma_f32 v[100:101], v[168:169], v[146:147], v[100:101] op_sel:[1,0,0]
	v_pk_fma_f32 v[116:117], v[172:173], v[146:147], v[116:117] op_sel:[1,0,0]
	v_pk_fma_f32 v[68:69], v[160:161], v[148:149], v[68:69] op_sel:[1,0,0]
	v_pk_fma_f32 v[84:85], v[164:165], v[148:149], v[84:85] op_sel:[1,0,0]
	v_pk_fma_f32 v[102:103], v[168:169], v[148:149], v[102:103] op_sel:[1,0,0]
	v_pk_fma_f32 v[118:119], v[172:173], v[148:149], v[118:119] op_sel:[1,0,0]
	ds_read_b128 v[146:149], v54 offset:12288
	s_waitcnt lgkmcnt(7)
	v_pk_fma_f32 v[70:71], v[160:161], v[150:151], v[70:71] op_sel:[1,0,0]
	v_pk_fma_f32 v[86:87], v[164:165], v[150:151], v[86:87] op_sel:[1,0,0]
	v_pk_fma_f32 v[104:105], v[168:169], v[150:151], v[104:105] op_sel:[1,0,0]
	v_pk_fma_f32 v[120:121], v[172:173], v[150:151], v[120:121] op_sel:[1,0,0]
	v_pk_fma_f32 v[72:73], v[160:161], v[152:153], v[72:73] op_sel:[1,0,0]
	v_pk_fma_f32 v[88:89], v[164:165], v[152:153], v[88:89] op_sel:[1,0,0]
	v_pk_fma_f32 v[106:107], v[168:169], v[152:153], v[106:107] op_sel:[1,0,0]
	v_pk_fma_f32 v[122:123], v[172:173], v[152:153], v[122:123] op_sel:[1,0,0]
	ds_read_b128 v[150:153], v55 offset:12288
	s_waitcnt lgkmcnt(7)
	v_pk_fma_f32 v[74:75], v[160:161], v[154:155], v[74:75] op_sel:[1,0,0]
	v_pk_fma_f32 v[90:91], v[164:165], v[154:155], v[90:91] op_sel:[1,0,0]
	v_pk_fma_f32 v[108:109], v[168:169], v[154:155], v[108:109] op_sel:[1,0,0]
	v_pk_fma_f32 v[24:25], v[172:173], v[154:155], v[24:25] op_sel:[1,0,0]
	v_pk_fma_f32 v[76:77], v[160:161], v[156:157], v[76:77] op_sel:[1,0,0]
	v_pk_fma_f32 v[94:95], v[164:165], v[156:157], v[94:95] op_sel:[1,0,0]
	v_pk_fma_f32 v[110:111], v[168:169], v[156:157], v[110:111] op_sel:[1,0,0]
	v_pk_fma_f32 v[26:27], v[172:173], v[156:157], v[26:27] op_sel:[1,0,0]
	ds_read_b128 v[154:157], v56 offset:12288
	s_waitcnt lgkmcnt(7)
	v_pk_fma_f32 v[78:79], v[160:161], v[44:45], v[78:79] op_sel:[1,0,0]
	v_pk_fma_f32 v[96:97], v[164:165], v[44:45], v[96:97] op_sel:[1,0,0]
	v_pk_fma_f32 v[112:113], v[168:169], v[44:45], v[112:113] op_sel:[1,0,0]
	v_pk_fma_f32 v[28:29], v[172:173], v[44:45], v[28:29] op_sel:[1,0,0]
	v_pk_fma_f32 v[80:81], v[160:161], v[46:47], v[80:81] op_sel:[1,0,0]
	v_pk_fma_f32 v[98:99], v[164:165], v[46:47], v[98:99] op_sel:[1,0,0]
	v_pk_fma_f32 v[114:115], v[168:169], v[46:47], v[114:115] op_sel:[1,0,0]
	v_pk_fma_f32 v[30:31], v[172:173], v[46:47], v[30:31] op_sel:[1,0,0]
	ds_read_b128 v[44:47], v57 offset:12288
	s_waitcnt lgkmcnt(7)
	v_pk_fma_f32 v[66:67], v[162:163], v[130:131], v[66:67] op_sel_hi:[0,1,1]
	v_pk_fma_f32 v[82:83], v[166:167], v[130:131], v[82:83] op_sel_hi:[0,1,1]
	v_pk_fma_f32 v[100:101], v[170:171], v[130:131], v[100:101] op_sel_hi:[0,1,1]
	v_pk_fma_f32 v[116:117], v[174:175], v[130:131], v[116:117] op_sel_hi:[0,1,1]
	v_pk_fma_f32 v[68:69], v[162:163], v[132:133], v[68:69] op_sel_hi:[0,1,1]
	v_pk_fma_f32 v[84:85], v[166:167], v[132:133], v[84:85] op_sel_hi:[0,1,1]
	v_pk_fma_f32 v[102:103], v[170:171], v[132:133], v[102:103] op_sel_hi:[0,1,1]
	v_pk_fma_f32 v[118:119], v[174:175], v[132:133], v[118:119] op_sel_hi:[0,1,1]
	ds_read_b128 v[130:133], v54 offset:16384
	s_waitcnt lgkmcnt(7)
	v_pk_fma_f32 v[70:71], v[162:163], v[134:135], v[70:71] op_sel_hi:[0,1,1]
	v_pk_fma_f32 v[86:87], v[166:167], v[134:135], v[86:87] op_sel_hi:[0,1,1]
	v_pk_fma_f32 v[104:105], v[170:171], v[134:135], v[104:105] op_sel_hi:[0,1,1]
	v_pk_fma_f32 v[120:121], v[174:175], v[134:135], v[120:121] op_sel_hi:[0,1,1]
	v_pk_fma_f32 v[72:73], v[162:163], v[136:137], v[72:73] op_sel_hi:[0,1,1]
	v_pk_fma_f32 v[88:89], v[166:167], v[136:137], v[88:89] op_sel_hi:[0,1,1]
	v_pk_fma_f32 v[106:107], v[170:171], v[136:137], v[106:107] op_sel_hi:[0,1,1]
	v_pk_fma_f32 v[122:123], v[174:175], v[136:137], v[122:123] op_sel_hi:[0,1,1]
	ds_read_b128 v[134:137], v55 offset:16384
	s_waitcnt lgkmcnt(7)
	v_pk_fma_f32 v[74:75], v[162:163], v[138:139], v[74:75] op_sel_hi:[0,1,1]
	v_pk_fma_f32 v[90:91], v[166:167], v[138:139], v[90:91] op_sel_hi:[0,1,1]
	v_pk_fma_f32 v[108:109], v[170:171], v[138:139], v[108:109] op_sel_hi:[0,1,1]
	v_pk_fma_f32 v[24:25], v[174:175], v[138:139], v[24:25] op_sel_hi:[0,1,1]
	v_pk_fma_f32 v[76:77], v[162:163], v[140:141], v[76:77] op_sel_hi:[0,1,1]
	v_pk_fma_f32 v[94:95], v[166:167], v[140:141], v[94:95] op_sel_hi:[0,1,1]
	v_pk_fma_f32 v[110:111], v[170:171], v[140:141], v[110:111] op_sel_hi:[0,1,1]
	v_pk_fma_f32 v[26:27], v[174:175], v[140:141], v[26:27] op_sel_hi:[0,1,1]
	ds_read_b128 v[138:141], v56 offset:16384
	s_waitcnt lgkmcnt(7)
	v_pk_fma_f32 v[78:79], v[162:163], v[142:143], v[78:79] op_sel_hi:[0,1,1]
	v_pk_fma_f32 v[96:97], v[166:167], v[142:143], v[96:97] op_sel_hi:[0,1,1]
	v_pk_fma_f32 v[112:113], v[170:171], v[142:143], v[112:113] op_sel_hi:[0,1,1]
	v_pk_fma_f32 v[28:29], v[174:175], v[142:143], v[28:29] op_sel_hi:[0,1,1]
	v_pk_fma_f32 v[80:81], v[162:163], v[144:145], v[80:81] op_sel_hi:[0,1,1]
	v_pk_fma_f32 v[98:99], v[166:167], v[144:145], v[98:99] op_sel_hi:[0,1,1]
	v_pk_fma_f32 v[114:115], v[170:171], v[144:145], v[114:115] op_sel_hi:[0,1,1]
	v_pk_fma_f32 v[30:31], v[174:175], v[144:145], v[30:31] op_sel_hi:[0,1,1]
	ds_read_b128 v[142:145], v57 offset:16384
	s_waitcnt lgkmcnt(7)
	v_pk_fma_f32 v[66:67], v[162:163], v[146:147], v[66:67] op_sel:[1,0,0]
	v_pk_fma_f32 v[82:83], v[166:167], v[146:147], v[82:83] op_sel:[1,0,0]
	v_pk_fma_f32 v[100:101], v[170:171], v[146:147], v[100:101] op_sel:[1,0,0]
	v_pk_fma_f32 v[116:117], v[174:175], v[146:147], v[116:117] op_sel:[1,0,0]
	v_pk_fma_f32 v[68:69], v[162:163], v[148:149], v[68:69] op_sel:[1,0,0]
	v_pk_fma_f32 v[84:85], v[166:167], v[148:149], v[84:85] op_sel:[1,0,0]
	v_pk_fma_f32 v[102:103], v[170:171], v[148:149], v[102:103] op_sel:[1,0,0]
	v_pk_fma_f32 v[118:119], v[174:175], v[148:149], v[118:119] op_sel:[1,0,0]
	ds_read_b128 v[146:149], v54 offset:20480
	s_waitcnt lgkmcnt(7)
	v_pk_fma_f32 v[70:71], v[162:163], v[150:151], v[70:71] op_sel:[1,0,0]
	v_pk_fma_f32 v[86:87], v[166:167], v[150:151], v[86:87] op_sel:[1,0,0]
	v_pk_fma_f32 v[104:105], v[170:171], v[150:151], v[104:105] op_sel:[1,0,0]
	v_pk_fma_f32 v[120:121], v[174:175], v[150:151], v[120:121] op_sel:[1,0,0]
	v_pk_fma_f32 v[72:73], v[162:163], v[152:153], v[72:73] op_sel:[1,0,0]
	v_pk_fma_f32 v[88:89], v[166:167], v[152:153], v[88:89] op_sel:[1,0,0]
	v_pk_fma_f32 v[106:107], v[170:171], v[152:153], v[106:107] op_sel:[1,0,0]
	v_pk_fma_f32 v[122:123], v[174:175], v[152:153], v[122:123] op_sel:[1,0,0]
	ds_read_b128 v[150:153], v55 offset:20480
	s_waitcnt lgkmcnt(7)
	v_pk_fma_f32 v[74:75], v[162:163], v[154:155], v[74:75] op_sel:[1,0,0]
	v_pk_fma_f32 v[90:91], v[166:167], v[154:155], v[90:91] op_sel:[1,0,0]
	v_pk_fma_f32 v[108:109], v[170:171], v[154:155], v[108:109] op_sel:[1,0,0]
	v_pk_fma_f32 v[24:25], v[174:175], v[154:155], v[24:25] op_sel:[1,0,0]
	v_pk_fma_f32 v[76:77], v[162:163], v[156:157], v[76:77] op_sel:[1,0,0]
	v_pk_fma_f32 v[94:95], v[166:167], v[156:157], v[94:95] op_sel:[1,0,0]
	v_pk_fma_f32 v[110:111], v[170:171], v[156:157], v[110:111] op_sel:[1,0,0]
	v_pk_fma_f32 v[26:27], v[174:175], v[156:157], v[26:27] op_sel:[1,0,0]
	ds_read_b128 v[154:157], v56 offset:20480
	s_waitcnt lgkmcnt(7)
	v_pk_fma_f32 v[78:79], v[162:163], v[44:45], v[78:79] op_sel:[1,0,0]
	v_pk_fma_f32 v[96:97], v[166:167], v[44:45], v[96:97] op_sel:[1,0,0]
	v_pk_fma_f32 v[112:113], v[170:171], v[44:45], v[112:113] op_sel:[1,0,0]
	v_pk_fma_f32 v[28:29], v[174:175], v[44:45], v[28:29] op_sel:[1,0,0]
	v_pk_fma_f32 v[80:81], v[162:163], v[46:47], v[80:81] op_sel:[1,0,0]
	v_pk_fma_f32 v[98:99], v[166:167], v[46:47], v[98:99] op_sel:[1,0,0]
	v_pk_fma_f32 v[114:115], v[170:171], v[46:47], v[114:115] op_sel:[1,0,0]
	v_pk_fma_f32 v[30:31], v[174:175], v[46:47], v[30:31] op_sel:[1,0,0]
	ds_read_b128 v[44:47], v57 offset:20480
	global_load_dwordx4 v[160:163], v[38:39], off offset:1024 nt
	global_load_dwordx4 v[164:167], v[8:9], off offset:1024 nt
	global_load_dwordx4 v[168:171], v[10:11], off offset:1024 nt
	global_load_dwordx4 v[172:175], v[12:13], off offset:1024 nt
	s_waitcnt vmcnt(23)
	v_cvt_pk_bf16_f32 v244, v176, v177
	v_cvt_pk_bf16_f32 v245, v178, v179
	global_store_dwordx2 v[14:15], v[244:245], off offset:512 sc0 sc1
	v_pk_mul_f32 v[22:23], v[176:177], v[176:177]
	v_pk_fma_f32 v[22:23], v[178:179], v[178:179], v[22:23]
	v_add_f32_e32 v22, v22, v23
	v_add_f32_e32 v240, v240, v22
	s_waitcnt vmcnt(23)
	v_cvt_pk_bf16_f32 v246, v180, v181
	v_cvt_pk_bf16_f32 v247, v182, v183
	global_store_dwordx2 v[16:17], v[246:247], off offset:512 sc0 sc1
	v_pk_mul_f32 v[22:23], v[180:181], v[180:181]
	v_pk_fma_f32 v[22:23], v[182:183], v[182:183], v[22:23]
	v_add_f32_e32 v22, v22, v23
	v_add_f32_e32 v241, v241, v22
	s_waitcnt vmcnt(23)
	v_cvt_pk_bf16_f32 v248, v184, v185
	v_cvt_pk_bf16_f32 v249, v186, v187
	global_store_dwordx2 v[18:19], v[248:249], off offset:512 sc0 sc1
	v_pk_mul_f32 v[22:23], v[184:185], v[184:185]
	v_pk_fma_f32 v[22:23], v[186:187], v[186:187], v[22:23]
	v_add_f32_e32 v22, v22, v23
	v_add_f32_e32 v242, v242, v22
	s_waitcnt vmcnt(23)
	v_cvt_pk_bf16_f32 v232, v188, v189
	v_cvt_pk_bf16_f32 v233, v190, v191
	global_store_dwordx2 v[20:21], v[232:233], off offset:512 sc0 sc1
	v_pk_mul_f32 v[22:23], v[188:189], v[188:189]
	v_pk_fma_f32 v[22:23], v[190:191], v[190:191], v[22:23]
	v_add_f32_e32 v22, v22, v23
	v_add_f32_e32 v243, v243, v22
	s_waitcnt lgkmcnt(7)
	v_pk_fma_f32 v[66:67], v[176:177], v[130:131], v[66:67] op_sel_hi:[0,1,1]
	v_pk_fma_f32 v[82:83], v[180:181], v[130:131], v[82:83] op_sel_hi:[0,1,1]
	v_pk_fma_f32 v[100:101], v[184:185], v[130:131], v[100:101] op_sel_hi:[0,1,1]
	v_pk_fma_f32 v[116:117], v[188:189], v[130:131], v[116:117] op_sel_hi:[0,1,1]
	v_pk_fma_f32 v[68:69], v[176:177], v[132:133], v[68:69] op_sel_hi:[0,1,1]
	v_pk_fma_f32 v[84:85], v[180:181], v[132:133], v[84:85] op_sel_hi:[0,1,1]
	v_pk_fma_f32 v[102:103], v[184:185], v[132:133], v[102:103] op_sel_hi:[0,1,1]
	v_pk_fma_f32 v[118:119], v[188:189], v[132:133], v[118:119] op_sel_hi:[0,1,1]
	ds_read_b128 v[130:133], v54 offset:24576
	s_waitcnt lgkmcnt(7)
	v_pk_fma_f32 v[70:71], v[176:177], v[134:135], v[70:71] op_sel_hi:[0,1,1]
	v_pk_fma_f32 v[86:87], v[180:181], v[134:135], v[86:87] op_sel_hi:[0,1,1]
	v_pk_fma_f32 v[104:105], v[184:185], v[134:135], v[104:105] op_sel_hi:[0,1,1]
	v_pk_fma_f32 v[120:121], v[188:189], v[134:135], v[120:121] op_sel_hi:[0,1,1]
	v_pk_fma_f32 v[72:73], v[176:177], v[136:137], v[72:73] op_sel_hi:[0,1,1]
	v_pk_fma_f32 v[88:89], v[180:181], v[136:137], v[88:89] op_sel_hi:[0,1,1]
	v_pk_fma_f32 v[106:107], v[184:185], v[136:137], v[106:107] op_sel_hi:[0,1,1]
	v_pk_fma_f32 v[122:123], v[188:189], v[136:137], v[122:123] op_sel_hi:[0,1,1]
	ds_read_b128 v[134:137], v55 offset:24576
	s_waitcnt lgkmcnt(7)
	v_pk_fma_f32 v[74:75], v[176:177], v[138:139], v[74:75] op_sel_hi:[0,1,1]
	v_pk_fma_f32 v[90:91], v[180:181], v[138:139], v[90:91] op_sel_hi:[0,1,1]
	v_pk_fma_f32 v[108:109], v[184:185], v[138:139], v[108:109] op_sel_hi:[0,1,1]
	v_pk_fma_f32 v[24:25], v[188:189], v[138:139], v[24:25] op_sel_hi:[0,1,1]
	v_pk_fma_f32 v[76:77], v[176:177], v[140:141], v[76:77] op_sel_hi:[0,1,1]
	v_pk_fma_f32 v[94:95], v[180:181], v[140:141], v[94:95] op_sel_hi:[0,1,1]
	v_pk_fma_f32 v[110:111], v[184:185], v[140:141], v[110:111] op_sel_hi:[0,1,1]
	v_pk_fma_f32 v[26:27], v[188:189], v[140:141], v[26:27] op_sel_hi:[0,1,1]
	ds_read_b128 v[138:141], v56 offset:24576
	s_waitcnt lgkmcnt(7)
	v_pk_fma_f32 v[78:79], v[176:177], v[142:143], v[78:79] op_sel_hi:[0,1,1]
	v_pk_fma_f32 v[96:97], v[180:181], v[142:143], v[96:97] op_sel_hi:[0,1,1]
	v_pk_fma_f32 v[112:113], v[184:185], v[142:143], v[112:113] op_sel_hi:[0,1,1]
	v_pk_fma_f32 v[28:29], v[188:189], v[142:143], v[28:29] op_sel_hi:[0,1,1]
	v_pk_fma_f32 v[80:81], v[176:177], v[144:145], v[80:81] op_sel_hi:[0,1,1]
	v_pk_fma_f32 v[98:99], v[180:181], v[144:145], v[98:99] op_sel_hi:[0,1,1]
	v_pk_fma_f32 v[114:115], v[184:185], v[144:145], v[114:115] op_sel_hi:[0,1,1]
	v_pk_fma_f32 v[30:31], v[188:189], v[144:145], v[30:31] op_sel_hi:[0,1,1]
	ds_read_b128 v[142:145], v57 offset:24576
	s_waitcnt lgkmcnt(7)
	v_pk_fma_f32 v[66:67], v[176:177], v[146:147], v[66:67] op_sel:[1,0,0]
	v_pk_fma_f32 v[82:83], v[180:181], v[146:147], v[82:83] op_sel:[1,0,0]
	v_pk_fma_f32 v[100:101], v[184:185], v[146:147], v[100:101] op_sel:[1,0,0]
	v_pk_fma_f32 v[116:117], v[188:189], v[146:147], v[116:117] op_sel:[1,0,0]
	v_pk_fma_f32 v[68:69], v[176:177], v[148:149], v[68:69] op_sel:[1,0,0]
	v_pk_fma_f32 v[84:85], v[180:181], v[148:149], v[84:85] op_sel:[1,0,0]
	v_pk_fma_f32 v[102:103], v[184:185], v[148:149], v[102:103] op_sel:[1,0,0]
	v_pk_fma_f32 v[118:119], v[188:189], v[148:149], v[118:119] op_sel:[1,0,0]
	ds_read_b128 v[146:149], v54 offset:28672
	s_waitcnt lgkmcnt(7)
	v_pk_fma_f32 v[70:71], v[176:177], v[150:151], v[70:71] op_sel:[1,0,0]
	v_pk_fma_f32 v[86:87], v[180:181], v[150:151], v[86:87] op_sel:[1,0,0]
	v_pk_fma_f32 v[104:105], v[184:185], v[150:151], v[104:105] op_sel:[1,0,0]
	v_pk_fma_f32 v[120:121], v[188:189], v[150:151], v[120:121] op_sel:[1,0,0]
	v_pk_fma_f32 v[72:73], v[176:177], v[152:153], v[72:73] op_sel:[1,0,0]
	v_pk_fma_f32 v[88:89], v[180:181], v[152:153], v[88:89] op_sel:[1,0,0]
	v_pk_fma_f32 v[106:107], v[184:185], v[152:153], v[106:107] op_sel:[1,0,0]
	v_pk_fma_f32 v[122:123], v[188:189], v[152:153], v[122:123] op_sel:[1,0,0]
	ds_read_b128 v[150:153], v55 offset:28672
	s_waitcnt lgkmcnt(7)
	v_pk_fma_f32 v[74:75], v[176:177], v[154:155], v[74:75] op_sel:[1,0,0]
	v_pk_fma_f32 v[90:91], v[180:181], v[154:155], v[90:91] op_sel:[1,0,0]
	v_pk_fma_f32 v[108:109], v[184:185], v[154:155], v[108:109] op_sel:[1,0,0]
	v_pk_fma_f32 v[24:25], v[188:189], v[154:155], v[24:25] op_sel:[1,0,0]
	v_pk_fma_f32 v[76:77], v[176:177], v[156:157], v[76:77] op_sel:[1,0,0]
	v_pk_fma_f32 v[94:95], v[180:181], v[156:157], v[94:95] op_sel:[1,0,0]
	v_pk_fma_f32 v[110:111], v[184:185], v[156:157], v[110:111] op_sel:[1,0,0]
	v_pk_fma_f32 v[26:27], v[188:189], v[156:157], v[26:27] op_sel:[1,0,0]
	ds_read_b128 v[154:157], v56 offset:28672
	s_waitcnt lgkmcnt(7)
	v_pk_fma_f32 v[78:79], v[176:177], v[44:45], v[78:79] op_sel:[1,0,0]
	v_pk_fma_f32 v[96:97], v[180:181], v[44:45], v[96:97] op_sel:[1,0,0]
	v_pk_fma_f32 v[112:113], v[184:185], v[44:45], v[112:113] op_sel:[1,0,0]
	v_pk_fma_f32 v[28:29], v[188:189], v[44:45], v[28:29] op_sel:[1,0,0]
	v_pk_fma_f32 v[80:81], v[176:177], v[46:47], v[80:81] op_sel:[1,0,0]
	v_pk_fma_f32 v[98:99], v[180:181], v[46:47], v[98:99] op_sel:[1,0,0]
	v_pk_fma_f32 v[114:115], v[184:185], v[46:47], v[114:115] op_sel:[1,0,0]
	v_pk_fma_f32 v[30:31], v[188:189], v[46:47], v[30:31] op_sel:[1,0,0]
	ds_read_b128 v[44:47], v57 offset:28672
	s_waitcnt lgkmcnt(7)
	v_pk_fma_f32 v[66:67], v[178:179], v[130:131], v[66:67] op_sel_hi:[0,1,1]
	v_pk_fma_f32 v[82:83], v[182:183], v[130:131], v[82:83] op_sel_hi:[0,1,1]
	v_pk_fma_f32 v[100:101], v[186:187], v[130:131], v[100:101] op_sel_hi:[0,1,1]
	v_pk_fma_f32 v[116:117], v[190:191], v[130:131], v[116:117] op_sel_hi:[0,1,1]
	v_pk_fma_f32 v[68:69], v[178:179], v[132:133], v[68:69] op_sel_hi:[0,1,1]
	v_pk_fma_f32 v[84:85], v[182:183], v[132:133], v[84:85] op_sel_hi:[0,1,1]
	v_pk_fma_f32 v[102:103], v[186:187], v[132:133], v[102:103] op_sel_hi:[0,1,1]
	v_pk_fma_f32 v[118:119], v[190:191], v[132:133], v[118:119] op_sel_hi:[0,1,1]
	ds_read_b128 v[130:133], v54 offset:32768
	s_waitcnt lgkmcnt(7)
	v_pk_fma_f32 v[70:71], v[178:179], v[134:135], v[70:71] op_sel_hi:[0,1,1]
	v_pk_fma_f32 v[86:87], v[182:183], v[134:135], v[86:87] op_sel_hi:[0,1,1]
	v_pk_fma_f32 v[104:105], v[186:187], v[134:135], v[104:105] op_sel_hi:[0,1,1]
	v_pk_fma_f32 v[120:121], v[190:191], v[134:135], v[120:121] op_sel_hi:[0,1,1]
	v_pk_fma_f32 v[72:73], v[178:179], v[136:137], v[72:73] op_sel_hi:[0,1,1]
	v_pk_fma_f32 v[88:89], v[182:183], v[136:137], v[88:89] op_sel_hi:[0,1,1]
	v_pk_fma_f32 v[106:107], v[186:187], v[136:137], v[106:107] op_sel_hi:[0,1,1]
	v_pk_fma_f32 v[122:123], v[190:191], v[136:137], v[122:123] op_sel_hi:[0,1,1]
	ds_read_b128 v[134:137], v55 offset:32768
	s_waitcnt lgkmcnt(7)
	v_pk_fma_f32 v[74:75], v[178:179], v[138:139], v[74:75] op_sel_hi:[0,1,1]
	v_pk_fma_f32 v[90:91], v[182:183], v[138:139], v[90:91] op_sel_hi:[0,1,1]
	v_pk_fma_f32 v[108:109], v[186:187], v[138:139], v[108:109] op_sel_hi:[0,1,1]
	v_pk_fma_f32 v[24:25], v[190:191], v[138:139], v[24:25] op_sel_hi:[0,1,1]
	v_pk_fma_f32 v[76:77], v[178:179], v[140:141], v[76:77] op_sel_hi:[0,1,1]
	v_pk_fma_f32 v[94:95], v[182:183], v[140:141], v[94:95] op_sel_hi:[0,1,1]
	v_pk_fma_f32 v[110:111], v[186:187], v[140:141], v[110:111] op_sel_hi:[0,1,1]
	v_pk_fma_f32 v[26:27], v[190:191], v[140:141], v[26:27] op_sel_hi:[0,1,1]
	ds_read_b128 v[138:141], v56 offset:32768
	s_waitcnt lgkmcnt(7)
	v_pk_fma_f32 v[78:79], v[178:179], v[142:143], v[78:79] op_sel_hi:[0,1,1]
	v_pk_fma_f32 v[96:97], v[182:183], v[142:143], v[96:97] op_sel_hi:[0,1,1]
	v_pk_fma_f32 v[112:113], v[186:187], v[142:143], v[112:113] op_sel_hi:[0,1,1]
	v_pk_fma_f32 v[28:29], v[190:191], v[142:143], v[28:29] op_sel_hi:[0,1,1]
	v_pk_fma_f32 v[80:81], v[178:179], v[144:145], v[80:81] op_sel_hi:[0,1,1]
	v_pk_fma_f32 v[98:99], v[182:183], v[144:145], v[98:99] op_sel_hi:[0,1,1]
	v_pk_fma_f32 v[114:115], v[186:187], v[144:145], v[114:115] op_sel_hi:[0,1,1]
	v_pk_fma_f32 v[30:31], v[190:191], v[144:145], v[30:31] op_sel_hi:[0,1,1]
	ds_read_b128 v[142:145], v57 offset:32768
	s_waitcnt lgkmcnt(7)
	v_pk_fma_f32 v[66:67], v[178:179], v[146:147], v[66:67] op_sel:[1,0,0]
	v_pk_fma_f32 v[82:83], v[182:183], v[146:147], v[82:83] op_sel:[1,0,0]
	v_pk_fma_f32 v[100:101], v[186:187], v[146:147], v[100:101] op_sel:[1,0,0]
	v_pk_fma_f32 v[116:117], v[190:191], v[146:147], v[116:117] op_sel:[1,0,0]
	v_pk_fma_f32 v[68:69], v[178:179], v[148:149], v[68:69] op_sel:[1,0,0]
	v_pk_fma_f32 v[84:85], v[182:183], v[148:149], v[84:85] op_sel:[1,0,0]
	v_pk_fma_f32 v[102:103], v[186:187], v[148:149], v[102:103] op_sel:[1,0,0]
	v_pk_fma_f32 v[118:119], v[190:191], v[148:149], v[118:119] op_sel:[1,0,0]
	ds_read_b128 v[146:149], v54 offset:36864
	s_waitcnt lgkmcnt(7)
	v_pk_fma_f32 v[70:71], v[178:179], v[150:151], v[70:71] op_sel:[1,0,0]
	v_pk_fma_f32 v[86:87], v[182:183], v[150:151], v[86:87] op_sel:[1,0,0]
	v_pk_fma_f32 v[104:105], v[186:187], v[150:151], v[104:105] op_sel:[1,0,0]
	v_pk_fma_f32 v[120:121], v[190:191], v[150:151], v[120:121] op_sel:[1,0,0]
	v_pk_fma_f32 v[72:73], v[178:179], v[152:153], v[72:73] op_sel:[1,0,0]
	v_pk_fma_f32 v[88:89], v[182:183], v[152:153], v[88:89] op_sel:[1,0,0]
	v_pk_fma_f32 v[106:107], v[186:187], v[152:153], v[106:107] op_sel:[1,0,0]
	v_pk_fma_f32 v[122:123], v[190:191], v[152:153], v[122:123] op_sel:[1,0,0]
	ds_read_b128 v[150:153], v55 offset:36864
	s_waitcnt lgkmcnt(7)
	v_pk_fma_f32 v[74:75], v[178:179], v[154:155], v[74:75] op_sel:[1,0,0]
	v_pk_fma_f32 v[90:91], v[182:183], v[154:155], v[90:91] op_sel:[1,0,0]
	v_pk_fma_f32 v[108:109], v[186:187], v[154:155], v[108:109] op_sel:[1,0,0]
	v_pk_fma_f32 v[24:25], v[190:191], v[154:155], v[24:25] op_sel:[1,0,0]
	v_pk_fma_f32 v[76:77], v[178:179], v[156:157], v[76:77] op_sel:[1,0,0]
	v_pk_fma_f32 v[94:95], v[182:183], v[156:157], v[94:95] op_sel:[1,0,0]
	v_pk_fma_f32 v[110:111], v[186:187], v[156:157], v[110:111] op_sel:[1,0,0]
	v_pk_fma_f32 v[26:27], v[190:191], v[156:157], v[26:27] op_sel:[1,0,0]
	ds_read_b128 v[154:157], v56 offset:36864
	s_waitcnt lgkmcnt(7)
	v_pk_fma_f32 v[78:79], v[178:179], v[44:45], v[78:79] op_sel:[1,0,0]
	v_pk_fma_f32 v[96:97], v[182:183], v[44:45], v[96:97] op_sel:[1,0,0]
	v_pk_fma_f32 v[112:113], v[186:187], v[44:45], v[112:113] op_sel:[1,0,0]
	v_pk_fma_f32 v[28:29], v[190:191], v[44:45], v[28:29] op_sel:[1,0,0]
	v_pk_fma_f32 v[80:81], v[178:179], v[46:47], v[80:81] op_sel:[1,0,0]
	v_pk_fma_f32 v[98:99], v[182:183], v[46:47], v[98:99] op_sel:[1,0,0]
	v_pk_fma_f32 v[114:115], v[186:187], v[46:47], v[114:115] op_sel:[1,0,0]
	v_pk_fma_f32 v[30:31], v[190:191], v[46:47], v[30:31] op_sel:[1,0,0]
	ds_read_b128 v[44:47], v57 offset:36864
	global_load_dwordx4 v[176:179], v[38:39], off offset:2048 nt
	global_load_dwordx4 v[180:183], v[8:9], off offset:2048 nt
	global_load_dwordx4 v[184:187], v[10:11], off offset:2048 nt
	global_load_dwordx4 v[188:191], v[12:13], off offset:2048 nt
	s_waitcnt vmcnt(27)
	v_cvt_pk_bf16_f32 v244, v192, v193
	v_cvt_pk_bf16_f32 v245, v194, v195
	global_store_dwordx2 v[14:15], v[244:245], off offset:1024 sc0 sc1
	v_pk_mul_f32 v[22:23], v[192:193], v[192:193]
	v_pk_fma_f32 v[22:23], v[194:195], v[194:195], v[22:23]
	v_add_f32_e32 v22, v22, v23
	v_add_f32_e32 v240, v240, v22
	s_waitcnt vmcnt(27)
	v_cvt_pk_bf16_f32 v246, v196, v197
	v_cvt_pk_bf16_f32 v247, v198, v199
	global_store_dwordx2 v[16:17], v[246:247], off offset:1024 sc0 sc1
	v_pk_mul_f32 v[22:23], v[196:197], v[196:197]
	v_pk_fma_f32 v[22:23], v[198:199], v[198:199], v[22:23]
	v_add_f32_e32 v22, v22, v23
	v_add_f32_e32 v241, v241, v22
	s_waitcnt vmcnt(27)
	v_cvt_pk_bf16_f32 v248, v200, v201
	v_cvt_pk_bf16_f32 v249, v202, v203
	global_store_dwordx2 v[18:19], v[248:249], off offset:1024 sc0 sc1
	v_pk_mul_f32 v[22:23], v[200:201], v[200:201]
	v_pk_fma_f32 v[22:23], v[202:203], v[202:203], v[22:23]
	v_add_f32_e32 v22, v22, v23
	v_add_f32_e32 v242, v242, v22
	s_waitcnt vmcnt(27)
	v_cvt_pk_bf16_f32 v232, v204, v205
	v_cvt_pk_bf16_f32 v233, v206, v207
	global_store_dwordx2 v[20:21], v[232:233], off offset:1024 sc0 sc1
	v_pk_mul_f32 v[22:23], v[204:205], v[204:205]
	v_pk_fma_f32 v[22:23], v[206:207], v[206:207], v[22:23]
	v_add_f32_e32 v22, v22, v23
	v_add_f32_e32 v243, v243, v22
	s_waitcnt lgkmcnt(7)
	v_pk_fma_f32 v[66:67], v[192:193], v[130:131], v[66:67] op_sel_hi:[0,1,1]
	v_pk_fma_f32 v[82:83], v[196:197], v[130:131], v[82:83] op_sel_hi:[0,1,1]
	v_pk_fma_f32 v[100:101], v[200:201], v[130:131], v[100:101] op_sel_hi:[0,1,1]
	v_pk_fma_f32 v[116:117], v[204:205], v[130:131], v[116:117] op_sel_hi:[0,1,1]
	v_pk_fma_f32 v[68:69], v[192:193], v[132:133], v[68:69] op_sel_hi:[0,1,1]
	v_pk_fma_f32 v[84:85], v[196:197], v[132:133], v[84:85] op_sel_hi:[0,1,1]
	v_pk_fma_f32 v[102:103], v[200:201], v[132:133], v[102:103] op_sel_hi:[0,1,1]
	v_pk_fma_f32 v[118:119], v[204:205], v[132:133], v[118:119] op_sel_hi:[0,1,1]
	ds_read_b128 v[130:133], v54 offset:40960
	s_waitcnt lgkmcnt(7)
	v_pk_fma_f32 v[70:71], v[192:193], v[134:135], v[70:71] op_sel_hi:[0,1,1]
	v_pk_fma_f32 v[86:87], v[196:197], v[134:135], v[86:87] op_sel_hi:[0,1,1]
	v_pk_fma_f32 v[104:105], v[200:201], v[134:135], v[104:105] op_sel_hi:[0,1,1]
	v_pk_fma_f32 v[120:121], v[204:205], v[134:135], v[120:121] op_sel_hi:[0,1,1]
	v_pk_fma_f32 v[72:73], v[192:193], v[136:137], v[72:73] op_sel_hi:[0,1,1]
	v_pk_fma_f32 v[88:89], v[196:197], v[136:137], v[88:89] op_sel_hi:[0,1,1]
	v_pk_fma_f32 v[106:107], v[200:201], v[136:137], v[106:107] op_sel_hi:[0,1,1]
	v_pk_fma_f32 v[122:123], v[204:205], v[136:137], v[122:123] op_sel_hi:[0,1,1]
	ds_read_b128 v[134:137], v55 offset:40960
	s_waitcnt lgkmcnt(7)
	v_pk_fma_f32 v[74:75], v[192:193], v[138:139], v[74:75] op_sel_hi:[0,1,1]
	v_pk_fma_f32 v[90:91], v[196:197], v[138:139], v[90:91] op_sel_hi:[0,1,1]
	v_pk_fma_f32 v[108:109], v[200:201], v[138:139], v[108:109] op_sel_hi:[0,1,1]
	v_pk_fma_f32 v[24:25], v[204:205], v[138:139], v[24:25] op_sel_hi:[0,1,1]
	v_pk_fma_f32 v[76:77], v[192:193], v[140:141], v[76:77] op_sel_hi:[0,1,1]
	v_pk_fma_f32 v[94:95], v[196:197], v[140:141], v[94:95] op_sel_hi:[0,1,1]
	v_pk_fma_f32 v[110:111], v[200:201], v[140:141], v[110:111] op_sel_hi:[0,1,1]
	v_pk_fma_f32 v[26:27], v[204:205], v[140:141], v[26:27] op_sel_hi:[0,1,1]
	ds_read_b128 v[138:141], v56 offset:40960
	s_waitcnt lgkmcnt(7)
	v_pk_fma_f32 v[78:79], v[192:193], v[142:143], v[78:79] op_sel_hi:[0,1,1]
	v_pk_fma_f32 v[96:97], v[196:197], v[142:143], v[96:97] op_sel_hi:[0,1,1]
	v_pk_fma_f32 v[112:113], v[200:201], v[142:143], v[112:113] op_sel_hi:[0,1,1]
	v_pk_fma_f32 v[28:29], v[204:205], v[142:143], v[28:29] op_sel_hi:[0,1,1]
	v_pk_fma_f32 v[80:81], v[192:193], v[144:145], v[80:81] op_sel_hi:[0,1,1]
	v_pk_fma_f32 v[98:99], v[196:197], v[144:145], v[98:99] op_sel_hi:[0,1,1]
	v_pk_fma_f32 v[114:115], v[200:201], v[144:145], v[114:115] op_sel_hi:[0,1,1]
	v_pk_fma_f32 v[30:31], v[204:205], v[144:145], v[30:31] op_sel_hi:[0,1,1]
	ds_read_b128 v[142:145], v57 offset:40960
	s_waitcnt lgkmcnt(7)
	v_pk_fma_f32 v[66:67], v[192:193], v[146:147], v[66:67] op_sel:[1,0,0]
	v_pk_fma_f32 v[82:83], v[196:197], v[146:147], v[82:83] op_sel:[1,0,0]
	v_pk_fma_f32 v[100:101], v[200:201], v[146:147], v[100:101] op_sel:[1,0,0]
	v_pk_fma_f32 v[116:117], v[204:205], v[146:147], v[116:117] op_sel:[1,0,0]
	v_pk_fma_f32 v[68:69], v[192:193], v[148:149], v[68:69] op_sel:[1,0,0]
	v_pk_fma_f32 v[84:85], v[196:197], v[148:149], v[84:85] op_sel:[1,0,0]
	v_pk_fma_f32 v[102:103], v[200:201], v[148:149], v[102:103] op_sel:[1,0,0]
	v_pk_fma_f32 v[118:119], v[204:205], v[148:149], v[118:119] op_sel:[1,0,0]
	ds_read_b128 v[146:149], v54 offset:45056
	s_waitcnt lgkmcnt(7)
	v_pk_fma_f32 v[70:71], v[192:193], v[150:151], v[70:71] op_sel:[1,0,0]
	v_pk_fma_f32 v[86:87], v[196:197], v[150:151], v[86:87] op_sel:[1,0,0]
	v_pk_fma_f32 v[104:105], v[200:201], v[150:151], v[104:105] op_sel:[1,0,0]
	v_pk_fma_f32 v[120:121], v[204:205], v[150:151], v[120:121] op_sel:[1,0,0]
	v_pk_fma_f32 v[72:73], v[192:193], v[152:153], v[72:73] op_sel:[1,0,0]
	v_pk_fma_f32 v[88:89], v[196:197], v[152:153], v[88:89] op_sel:[1,0,0]
	v_pk_fma_f32 v[106:107], v[200:201], v[152:153], v[106:107] op_sel:[1,0,0]
	v_pk_fma_f32 v[122:123], v[204:205], v[152:153], v[122:123] op_sel:[1,0,0]
	ds_read_b128 v[150:153], v55 offset:45056
	s_waitcnt lgkmcnt(7)
	v_pk_fma_f32 v[74:75], v[192:193], v[154:155], v[74:75] op_sel:[1,0,0]
	v_pk_fma_f32 v[90:91], v[196:197], v[154:155], v[90:91] op_sel:[1,0,0]
	v_pk_fma_f32 v[108:109], v[200:201], v[154:155], v[108:109] op_sel:[1,0,0]
	v_pk_fma_f32 v[24:25], v[204:205], v[154:155], v[24:25] op_sel:[1,0,0]
	v_pk_fma_f32 v[76:77], v[192:193], v[156:157], v[76:77] op_sel:[1,0,0]
	v_pk_fma_f32 v[94:95], v[196:197], v[156:157], v[94:95] op_sel:[1,0,0]
	v_pk_fma_f32 v[110:111], v[200:201], v[156:157], v[110:111] op_sel:[1,0,0]
	v_pk_fma_f32 v[26:27], v[204:205], v[156:157], v[26:27] op_sel:[1,0,0]
	ds_read_b128 v[154:157], v56 offset:45056
	s_waitcnt lgkmcnt(7)
	v_pk_fma_f32 v[78:79], v[192:193], v[44:45], v[78:79] op_sel:[1,0,0]
	v_pk_fma_f32 v[96:97], v[196:197], v[44:45], v[96:97] op_sel:[1,0,0]
	v_pk_fma_f32 v[112:113], v[200:201], v[44:45], v[112:113] op_sel:[1,0,0]
	v_pk_fma_f32 v[28:29], v[204:205], v[44:45], v[28:29] op_sel:[1,0,0]
	v_pk_fma_f32 v[80:81], v[192:193], v[46:47], v[80:81] op_sel:[1,0,0]
	v_pk_fma_f32 v[98:99], v[196:197], v[46:47], v[98:99] op_sel:[1,0,0]
	v_pk_fma_f32 v[114:115], v[200:201], v[46:47], v[114:115] op_sel:[1,0,0]
	v_pk_fma_f32 v[30:31], v[204:205], v[46:47], v[30:31] op_sel:[1,0,0]
	ds_read_b128 v[44:47], v57 offset:45056
	s_waitcnt lgkmcnt(7)
	v_pk_fma_f32 v[66:67], v[194:195], v[130:131], v[66:67] op_sel_hi:[0,1,1]
	v_pk_fma_f32 v[82:83], v[198:199], v[130:131], v[82:83] op_sel_hi:[0,1,1]
	v_pk_fma_f32 v[100:101], v[202:203], v[130:131], v[100:101] op_sel_hi:[0,1,1]
	v_pk_fma_f32 v[116:117], v[206:207], v[130:131], v[116:117] op_sel_hi:[0,1,1]
	v_pk_fma_f32 v[68:69], v[194:195], v[132:133], v[68:69] op_sel_hi:[0,1,1]
	v_pk_fma_f32 v[84:85], v[198:199], v[132:133], v[84:85] op_sel_hi:[0,1,1]
	v_pk_fma_f32 v[102:103], v[202:203], v[132:133], v[102:103] op_sel_hi:[0,1,1]
	v_pk_fma_f32 v[118:119], v[206:207], v[132:133], v[118:119] op_sel_hi:[0,1,1]
	ds_read_b128 v[130:133], v54 offset:49152
	s_waitcnt lgkmcnt(7)
	v_pk_fma_f32 v[70:71], v[194:195], v[134:135], v[70:71] op_sel_hi:[0,1,1]
	v_pk_fma_f32 v[86:87], v[198:199], v[134:135], v[86:87] op_sel_hi:[0,1,1]
	v_pk_fma_f32 v[104:105], v[202:203], v[134:135], v[104:105] op_sel_hi:[0,1,1]
	v_pk_fma_f32 v[120:121], v[206:207], v[134:135], v[120:121] op_sel_hi:[0,1,1]
	v_pk_fma_f32 v[72:73], v[194:195], v[136:137], v[72:73] op_sel_hi:[0,1,1]
	v_pk_fma_f32 v[88:89], v[198:199], v[136:137], v[88:89] op_sel_hi:[0,1,1]
	v_pk_fma_f32 v[106:107], v[202:203], v[136:137], v[106:107] op_sel_hi:[0,1,1]
	v_pk_fma_f32 v[122:123], v[206:207], v[136:137], v[122:123] op_sel_hi:[0,1,1]
	ds_read_b128 v[134:137], v55 offset:49152
	s_waitcnt lgkmcnt(7)
	v_pk_fma_f32 v[74:75], v[194:195], v[138:139], v[74:75] op_sel_hi:[0,1,1]
	v_pk_fma_f32 v[90:91], v[198:199], v[138:139], v[90:91] op_sel_hi:[0,1,1]
	v_pk_fma_f32 v[108:109], v[202:203], v[138:139], v[108:109] op_sel_hi:[0,1,1]
	v_pk_fma_f32 v[24:25], v[206:207], v[138:139], v[24:25] op_sel_hi:[0,1,1]
	v_pk_fma_f32 v[76:77], v[194:195], v[140:141], v[76:77] op_sel_hi:[0,1,1]
	v_pk_fma_f32 v[94:95], v[198:199], v[140:141], v[94:95] op_sel_hi:[0,1,1]
	v_pk_fma_f32 v[110:111], v[202:203], v[140:141], v[110:111] op_sel_hi:[0,1,1]
	v_pk_fma_f32 v[26:27], v[206:207], v[140:141], v[26:27] op_sel_hi:[0,1,1]
	ds_read_b128 v[138:141], v56 offset:49152
	s_waitcnt lgkmcnt(7)
	v_pk_fma_f32 v[78:79], v[194:195], v[142:143], v[78:79] op_sel_hi:[0,1,1]
	v_pk_fma_f32 v[96:97], v[198:199], v[142:143], v[96:97] op_sel_hi:[0,1,1]
	v_pk_fma_f32 v[112:113], v[202:203], v[142:143], v[112:113] op_sel_hi:[0,1,1]
	v_pk_fma_f32 v[28:29], v[206:207], v[142:143], v[28:29] op_sel_hi:[0,1,1]
	v_pk_fma_f32 v[80:81], v[194:195], v[144:145], v[80:81] op_sel_hi:[0,1,1]
	v_pk_fma_f32 v[98:99], v[198:199], v[144:145], v[98:99] op_sel_hi:[0,1,1]
	v_pk_fma_f32 v[114:115], v[202:203], v[144:145], v[114:115] op_sel_hi:[0,1,1]
	v_pk_fma_f32 v[30:31], v[206:207], v[144:145], v[30:31] op_sel_hi:[0,1,1]
	ds_read_b128 v[142:145], v57 offset:49152
	s_waitcnt lgkmcnt(7)
	v_pk_fma_f32 v[66:67], v[194:195], v[146:147], v[66:67] op_sel:[1,0,0]
	v_pk_fma_f32 v[82:83], v[198:199], v[146:147], v[82:83] op_sel:[1,0,0]
	v_pk_fma_f32 v[100:101], v[202:203], v[146:147], v[100:101] op_sel:[1,0,0]
	v_pk_fma_f32 v[116:117], v[206:207], v[146:147], v[116:117] op_sel:[1,0,0]
	v_pk_fma_f32 v[68:69], v[194:195], v[148:149], v[68:69] op_sel:[1,0,0]
	v_pk_fma_f32 v[84:85], v[198:199], v[148:149], v[84:85] op_sel:[1,0,0]
	v_pk_fma_f32 v[102:103], v[202:203], v[148:149], v[102:103] op_sel:[1,0,0]
	v_pk_fma_f32 v[118:119], v[206:207], v[148:149], v[118:119] op_sel:[1,0,0]
	ds_read_b128 v[146:149], v54 offset:53248
	s_waitcnt lgkmcnt(7)
	v_pk_fma_f32 v[70:71], v[194:195], v[150:151], v[70:71] op_sel:[1,0,0]
	v_pk_fma_f32 v[86:87], v[198:199], v[150:151], v[86:87] op_sel:[1,0,0]
	v_pk_fma_f32 v[104:105], v[202:203], v[150:151], v[104:105] op_sel:[1,0,0]
	v_pk_fma_f32 v[120:121], v[206:207], v[150:151], v[120:121] op_sel:[1,0,0]
	v_pk_fma_f32 v[72:73], v[194:195], v[152:153], v[72:73] op_sel:[1,0,0]
	v_pk_fma_f32 v[88:89], v[198:199], v[152:153], v[88:89] op_sel:[1,0,0]
	v_pk_fma_f32 v[106:107], v[202:203], v[152:153], v[106:107] op_sel:[1,0,0]
	v_pk_fma_f32 v[122:123], v[206:207], v[152:153], v[122:123] op_sel:[1,0,0]
	ds_read_b128 v[150:153], v55 offset:53248
	s_waitcnt lgkmcnt(7)
	v_pk_fma_f32 v[74:75], v[194:195], v[154:155], v[74:75] op_sel:[1,0,0]
	v_pk_fma_f32 v[90:91], v[198:199], v[154:155], v[90:91] op_sel:[1,0,0]
	v_pk_fma_f32 v[108:109], v[202:203], v[154:155], v[108:109] op_sel:[1,0,0]
	v_pk_fma_f32 v[24:25], v[206:207], v[154:155], v[24:25] op_sel:[1,0,0]
	v_pk_fma_f32 v[76:77], v[194:195], v[156:157], v[76:77] op_sel:[1,0,0]
	v_pk_fma_f32 v[94:95], v[198:199], v[156:157], v[94:95] op_sel:[1,0,0]
	v_pk_fma_f32 v[110:111], v[202:203], v[156:157], v[110:111] op_sel:[1,0,0]
	v_pk_fma_f32 v[26:27], v[206:207], v[156:157], v[26:27] op_sel:[1,0,0]
	ds_read_b128 v[154:157], v56 offset:53248
	s_waitcnt lgkmcnt(7)
	v_pk_fma_f32 v[78:79], v[194:195], v[44:45], v[78:79] op_sel:[1,0,0]
	v_pk_fma_f32 v[96:97], v[198:199], v[44:45], v[96:97] op_sel:[1,0,0]
	v_pk_fma_f32 v[112:113], v[202:203], v[44:45], v[112:113] op_sel:[1,0,0]
	v_pk_fma_f32 v[28:29], v[206:207], v[44:45], v[28:29] op_sel:[1,0,0]
	v_pk_fma_f32 v[80:81], v[194:195], v[46:47], v[80:81] op_sel:[1,0,0]
	v_pk_fma_f32 v[98:99], v[198:199], v[46:47], v[98:99] op_sel:[1,0,0]
	v_pk_fma_f32 v[114:115], v[202:203], v[46:47], v[114:115] op_sel:[1,0,0]
	v_pk_fma_f32 v[30:31], v[206:207], v[46:47], v[30:31] op_sel:[1,0,0]
	ds_read_b128 v[44:47], v57 offset:53248
	global_load_dwordx4 v[192:195], v[38:39], off offset:3072 nt
	global_load_dwordx4 v[196:199], v[8:9], off offset:3072 nt
	global_load_dwordx4 v[200:203], v[10:11], off offset:3072 nt
	global_load_dwordx4 v[204:207], v[12:13], off offset:3072 nt
	s_waitcnt vmcnt(31)
	v_cvt_pk_bf16_f32 v244, v208, v209
	v_cvt_pk_bf16_f32 v245, v210, v211
	global_store_dwordx2 v[14:15], v[244:245], off offset:1536 sc0 sc1
	v_pk_mul_f32 v[22:23], v[208:209], v[208:209]
	v_pk_fma_f32 v[22:23], v[210:211], v[210:211], v[22:23]
	v_add_f32_e32 v22, v22, v23
	v_add_f32_e32 v240, v240, v22
	s_waitcnt vmcnt(31)
	v_cvt_pk_bf16_f32 v246, v212, v213
	v_cvt_pk_bf16_f32 v247, v214, v215
	global_store_dwordx2 v[16:17], v[246:247], off offset:1536 sc0 sc1
	v_pk_mul_f32 v[22:23], v[212:213], v[212:213]
	v_pk_fma_f32 v[22:23], v[214:215], v[214:215], v[22:23]
	v_add_f32_e32 v22, v22, v23
	v_add_f32_e32 v241, v241, v22
	s_waitcnt vmcnt(31)
	v_cvt_pk_bf16_f32 v248, v216, v217
	v_cvt_pk_bf16_f32 v249, v218, v219
	global_store_dwordx2 v[18:19], v[248:249], off offset:1536 sc0 sc1
	v_pk_mul_f32 v[22:23], v[216:217], v[216:217]
	v_pk_fma_f32 v[22:23], v[218:219], v[218:219], v[22:23]
	v_add_f32_e32 v22, v22, v23
	v_add_f32_e32 v242, v242, v22
	s_waitcnt vmcnt(31)
	v_cvt_pk_bf16_f32 v232, v220, v221
	v_cvt_pk_bf16_f32 v233, v222, v223
	global_store_dwordx2 v[20:21], v[232:233], off offset:1536 sc0 sc1
	v_pk_mul_f32 v[22:23], v[220:221], v[220:221]
	v_pk_fma_f32 v[22:23], v[222:223], v[222:223], v[22:23]
	v_add_f32_e32 v22, v22, v23
	v_add_f32_e32 v243, v243, v22
	s_waitcnt lgkmcnt(7)
	v_pk_fma_f32 v[66:67], v[208:209], v[130:131], v[66:67] op_sel_hi:[0,1,1]
	v_pk_fma_f32 v[82:83], v[212:213], v[130:131], v[82:83] op_sel_hi:[0,1,1]
	v_pk_fma_f32 v[100:101], v[216:217], v[130:131], v[100:101] op_sel_hi:[0,1,1]
	v_pk_fma_f32 v[116:117], v[220:221], v[130:131], v[116:117] op_sel_hi:[0,1,1]
	v_pk_fma_f32 v[68:69], v[208:209], v[132:133], v[68:69] op_sel_hi:[0,1,1]
	v_pk_fma_f32 v[84:85], v[212:213], v[132:133], v[84:85] op_sel_hi:[0,1,1]
	v_pk_fma_f32 v[102:103], v[216:217], v[132:133], v[102:103] op_sel_hi:[0,1,1]
	v_pk_fma_f32 v[118:119], v[220:221], v[132:133], v[118:119] op_sel_hi:[0,1,1]
	ds_read_b128 v[130:133], v54 offset:57344
	s_waitcnt lgkmcnt(7)
	v_pk_fma_f32 v[70:71], v[208:209], v[134:135], v[70:71] op_sel_hi:[0,1,1]
	v_pk_fma_f32 v[86:87], v[212:213], v[134:135], v[86:87] op_sel_hi:[0,1,1]
	v_pk_fma_f32 v[104:105], v[216:217], v[134:135], v[104:105] op_sel_hi:[0,1,1]
	v_pk_fma_f32 v[120:121], v[220:221], v[134:135], v[120:121] op_sel_hi:[0,1,1]
	v_pk_fma_f32 v[72:73], v[208:209], v[136:137], v[72:73] op_sel_hi:[0,1,1]
	v_pk_fma_f32 v[88:89], v[212:213], v[136:137], v[88:89] op_sel_hi:[0,1,1]
	v_pk_fma_f32 v[106:107], v[216:217], v[136:137], v[106:107] op_sel_hi:[0,1,1]
	v_pk_fma_f32 v[122:123], v[220:221], v[136:137], v[122:123] op_sel_hi:[0,1,1]
	ds_read_b128 v[134:137], v55 offset:57344
	s_waitcnt lgkmcnt(7)
	v_pk_fma_f32 v[74:75], v[208:209], v[138:139], v[74:75] op_sel_hi:[0,1,1]
	v_pk_fma_f32 v[90:91], v[212:213], v[138:139], v[90:91] op_sel_hi:[0,1,1]
	v_pk_fma_f32 v[108:109], v[216:217], v[138:139], v[108:109] op_sel_hi:[0,1,1]
	v_pk_fma_f32 v[24:25], v[220:221], v[138:139], v[24:25] op_sel_hi:[0,1,1]
	v_pk_fma_f32 v[76:77], v[208:209], v[140:141], v[76:77] op_sel_hi:[0,1,1]
	v_pk_fma_f32 v[94:95], v[212:213], v[140:141], v[94:95] op_sel_hi:[0,1,1]
	v_pk_fma_f32 v[110:111], v[216:217], v[140:141], v[110:111] op_sel_hi:[0,1,1]
	v_pk_fma_f32 v[26:27], v[220:221], v[140:141], v[26:27] op_sel_hi:[0,1,1]
	ds_read_b128 v[138:141], v56 offset:57344
	s_waitcnt lgkmcnt(7)
	v_pk_fma_f32 v[78:79], v[208:209], v[142:143], v[78:79] op_sel_hi:[0,1,1]
	v_pk_fma_f32 v[96:97], v[212:213], v[142:143], v[96:97] op_sel_hi:[0,1,1]
	v_pk_fma_f32 v[112:113], v[216:217], v[142:143], v[112:113] op_sel_hi:[0,1,1]
	v_pk_fma_f32 v[28:29], v[220:221], v[142:143], v[28:29] op_sel_hi:[0,1,1]
	v_pk_fma_f32 v[80:81], v[208:209], v[144:145], v[80:81] op_sel_hi:[0,1,1]
	v_pk_fma_f32 v[98:99], v[212:213], v[144:145], v[98:99] op_sel_hi:[0,1,1]
	v_pk_fma_f32 v[114:115], v[216:217], v[144:145], v[114:115] op_sel_hi:[0,1,1]
	v_pk_fma_f32 v[30:31], v[220:221], v[144:145], v[30:31] op_sel_hi:[0,1,1]
	ds_read_b128 v[142:145], v57 offset:57344
	s_waitcnt lgkmcnt(7)
	v_pk_fma_f32 v[66:67], v[208:209], v[146:147], v[66:67] op_sel:[1,0,0]
	v_pk_fma_f32 v[82:83], v[212:213], v[146:147], v[82:83] op_sel:[1,0,0]
	v_pk_fma_f32 v[100:101], v[216:217], v[146:147], v[100:101] op_sel:[1,0,0]
	v_pk_fma_f32 v[116:117], v[220:221], v[146:147], v[116:117] op_sel:[1,0,0]
	v_pk_fma_f32 v[68:69], v[208:209], v[148:149], v[68:69] op_sel:[1,0,0]
	v_pk_fma_f32 v[84:85], v[212:213], v[148:149], v[84:85] op_sel:[1,0,0]
	v_pk_fma_f32 v[102:103], v[216:217], v[148:149], v[102:103] op_sel:[1,0,0]
	v_pk_fma_f32 v[118:119], v[220:221], v[148:149], v[118:119] op_sel:[1,0,0]
	ds_read_b128 v[146:149], v54 offset:61440
	s_waitcnt lgkmcnt(7)
	v_pk_fma_f32 v[70:71], v[208:209], v[150:151], v[70:71] op_sel:[1,0,0]
	v_pk_fma_f32 v[86:87], v[212:213], v[150:151], v[86:87] op_sel:[1,0,0]
	v_pk_fma_f32 v[104:105], v[216:217], v[150:151], v[104:105] op_sel:[1,0,0]
	v_pk_fma_f32 v[120:121], v[220:221], v[150:151], v[120:121] op_sel:[1,0,0]
	v_pk_fma_f32 v[72:73], v[208:209], v[152:153], v[72:73] op_sel:[1,0,0]
	v_pk_fma_f32 v[88:89], v[212:213], v[152:153], v[88:89] op_sel:[1,0,0]
	v_pk_fma_f32 v[106:107], v[216:217], v[152:153], v[106:107] op_sel:[1,0,0]
	v_pk_fma_f32 v[122:123], v[220:221], v[152:153], v[122:123] op_sel:[1,0,0]
	ds_read_b128 v[150:153], v55 offset:61440
	s_waitcnt lgkmcnt(7)
	v_pk_fma_f32 v[74:75], v[208:209], v[154:155], v[74:75] op_sel:[1,0,0]
	v_pk_fma_f32 v[90:91], v[212:213], v[154:155], v[90:91] op_sel:[1,0,0]
	v_pk_fma_f32 v[108:109], v[216:217], v[154:155], v[108:109] op_sel:[1,0,0]
	v_pk_fma_f32 v[24:25], v[220:221], v[154:155], v[24:25] op_sel:[1,0,0]
	v_pk_fma_f32 v[76:77], v[208:209], v[156:157], v[76:77] op_sel:[1,0,0]
	v_pk_fma_f32 v[94:95], v[212:213], v[156:157], v[94:95] op_sel:[1,0,0]
	v_pk_fma_f32 v[110:111], v[216:217], v[156:157], v[110:111] op_sel:[1,0,0]
	v_pk_fma_f32 v[26:27], v[220:221], v[156:157], v[26:27] op_sel:[1,0,0]
	ds_read_b128 v[154:157], v56 offset:61440
	s_waitcnt lgkmcnt(7)
	v_pk_fma_f32 v[78:79], v[208:209], v[44:45], v[78:79] op_sel:[1,0,0]
	v_pk_fma_f32 v[96:97], v[212:213], v[44:45], v[96:97] op_sel:[1,0,0]
	v_pk_fma_f32 v[112:113], v[216:217], v[44:45], v[112:113] op_sel:[1,0,0]
	v_pk_fma_f32 v[28:29], v[220:221], v[44:45], v[28:29] op_sel:[1,0,0]
	v_pk_fma_f32 v[80:81], v[208:209], v[46:47], v[80:81] op_sel:[1,0,0]
	v_pk_fma_f32 v[98:99], v[212:213], v[46:47], v[98:99] op_sel:[1,0,0]
	v_pk_fma_f32 v[114:115], v[216:217], v[46:47], v[114:115] op_sel:[1,0,0]
	v_pk_fma_f32 v[30:31], v[220:221], v[46:47], v[30:31] op_sel:[1,0,0]
	ds_read_b128 v[44:47], v57 offset:61440
	s_waitcnt lgkmcnt(7)
	v_pk_fma_f32 v[66:67], v[210:211], v[130:131], v[66:67] op_sel_hi:[0,1,1]
	v_pk_fma_f32 v[82:83], v[214:215], v[130:131], v[82:83] op_sel_hi:[0,1,1]
	v_pk_fma_f32 v[100:101], v[218:219], v[130:131], v[100:101] op_sel_hi:[0,1,1]
	v_pk_fma_f32 v[116:117], v[222:223], v[130:131], v[116:117] op_sel_hi:[0,1,1]
	v_pk_fma_f32 v[68:69], v[210:211], v[132:133], v[68:69] op_sel_hi:[0,1,1]
	v_pk_fma_f32 v[84:85], v[214:215], v[132:133], v[84:85] op_sel_hi:[0,1,1]
	v_pk_fma_f32 v[102:103], v[218:219], v[132:133], v[102:103] op_sel_hi:[0,1,1]
	v_pk_fma_f32 v[118:119], v[222:223], v[132:133], v[118:119] op_sel_hi:[0,1,1]
	ds_read_b128 v[130:133], v58
	s_waitcnt lgkmcnt(7)
	v_pk_fma_f32 v[70:71], v[210:211], v[134:135], v[70:71] op_sel_hi:[0,1,1]
	v_pk_fma_f32 v[86:87], v[214:215], v[134:135], v[86:87] op_sel_hi:[0,1,1]
	v_pk_fma_f32 v[104:105], v[218:219], v[134:135], v[104:105] op_sel_hi:[0,1,1]
	v_pk_fma_f32 v[120:121], v[222:223], v[134:135], v[120:121] op_sel_hi:[0,1,1]
	v_pk_fma_f32 v[72:73], v[210:211], v[136:137], v[72:73] op_sel_hi:[0,1,1]
	v_pk_fma_f32 v[88:89], v[214:215], v[136:137], v[88:89] op_sel_hi:[0,1,1]
	v_pk_fma_f32 v[106:107], v[218:219], v[136:137], v[106:107] op_sel_hi:[0,1,1]
	v_pk_fma_f32 v[122:123], v[222:223], v[136:137], v[122:123] op_sel_hi:[0,1,1]
	ds_read_b128 v[134:137], v59
	s_waitcnt lgkmcnt(7)
	v_pk_fma_f32 v[74:75], v[210:211], v[138:139], v[74:75] op_sel_hi:[0,1,1]
	v_pk_fma_f32 v[90:91], v[214:215], v[138:139], v[90:91] op_sel_hi:[0,1,1]
	v_pk_fma_f32 v[108:109], v[218:219], v[138:139], v[108:109] op_sel_hi:[0,1,1]
	v_pk_fma_f32 v[24:25], v[222:223], v[138:139], v[24:25] op_sel_hi:[0,1,1]
	v_pk_fma_f32 v[76:77], v[210:211], v[140:141], v[76:77] op_sel_hi:[0,1,1]
	v_pk_fma_f32 v[94:95], v[214:215], v[140:141], v[94:95] op_sel_hi:[0,1,1]
	v_pk_fma_f32 v[110:111], v[218:219], v[140:141], v[110:111] op_sel_hi:[0,1,1]
	v_pk_fma_f32 v[26:27], v[222:223], v[140:141], v[26:27] op_sel_hi:[0,1,1]
	ds_read_b128 v[138:141], v60
	s_waitcnt lgkmcnt(7)
	v_pk_fma_f32 v[78:79], v[210:211], v[142:143], v[78:79] op_sel_hi:[0,1,1]
	v_pk_fma_f32 v[96:97], v[214:215], v[142:143], v[96:97] op_sel_hi:[0,1,1]
	v_pk_fma_f32 v[112:113], v[218:219], v[142:143], v[112:113] op_sel_hi:[0,1,1]
	v_pk_fma_f32 v[28:29], v[222:223], v[142:143], v[28:29] op_sel_hi:[0,1,1]
	v_pk_fma_f32 v[80:81], v[210:211], v[144:145], v[80:81] op_sel_hi:[0,1,1]
	v_pk_fma_f32 v[98:99], v[214:215], v[144:145], v[98:99] op_sel_hi:[0,1,1]
	v_pk_fma_f32 v[114:115], v[218:219], v[144:145], v[114:115] op_sel_hi:[0,1,1]
	v_pk_fma_f32 v[30:31], v[222:223], v[144:145], v[30:31] op_sel_hi:[0,1,1]
	ds_read_b128 v[142:145], v61
	s_waitcnt lgkmcnt(7)
	v_pk_fma_f32 v[66:67], v[210:211], v[146:147], v[66:67] op_sel:[1,0,0]
	v_pk_fma_f32 v[82:83], v[214:215], v[146:147], v[82:83] op_sel:[1,0,0]
	v_pk_fma_f32 v[100:101], v[218:219], v[146:147], v[100:101] op_sel:[1,0,0]
	v_pk_fma_f32 v[116:117], v[222:223], v[146:147], v[116:117] op_sel:[1,0,0]
	v_pk_fma_f32 v[68:69], v[210:211], v[148:149], v[68:69] op_sel:[1,0,0]
	v_pk_fma_f32 v[84:85], v[214:215], v[148:149], v[84:85] op_sel:[1,0,0]
	v_pk_fma_f32 v[102:103], v[218:219], v[148:149], v[102:103] op_sel:[1,0,0]
	v_pk_fma_f32 v[118:119], v[222:223], v[148:149], v[118:119] op_sel:[1,0,0]
	ds_read_b128 v[146:149], v58 offset:4096
	s_waitcnt lgkmcnt(7)
	v_pk_fma_f32 v[70:71], v[210:211], v[150:151], v[70:71] op_sel:[1,0,0]
	v_pk_fma_f32 v[86:87], v[214:215], v[150:151], v[86:87] op_sel:[1,0,0]
	v_pk_fma_f32 v[104:105], v[218:219], v[150:151], v[104:105] op_sel:[1,0,0]
	v_pk_fma_f32 v[120:121], v[222:223], v[150:151], v[120:121] op_sel:[1,0,0]
	v_pk_fma_f32 v[72:73], v[210:211], v[152:153], v[72:73] op_sel:[1,0,0]
	v_pk_fma_f32 v[88:89], v[214:215], v[152:153], v[88:89] op_sel:[1,0,0]
	v_pk_fma_f32 v[106:107], v[218:219], v[152:153], v[106:107] op_sel:[1,0,0]
	v_pk_fma_f32 v[122:123], v[222:223], v[152:153], v[122:123] op_sel:[1,0,0]
	ds_read_b128 v[150:153], v59 offset:4096
	s_waitcnt lgkmcnt(7)
	v_pk_fma_f32 v[74:75], v[210:211], v[154:155], v[74:75] op_sel:[1,0,0]
	v_pk_fma_f32 v[90:91], v[214:215], v[154:155], v[90:91] op_sel:[1,0,0]
	v_pk_fma_f32 v[108:109], v[218:219], v[154:155], v[108:109] op_sel:[1,0,0]
	v_pk_fma_f32 v[24:25], v[222:223], v[154:155], v[24:25] op_sel:[1,0,0]
	v_pk_fma_f32 v[76:77], v[210:211], v[156:157], v[76:77] op_sel:[1,0,0]
	v_pk_fma_f32 v[94:95], v[214:215], v[156:157], v[94:95] op_sel:[1,0,0]
	v_pk_fma_f32 v[110:111], v[218:219], v[156:157], v[110:111] op_sel:[1,0,0]
	v_pk_fma_f32 v[26:27], v[222:223], v[156:157], v[26:27] op_sel:[1,0,0]
	ds_read_b128 v[154:157], v60 offset:4096
	s_waitcnt lgkmcnt(7)
	v_pk_fma_f32 v[78:79], v[210:211], v[44:45], v[78:79] op_sel:[1,0,0]
	v_pk_fma_f32 v[96:97], v[214:215], v[44:45], v[96:97] op_sel:[1,0,0]
	v_pk_fma_f32 v[112:113], v[218:219], v[44:45], v[112:113] op_sel:[1,0,0]
	v_pk_fma_f32 v[28:29], v[222:223], v[44:45], v[28:29] op_sel:[1,0,0]
	v_pk_fma_f32 v[80:81], v[210:211], v[46:47], v[80:81] op_sel:[1,0,0]
	v_pk_fma_f32 v[98:99], v[214:215], v[46:47], v[98:99] op_sel:[1,0,0]
	v_pk_fma_f32 v[114:115], v[218:219], v[46:47], v[114:115] op_sel:[1,0,0]
	v_pk_fma_f32 v[30:31], v[222:223], v[46:47], v[30:31] op_sel:[1,0,0]
	ds_read_b128 v[44:47], v61 offset:4096
	s_waitcnt vmcnt(31)
	v_cvt_pk_bf16_f32 v244, v224, v225
	v_cvt_pk_bf16_f32 v245, v226, v227
	global_store_dwordx2 v[14:15], v[244:245], off offset:2048 sc0 sc1
	v_pk_mul_f32 v[22:23], v[224:225], v[224:225]
	v_pk_fma_f32 v[22:23], v[226:227], v[226:227], v[22:23]
	v_add_f32_e32 v22, v22, v23
	v_add_f32_e32 v240, v240, v22
	s_waitcnt vmcnt(31)
	v_cvt_pk_bf16_f32 v246, v228, v229
	v_cvt_pk_bf16_f32 v247, v230, v231
	global_store_dwordx2 v[16:17], v[246:247], off offset:2048 sc0 sc1
	v_pk_mul_f32 v[22:23], v[228:229], v[228:229]
	v_pk_fma_f32 v[22:23], v[230:231], v[230:231], v[22:23]
	v_add_f32_e32 v22, v22, v23
	v_add_f32_e32 v241, v241, v22
	s_waitcnt vmcnt(31)
	v_cvt_pk_bf16_f32 v248, v0, v1
	v_cvt_pk_bf16_f32 v249, v2, v3
	global_store_dwordx2 v[18:19], v[248:249], off offset:2048 sc0 sc1
	v_pk_mul_f32 v[22:23], v[0:1], v[0:1]
	v_pk_fma_f32 v[22:23], v[2:3], v[2:3], v[22:23]
	v_add_f32_e32 v22, v22, v23
	v_add_f32_e32 v242, v242, v22
	s_waitcnt vmcnt(31)
	v_cvt_pk_bf16_f32 v232, v4, v5
	v_cvt_pk_bf16_f32 v233, v6, v7
	global_store_dwordx2 v[20:21], v[232:233], off offset:2048 sc0 sc1
	v_pk_mul_f32 v[22:23], v[4:5], v[4:5]
	v_pk_fma_f32 v[22:23], v[6:7], v[6:7], v[22:23]
	v_add_f32_e32 v22, v22, v23
	v_add_f32_e32 v243, v243, v22
	s_waitcnt lgkmcnt(7)
	v_pk_fma_f32 v[66:67], v[224:225], v[130:131], v[66:67] op_sel_hi:[0,1,1]
	v_pk_fma_f32 v[82:83], v[228:229], v[130:131], v[82:83] op_sel_hi:[0,1,1]
	v_pk_fma_f32 v[100:101], v[0:1], v[130:131], v[100:101] op_sel_hi:[0,1,1]
	v_pk_fma_f32 v[116:117], v[4:5], v[130:131], v[116:117] op_sel_hi:[0,1,1]
	v_pk_fma_f32 v[68:69], v[224:225], v[132:133], v[68:69] op_sel_hi:[0,1,1]
	v_pk_fma_f32 v[84:85], v[228:229], v[132:133], v[84:85] op_sel_hi:[0,1,1]
	v_pk_fma_f32 v[102:103], v[0:1], v[132:133], v[102:103] op_sel_hi:[0,1,1]
	v_pk_fma_f32 v[118:119], v[4:5], v[132:133], v[118:119] op_sel_hi:[0,1,1]
	ds_read_b128 v[130:133], v58 offset:8192
	s_waitcnt lgkmcnt(7)
	v_pk_fma_f32 v[70:71], v[224:225], v[134:135], v[70:71] op_sel_hi:[0,1,1]
	v_pk_fma_f32 v[86:87], v[228:229], v[134:135], v[86:87] op_sel_hi:[0,1,1]
	v_pk_fma_f32 v[104:105], v[0:1], v[134:135], v[104:105] op_sel_hi:[0,1,1]
	v_pk_fma_f32 v[120:121], v[4:5], v[134:135], v[120:121] op_sel_hi:[0,1,1]
	v_pk_fma_f32 v[72:73], v[224:225], v[136:137], v[72:73] op_sel_hi:[0,1,1]
	v_pk_fma_f32 v[88:89], v[228:229], v[136:137], v[88:89] op_sel_hi:[0,1,1]
	v_pk_fma_f32 v[106:107], v[0:1], v[136:137], v[106:107] op_sel_hi:[0,1,1]
	v_pk_fma_f32 v[122:123], v[4:5], v[136:137], v[122:123] op_sel_hi:[0,1,1]
	ds_read_b128 v[134:137], v59 offset:8192
	s_waitcnt lgkmcnt(7)
	v_pk_fma_f32 v[74:75], v[224:225], v[138:139], v[74:75] op_sel_hi:[0,1,1]
	v_pk_fma_f32 v[90:91], v[228:229], v[138:139], v[90:91] op_sel_hi:[0,1,1]
	v_pk_fma_f32 v[108:109], v[0:1], v[138:139], v[108:109] op_sel_hi:[0,1,1]
	v_pk_fma_f32 v[24:25], v[4:5], v[138:139], v[24:25] op_sel_hi:[0,1,1]
	v_pk_fma_f32 v[76:77], v[224:225], v[140:141], v[76:77] op_sel_hi:[0,1,1]
	v_pk_fma_f32 v[94:95], v[228:229], v[140:141], v[94:95] op_sel_hi:[0,1,1]
	v_pk_fma_f32 v[110:111], v[0:1], v[140:141], v[110:111] op_sel_hi:[0,1,1]
	v_pk_fma_f32 v[26:27], v[4:5], v[140:141], v[26:27] op_sel_hi:[0,1,1]
	ds_read_b128 v[138:141], v60 offset:8192
	s_waitcnt lgkmcnt(7)
	v_pk_fma_f32 v[78:79], v[224:225], v[142:143], v[78:79] op_sel_hi:[0,1,1]
	v_pk_fma_f32 v[96:97], v[228:229], v[142:143], v[96:97] op_sel_hi:[0,1,1]
	v_pk_fma_f32 v[112:113], v[0:1], v[142:143], v[112:113] op_sel_hi:[0,1,1]
	v_pk_fma_f32 v[28:29], v[4:5], v[142:143], v[28:29] op_sel_hi:[0,1,1]
	v_pk_fma_f32 v[80:81], v[224:225], v[144:145], v[80:81] op_sel_hi:[0,1,1]
	v_pk_fma_f32 v[98:99], v[228:229], v[144:145], v[98:99] op_sel_hi:[0,1,1]
	v_pk_fma_f32 v[114:115], v[0:1], v[144:145], v[114:115] op_sel_hi:[0,1,1]
	v_pk_fma_f32 v[30:31], v[4:5], v[144:145], v[30:31] op_sel_hi:[0,1,1]
	ds_read_b128 v[142:145], v61 offset:8192
	s_waitcnt lgkmcnt(7)
	v_pk_fma_f32 v[66:67], v[224:225], v[146:147], v[66:67] op_sel:[1,0,0]
	v_pk_fma_f32 v[82:83], v[228:229], v[146:147], v[82:83] op_sel:[1,0,0]
	v_pk_fma_f32 v[100:101], v[0:1], v[146:147], v[100:101] op_sel:[1,0,0]
	v_pk_fma_f32 v[116:117], v[4:5], v[146:147], v[116:117] op_sel:[1,0,0]
	v_pk_fma_f32 v[68:69], v[224:225], v[148:149], v[68:69] op_sel:[1,0,0]
	v_pk_fma_f32 v[84:85], v[228:229], v[148:149], v[84:85] op_sel:[1,0,0]
	v_pk_fma_f32 v[102:103], v[0:1], v[148:149], v[102:103] op_sel:[1,0,0]
	v_pk_fma_f32 v[118:119], v[4:5], v[148:149], v[118:119] op_sel:[1,0,0]
	ds_read_b128 v[146:149], v58 offset:12288
	s_waitcnt lgkmcnt(7)
	v_pk_fma_f32 v[70:71], v[224:225], v[150:151], v[70:71] op_sel:[1,0,0]
	v_pk_fma_f32 v[86:87], v[228:229], v[150:151], v[86:87] op_sel:[1,0,0]
	v_pk_fma_f32 v[104:105], v[0:1], v[150:151], v[104:105] op_sel:[1,0,0]
	v_pk_fma_f32 v[120:121], v[4:5], v[150:151], v[120:121] op_sel:[1,0,0]
	v_pk_fma_f32 v[72:73], v[224:225], v[152:153], v[72:73] op_sel:[1,0,0]
	v_pk_fma_f32 v[88:89], v[228:229], v[152:153], v[88:89] op_sel:[1,0,0]
	v_pk_fma_f32 v[106:107], v[0:1], v[152:153], v[106:107] op_sel:[1,0,0]
	v_pk_fma_f32 v[122:123], v[4:5], v[152:153], v[122:123] op_sel:[1,0,0]
	ds_read_b128 v[150:153], v59 offset:12288
	s_waitcnt lgkmcnt(7)
	v_pk_fma_f32 v[74:75], v[224:225], v[154:155], v[74:75] op_sel:[1,0,0]
	v_pk_fma_f32 v[90:91], v[228:229], v[154:155], v[90:91] op_sel:[1,0,0]
	v_pk_fma_f32 v[108:109], v[0:1], v[154:155], v[108:109] op_sel:[1,0,0]
	v_pk_fma_f32 v[24:25], v[4:5], v[154:155], v[24:25] op_sel:[1,0,0]
	v_pk_fma_f32 v[76:77], v[224:225], v[156:157], v[76:77] op_sel:[1,0,0]
	v_pk_fma_f32 v[94:95], v[228:229], v[156:157], v[94:95] op_sel:[1,0,0]
	v_pk_fma_f32 v[110:111], v[0:1], v[156:157], v[110:111] op_sel:[1,0,0]
	v_pk_fma_f32 v[26:27], v[4:5], v[156:157], v[26:27] op_sel:[1,0,0]
	ds_read_b128 v[154:157], v60 offset:12288
	s_waitcnt lgkmcnt(7)
	v_pk_fma_f32 v[78:79], v[224:225], v[44:45], v[78:79] op_sel:[1,0,0]
	v_pk_fma_f32 v[96:97], v[228:229], v[44:45], v[96:97] op_sel:[1,0,0]
	v_pk_fma_f32 v[112:113], v[0:1], v[44:45], v[112:113] op_sel:[1,0,0]
	v_pk_fma_f32 v[28:29], v[4:5], v[44:45], v[28:29] op_sel:[1,0,0]
	v_pk_fma_f32 v[80:81], v[224:225], v[46:47], v[80:81] op_sel:[1,0,0]
	v_pk_fma_f32 v[98:99], v[228:229], v[46:47], v[98:99] op_sel:[1,0,0]
	v_pk_fma_f32 v[114:115], v[0:1], v[46:47], v[114:115] op_sel:[1,0,0]
	v_pk_fma_f32 v[30:31], v[4:5], v[46:47], v[30:31] op_sel:[1,0,0]
	ds_read_b128 v[44:47], v61 offset:12288
	s_waitcnt lgkmcnt(7)
	v_pk_fma_f32 v[66:67], v[226:227], v[130:131], v[66:67] op_sel_hi:[0,1,1]
	v_pk_fma_f32 v[82:83], v[230:231], v[130:131], v[82:83] op_sel_hi:[0,1,1]
	v_pk_fma_f32 v[100:101], v[2:3], v[130:131], v[100:101] op_sel_hi:[0,1,1]
	v_pk_fma_f32 v[116:117], v[6:7], v[130:131], v[116:117] op_sel_hi:[0,1,1]
	v_pk_fma_f32 v[68:69], v[226:227], v[132:133], v[68:69] op_sel_hi:[0,1,1]
	v_pk_fma_f32 v[84:85], v[230:231], v[132:133], v[84:85] op_sel_hi:[0,1,1]
	v_pk_fma_f32 v[102:103], v[2:3], v[132:133], v[102:103] op_sel_hi:[0,1,1]
	v_pk_fma_f32 v[118:119], v[6:7], v[132:133], v[118:119] op_sel_hi:[0,1,1]
	ds_read_b128 v[130:133], v58 offset:16384
	s_waitcnt lgkmcnt(7)
	v_pk_fma_f32 v[70:71], v[226:227], v[134:135], v[70:71] op_sel_hi:[0,1,1]
	v_pk_fma_f32 v[86:87], v[230:231], v[134:135], v[86:87] op_sel_hi:[0,1,1]
	v_pk_fma_f32 v[104:105], v[2:3], v[134:135], v[104:105] op_sel_hi:[0,1,1]
	v_pk_fma_f32 v[120:121], v[6:7], v[134:135], v[120:121] op_sel_hi:[0,1,1]
	v_pk_fma_f32 v[72:73], v[226:227], v[136:137], v[72:73] op_sel_hi:[0,1,1]
	v_pk_fma_f32 v[88:89], v[230:231], v[136:137], v[88:89] op_sel_hi:[0,1,1]
	v_pk_fma_f32 v[106:107], v[2:3], v[136:137], v[106:107] op_sel_hi:[0,1,1]
	v_pk_fma_f32 v[122:123], v[6:7], v[136:137], v[122:123] op_sel_hi:[0,1,1]
	ds_read_b128 v[134:137], v59 offset:16384
	s_waitcnt lgkmcnt(7)
	v_pk_fma_f32 v[74:75], v[226:227], v[138:139], v[74:75] op_sel_hi:[0,1,1]
	v_pk_fma_f32 v[90:91], v[230:231], v[138:139], v[90:91] op_sel_hi:[0,1,1]
	v_pk_fma_f32 v[108:109], v[2:3], v[138:139], v[108:109] op_sel_hi:[0,1,1]
	v_pk_fma_f32 v[24:25], v[6:7], v[138:139], v[24:25] op_sel_hi:[0,1,1]
	v_pk_fma_f32 v[76:77], v[226:227], v[140:141], v[76:77] op_sel_hi:[0,1,1]
	v_pk_fma_f32 v[94:95], v[230:231], v[140:141], v[94:95] op_sel_hi:[0,1,1]
	v_pk_fma_f32 v[110:111], v[2:3], v[140:141], v[110:111] op_sel_hi:[0,1,1]
	v_pk_fma_f32 v[26:27], v[6:7], v[140:141], v[26:27] op_sel_hi:[0,1,1]
	ds_read_b128 v[138:141], v60 offset:16384
	s_waitcnt lgkmcnt(7)
	v_pk_fma_f32 v[78:79], v[226:227], v[142:143], v[78:79] op_sel_hi:[0,1,1]
	v_pk_fma_f32 v[96:97], v[230:231], v[142:143], v[96:97] op_sel_hi:[0,1,1]
	v_pk_fma_f32 v[112:113], v[2:3], v[142:143], v[112:113] op_sel_hi:[0,1,1]
	v_pk_fma_f32 v[28:29], v[6:7], v[142:143], v[28:29] op_sel_hi:[0,1,1]
	v_pk_fma_f32 v[80:81], v[226:227], v[144:145], v[80:81] op_sel_hi:[0,1,1]
	v_pk_fma_f32 v[98:99], v[230:231], v[144:145], v[98:99] op_sel_hi:[0,1,1]
	v_pk_fma_f32 v[114:115], v[2:3], v[144:145], v[114:115] op_sel_hi:[0,1,1]
	v_pk_fma_f32 v[30:31], v[6:7], v[144:145], v[30:31] op_sel_hi:[0,1,1]
	ds_read_b128 v[142:145], v61 offset:16384
	s_waitcnt lgkmcnt(7)
	v_pk_fma_f32 v[66:67], v[226:227], v[146:147], v[66:67] op_sel:[1,0,0]
	v_pk_fma_f32 v[82:83], v[230:231], v[146:147], v[82:83] op_sel:[1,0,0]
	v_pk_fma_f32 v[100:101], v[2:3], v[146:147], v[100:101] op_sel:[1,0,0]
	v_pk_fma_f32 v[116:117], v[6:7], v[146:147], v[116:117] op_sel:[1,0,0]
	v_pk_fma_f32 v[68:69], v[226:227], v[148:149], v[68:69] op_sel:[1,0,0]
	v_pk_fma_f32 v[84:85], v[230:231], v[148:149], v[84:85] op_sel:[1,0,0]
	v_pk_fma_f32 v[102:103], v[2:3], v[148:149], v[102:103] op_sel:[1,0,0]
	v_pk_fma_f32 v[118:119], v[6:7], v[148:149], v[118:119] op_sel:[1,0,0]
	ds_read_b128 v[146:149], v58 offset:20480
	s_waitcnt lgkmcnt(7)
	v_pk_fma_f32 v[70:71], v[226:227], v[150:151], v[70:71] op_sel:[1,0,0]
	v_pk_fma_f32 v[86:87], v[230:231], v[150:151], v[86:87] op_sel:[1,0,0]
	v_pk_fma_f32 v[104:105], v[2:3], v[150:151], v[104:105] op_sel:[1,0,0]
	v_pk_fma_f32 v[120:121], v[6:7], v[150:151], v[120:121] op_sel:[1,0,0]
	v_pk_fma_f32 v[72:73], v[226:227], v[152:153], v[72:73] op_sel:[1,0,0]
	v_pk_fma_f32 v[88:89], v[230:231], v[152:153], v[88:89] op_sel:[1,0,0]
	v_pk_fma_f32 v[106:107], v[2:3], v[152:153], v[106:107] op_sel:[1,0,0]
	v_pk_fma_f32 v[122:123], v[6:7], v[152:153], v[122:123] op_sel:[1,0,0]
	ds_read_b128 v[150:153], v59 offset:20480
	s_waitcnt lgkmcnt(7)
	v_pk_fma_f32 v[74:75], v[226:227], v[154:155], v[74:75] op_sel:[1,0,0]
	v_pk_fma_f32 v[90:91], v[230:231], v[154:155], v[90:91] op_sel:[1,0,0]
	v_pk_fma_f32 v[108:109], v[2:3], v[154:155], v[108:109] op_sel:[1,0,0]
	v_pk_fma_f32 v[24:25], v[6:7], v[154:155], v[24:25] op_sel:[1,0,0]
	v_pk_fma_f32 v[76:77], v[226:227], v[156:157], v[76:77] op_sel:[1,0,0]
	v_pk_fma_f32 v[94:95], v[230:231], v[156:157], v[94:95] op_sel:[1,0,0]
	v_pk_fma_f32 v[110:111], v[2:3], v[156:157], v[110:111] op_sel:[1,0,0]
	v_pk_fma_f32 v[26:27], v[6:7], v[156:157], v[26:27] op_sel:[1,0,0]
	ds_read_b128 v[154:157], v60 offset:20480
	s_waitcnt lgkmcnt(7)
	v_pk_fma_f32 v[78:79], v[226:227], v[44:45], v[78:79] op_sel:[1,0,0]
	v_pk_fma_f32 v[96:97], v[230:231], v[44:45], v[96:97] op_sel:[1,0,0]
	v_pk_fma_f32 v[112:113], v[2:3], v[44:45], v[112:113] op_sel:[1,0,0]
	v_pk_fma_f32 v[28:29], v[6:7], v[44:45], v[28:29] op_sel:[1,0,0]
	v_pk_fma_f32 v[80:81], v[226:227], v[46:47], v[80:81] op_sel:[1,0,0]
	v_pk_fma_f32 v[98:99], v[230:231], v[46:47], v[98:99] op_sel:[1,0,0]
	v_pk_fma_f32 v[114:115], v[2:3], v[46:47], v[114:115] op_sel:[1,0,0]
	v_pk_fma_f32 v[30:31], v[6:7], v[46:47], v[30:31] op_sel:[1,0,0]
	ds_read_b128 v[44:47], v61 offset:20480
	s_waitcnt vmcnt(27)
	v_cvt_pk_bf16_f32 v244, v160, v161
	v_cvt_pk_bf16_f32 v245, v162, v163
	global_store_dwordx2 v[14:15], v[244:245], off offset:2560 sc0 sc1
	v_pk_mul_f32 v[22:23], v[160:161], v[160:161]
	v_pk_fma_f32 v[22:23], v[162:163], v[162:163], v[22:23]
	v_add_f32_e32 v22, v22, v23
	v_add_f32_e32 v240, v240, v22
	s_waitcnt vmcnt(27)
	v_cvt_pk_bf16_f32 v246, v164, v165
	v_cvt_pk_bf16_f32 v247, v166, v167
	global_store_dwordx2 v[16:17], v[246:247], off offset:2560 sc0 sc1
	v_pk_mul_f32 v[22:23], v[164:165], v[164:165]
	v_pk_fma_f32 v[22:23], v[166:167], v[166:167], v[22:23]
	v_add_f32_e32 v22, v22, v23
	v_add_f32_e32 v241, v241, v22
	s_waitcnt vmcnt(27)
	v_cvt_pk_bf16_f32 v248, v168, v169
	v_cvt_pk_bf16_f32 v249, v170, v171
	global_store_dwordx2 v[18:19], v[248:249], off offset:2560 sc0 sc1
	v_pk_mul_f32 v[22:23], v[168:169], v[168:169]
	v_pk_fma_f32 v[22:23], v[170:171], v[170:171], v[22:23]
	v_add_f32_e32 v22, v22, v23
	v_add_f32_e32 v242, v242, v22
	s_waitcnt vmcnt(27)
	v_cvt_pk_bf16_f32 v232, v172, v173
	v_cvt_pk_bf16_f32 v233, v174, v175
	global_store_dwordx2 v[20:21], v[232:233], off offset:2560 sc0 sc1
	v_pk_mul_f32 v[22:23], v[172:173], v[172:173]
	v_pk_fma_f32 v[22:23], v[174:175], v[174:175], v[22:23]
	v_add_f32_e32 v22, v22, v23
	v_add_f32_e32 v243, v243, v22
	s_waitcnt lgkmcnt(7)
	v_pk_fma_f32 v[66:67], v[160:161], v[130:131], v[66:67] op_sel_hi:[0,1,1]
	v_pk_fma_f32 v[82:83], v[164:165], v[130:131], v[82:83] op_sel_hi:[0,1,1]
	v_pk_fma_f32 v[100:101], v[168:169], v[130:131], v[100:101] op_sel_hi:[0,1,1]
	v_pk_fma_f32 v[116:117], v[172:173], v[130:131], v[116:117] op_sel_hi:[0,1,1]
	v_pk_fma_f32 v[68:69], v[160:161], v[132:133], v[68:69] op_sel_hi:[0,1,1]
	v_pk_fma_f32 v[84:85], v[164:165], v[132:133], v[84:85] op_sel_hi:[0,1,1]
	v_pk_fma_f32 v[102:103], v[168:169], v[132:133], v[102:103] op_sel_hi:[0,1,1]
	v_pk_fma_f32 v[118:119], v[172:173], v[132:133], v[118:119] op_sel_hi:[0,1,1]
	ds_read_b128 v[130:133], v58 offset:24576
	s_waitcnt lgkmcnt(7)
	v_pk_fma_f32 v[70:71], v[160:161], v[134:135], v[70:71] op_sel_hi:[0,1,1]
	v_pk_fma_f32 v[86:87], v[164:165], v[134:135], v[86:87] op_sel_hi:[0,1,1]
	v_pk_fma_f32 v[104:105], v[168:169], v[134:135], v[104:105] op_sel_hi:[0,1,1]
	v_pk_fma_f32 v[120:121], v[172:173], v[134:135], v[120:121] op_sel_hi:[0,1,1]
	v_pk_fma_f32 v[72:73], v[160:161], v[136:137], v[72:73] op_sel_hi:[0,1,1]
	v_pk_fma_f32 v[88:89], v[164:165], v[136:137], v[88:89] op_sel_hi:[0,1,1]
	v_pk_fma_f32 v[106:107], v[168:169], v[136:137], v[106:107] op_sel_hi:[0,1,1]
	v_pk_fma_f32 v[122:123], v[172:173], v[136:137], v[122:123] op_sel_hi:[0,1,1]
	ds_read_b128 v[134:137], v59 offset:24576
	s_waitcnt lgkmcnt(7)
	v_pk_fma_f32 v[74:75], v[160:161], v[138:139], v[74:75] op_sel_hi:[0,1,1]
	v_pk_fma_f32 v[90:91], v[164:165], v[138:139], v[90:91] op_sel_hi:[0,1,1]
	v_pk_fma_f32 v[108:109], v[168:169], v[138:139], v[108:109] op_sel_hi:[0,1,1]
	v_pk_fma_f32 v[24:25], v[172:173], v[138:139], v[24:25] op_sel_hi:[0,1,1]
	v_pk_fma_f32 v[76:77], v[160:161], v[140:141], v[76:77] op_sel_hi:[0,1,1]
	v_pk_fma_f32 v[94:95], v[164:165], v[140:141], v[94:95] op_sel_hi:[0,1,1]
	v_pk_fma_f32 v[110:111], v[168:169], v[140:141], v[110:111] op_sel_hi:[0,1,1]
	v_pk_fma_f32 v[26:27], v[172:173], v[140:141], v[26:27] op_sel_hi:[0,1,1]
	ds_read_b128 v[138:141], v60 offset:24576
	s_waitcnt lgkmcnt(7)
	v_pk_fma_f32 v[78:79], v[160:161], v[142:143], v[78:79] op_sel_hi:[0,1,1]
	v_pk_fma_f32 v[96:97], v[164:165], v[142:143], v[96:97] op_sel_hi:[0,1,1]
	v_pk_fma_f32 v[112:113], v[168:169], v[142:143], v[112:113] op_sel_hi:[0,1,1]
	v_pk_fma_f32 v[28:29], v[172:173], v[142:143], v[28:29] op_sel_hi:[0,1,1]
	v_pk_fma_f32 v[80:81], v[160:161], v[144:145], v[80:81] op_sel_hi:[0,1,1]
	v_pk_fma_f32 v[98:99], v[164:165], v[144:145], v[98:99] op_sel_hi:[0,1,1]
	v_pk_fma_f32 v[114:115], v[168:169], v[144:145], v[114:115] op_sel_hi:[0,1,1]
	v_pk_fma_f32 v[30:31], v[172:173], v[144:145], v[30:31] op_sel_hi:[0,1,1]
	ds_read_b128 v[142:145], v61 offset:24576
	s_waitcnt lgkmcnt(7)
	v_pk_fma_f32 v[66:67], v[160:161], v[146:147], v[66:67] op_sel:[1,0,0]
	v_pk_fma_f32 v[82:83], v[164:165], v[146:147], v[82:83] op_sel:[1,0,0]
	v_pk_fma_f32 v[100:101], v[168:169], v[146:147], v[100:101] op_sel:[1,0,0]
	v_pk_fma_f32 v[116:117], v[172:173], v[146:147], v[116:117] op_sel:[1,0,0]
	v_pk_fma_f32 v[68:69], v[160:161], v[148:149], v[68:69] op_sel:[1,0,0]
	v_pk_fma_f32 v[84:85], v[164:165], v[148:149], v[84:85] op_sel:[1,0,0]
	v_pk_fma_f32 v[102:103], v[168:169], v[148:149], v[102:103] op_sel:[1,0,0]
	v_pk_fma_f32 v[118:119], v[172:173], v[148:149], v[118:119] op_sel:[1,0,0]
	ds_read_b128 v[146:149], v58 offset:28672
	s_waitcnt lgkmcnt(7)
	v_pk_fma_f32 v[70:71], v[160:161], v[150:151], v[70:71] op_sel:[1,0,0]
	v_pk_fma_f32 v[86:87], v[164:165], v[150:151], v[86:87] op_sel:[1,0,0]
	v_pk_fma_f32 v[104:105], v[168:169], v[150:151], v[104:105] op_sel:[1,0,0]
	v_pk_fma_f32 v[120:121], v[172:173], v[150:151], v[120:121] op_sel:[1,0,0]
	v_pk_fma_f32 v[72:73], v[160:161], v[152:153], v[72:73] op_sel:[1,0,0]
	v_pk_fma_f32 v[88:89], v[164:165], v[152:153], v[88:89] op_sel:[1,0,0]
	v_pk_fma_f32 v[106:107], v[168:169], v[152:153], v[106:107] op_sel:[1,0,0]
	v_pk_fma_f32 v[122:123], v[172:173], v[152:153], v[122:123] op_sel:[1,0,0]
	ds_read_b128 v[150:153], v59 offset:28672
	s_waitcnt lgkmcnt(7)
	v_pk_fma_f32 v[74:75], v[160:161], v[154:155], v[74:75] op_sel:[1,0,0]
	v_pk_fma_f32 v[90:91], v[164:165], v[154:155], v[90:91] op_sel:[1,0,0]
	v_pk_fma_f32 v[108:109], v[168:169], v[154:155], v[108:109] op_sel:[1,0,0]
	v_pk_fma_f32 v[24:25], v[172:173], v[154:155], v[24:25] op_sel:[1,0,0]
	v_pk_fma_f32 v[76:77], v[160:161], v[156:157], v[76:77] op_sel:[1,0,0]
	v_pk_fma_f32 v[94:95], v[164:165], v[156:157], v[94:95] op_sel:[1,0,0]
	v_pk_fma_f32 v[110:111], v[168:169], v[156:157], v[110:111] op_sel:[1,0,0]
	v_pk_fma_f32 v[26:27], v[172:173], v[156:157], v[26:27] op_sel:[1,0,0]
	ds_read_b128 v[154:157], v60 offset:28672
	s_waitcnt lgkmcnt(7)
	v_pk_fma_f32 v[78:79], v[160:161], v[44:45], v[78:79] op_sel:[1,0,0]
	v_pk_fma_f32 v[96:97], v[164:165], v[44:45], v[96:97] op_sel:[1,0,0]
	v_pk_fma_f32 v[112:113], v[168:169], v[44:45], v[112:113] op_sel:[1,0,0]
	v_pk_fma_f32 v[28:29], v[172:173], v[44:45], v[28:29] op_sel:[1,0,0]
	v_pk_fma_f32 v[80:81], v[160:161], v[46:47], v[80:81] op_sel:[1,0,0]
	v_pk_fma_f32 v[98:99], v[164:165], v[46:47], v[98:99] op_sel:[1,0,0]
	v_pk_fma_f32 v[114:115], v[168:169], v[46:47], v[114:115] op_sel:[1,0,0]
	v_pk_fma_f32 v[30:31], v[172:173], v[46:47], v[30:31] op_sel:[1,0,0]
	ds_read_b128 v[44:47], v61 offset:28672
	s_waitcnt lgkmcnt(7)
	v_pk_fma_f32 v[66:67], v[162:163], v[130:131], v[66:67] op_sel_hi:[0,1,1]
	v_pk_fma_f32 v[82:83], v[166:167], v[130:131], v[82:83] op_sel_hi:[0,1,1]
	v_pk_fma_f32 v[100:101], v[170:171], v[130:131], v[100:101] op_sel_hi:[0,1,1]
	v_pk_fma_f32 v[116:117], v[174:175], v[130:131], v[116:117] op_sel_hi:[0,1,1]
	v_pk_fma_f32 v[68:69], v[162:163], v[132:133], v[68:69] op_sel_hi:[0,1,1]
	v_pk_fma_f32 v[84:85], v[166:167], v[132:133], v[84:85] op_sel_hi:[0,1,1]
	v_pk_fma_f32 v[102:103], v[170:171], v[132:133], v[102:103] op_sel_hi:[0,1,1]
	v_pk_fma_f32 v[118:119], v[174:175], v[132:133], v[118:119] op_sel_hi:[0,1,1]
	ds_read_b128 v[130:133], v58 offset:32768
	s_waitcnt lgkmcnt(7)
	v_pk_fma_f32 v[70:71], v[162:163], v[134:135], v[70:71] op_sel_hi:[0,1,1]
	v_pk_fma_f32 v[86:87], v[166:167], v[134:135], v[86:87] op_sel_hi:[0,1,1]
	v_pk_fma_f32 v[104:105], v[170:171], v[134:135], v[104:105] op_sel_hi:[0,1,1]
	v_pk_fma_f32 v[120:121], v[174:175], v[134:135], v[120:121] op_sel_hi:[0,1,1]
	v_pk_fma_f32 v[72:73], v[162:163], v[136:137], v[72:73] op_sel_hi:[0,1,1]
	v_pk_fma_f32 v[88:89], v[166:167], v[136:137], v[88:89] op_sel_hi:[0,1,1]
	v_pk_fma_f32 v[106:107], v[170:171], v[136:137], v[106:107] op_sel_hi:[0,1,1]
	v_pk_fma_f32 v[122:123], v[174:175], v[136:137], v[122:123] op_sel_hi:[0,1,1]
	ds_read_b128 v[134:137], v59 offset:32768
	s_waitcnt lgkmcnt(7)
	v_pk_fma_f32 v[74:75], v[162:163], v[138:139], v[74:75] op_sel_hi:[0,1,1]
	v_pk_fma_f32 v[90:91], v[166:167], v[138:139], v[90:91] op_sel_hi:[0,1,1]
	v_pk_fma_f32 v[108:109], v[170:171], v[138:139], v[108:109] op_sel_hi:[0,1,1]
	v_pk_fma_f32 v[24:25], v[174:175], v[138:139], v[24:25] op_sel_hi:[0,1,1]
	v_pk_fma_f32 v[76:77], v[162:163], v[140:141], v[76:77] op_sel_hi:[0,1,1]
	v_pk_fma_f32 v[94:95], v[166:167], v[140:141], v[94:95] op_sel_hi:[0,1,1]
	v_pk_fma_f32 v[110:111], v[170:171], v[140:141], v[110:111] op_sel_hi:[0,1,1]
	v_pk_fma_f32 v[26:27], v[174:175], v[140:141], v[26:27] op_sel_hi:[0,1,1]
	ds_read_b128 v[138:141], v60 offset:32768
	s_waitcnt lgkmcnt(7)
	v_pk_fma_f32 v[78:79], v[162:163], v[142:143], v[78:79] op_sel_hi:[0,1,1]
	v_pk_fma_f32 v[96:97], v[166:167], v[142:143], v[96:97] op_sel_hi:[0,1,1]
	v_pk_fma_f32 v[112:113], v[170:171], v[142:143], v[112:113] op_sel_hi:[0,1,1]
	v_pk_fma_f32 v[28:29], v[174:175], v[142:143], v[28:29] op_sel_hi:[0,1,1]
	v_pk_fma_f32 v[80:81], v[162:163], v[144:145], v[80:81] op_sel_hi:[0,1,1]
	v_pk_fma_f32 v[98:99], v[166:167], v[144:145], v[98:99] op_sel_hi:[0,1,1]
	v_pk_fma_f32 v[114:115], v[170:171], v[144:145], v[114:115] op_sel_hi:[0,1,1]
	v_pk_fma_f32 v[30:31], v[174:175], v[144:145], v[30:31] op_sel_hi:[0,1,1]
	ds_read_b128 v[142:145], v61 offset:32768
	s_waitcnt lgkmcnt(7)
	v_pk_fma_f32 v[66:67], v[162:163], v[146:147], v[66:67] op_sel:[1,0,0]
	v_pk_fma_f32 v[82:83], v[166:167], v[146:147], v[82:83] op_sel:[1,0,0]
	v_pk_fma_f32 v[100:101], v[170:171], v[146:147], v[100:101] op_sel:[1,0,0]
	v_pk_fma_f32 v[116:117], v[174:175], v[146:147], v[116:117] op_sel:[1,0,0]
	v_pk_fma_f32 v[68:69], v[162:163], v[148:149], v[68:69] op_sel:[1,0,0]
	v_pk_fma_f32 v[84:85], v[166:167], v[148:149], v[84:85] op_sel:[1,0,0]
	v_pk_fma_f32 v[102:103], v[170:171], v[148:149], v[102:103] op_sel:[1,0,0]
	v_pk_fma_f32 v[118:119], v[174:175], v[148:149], v[118:119] op_sel:[1,0,0]
	ds_read_b128 v[146:149], v58 offset:36864
	s_waitcnt lgkmcnt(7)
	v_pk_fma_f32 v[70:71], v[162:163], v[150:151], v[70:71] op_sel:[1,0,0]
	v_pk_fma_f32 v[86:87], v[166:167], v[150:151], v[86:87] op_sel:[1,0,0]
	v_pk_fma_f32 v[104:105], v[170:171], v[150:151], v[104:105] op_sel:[1,0,0]
	v_pk_fma_f32 v[120:121], v[174:175], v[150:151], v[120:121] op_sel:[1,0,0]
	v_pk_fma_f32 v[72:73], v[162:163], v[152:153], v[72:73] op_sel:[1,0,0]
	v_pk_fma_f32 v[88:89], v[166:167], v[152:153], v[88:89] op_sel:[1,0,0]
	v_pk_fma_f32 v[106:107], v[170:171], v[152:153], v[106:107] op_sel:[1,0,0]
	v_pk_fma_f32 v[122:123], v[174:175], v[152:153], v[122:123] op_sel:[1,0,0]
	ds_read_b128 v[150:153], v59 offset:36864
	s_waitcnt lgkmcnt(7)
	v_pk_fma_f32 v[74:75], v[162:163], v[154:155], v[74:75] op_sel:[1,0,0]
	v_pk_fma_f32 v[90:91], v[166:167], v[154:155], v[90:91] op_sel:[1,0,0]
	v_pk_fma_f32 v[108:109], v[170:171], v[154:155], v[108:109] op_sel:[1,0,0]
	v_pk_fma_f32 v[24:25], v[174:175], v[154:155], v[24:25] op_sel:[1,0,0]
	v_pk_fma_f32 v[76:77], v[162:163], v[156:157], v[76:77] op_sel:[1,0,0]
	v_pk_fma_f32 v[94:95], v[166:167], v[156:157], v[94:95] op_sel:[1,0,0]
	v_pk_fma_f32 v[110:111], v[170:171], v[156:157], v[110:111] op_sel:[1,0,0]
	v_pk_fma_f32 v[26:27], v[174:175], v[156:157], v[26:27] op_sel:[1,0,0]
	ds_read_b128 v[154:157], v60 offset:36864
	s_waitcnt lgkmcnt(7)
	v_pk_fma_f32 v[78:79], v[162:163], v[44:45], v[78:79] op_sel:[1,0,0]
	v_pk_fma_f32 v[96:97], v[166:167], v[44:45], v[96:97] op_sel:[1,0,0]
	v_pk_fma_f32 v[112:113], v[170:171], v[44:45], v[112:113] op_sel:[1,0,0]
	v_pk_fma_f32 v[28:29], v[174:175], v[44:45], v[28:29] op_sel:[1,0,0]
	v_pk_fma_f32 v[80:81], v[162:163], v[46:47], v[80:81] op_sel:[1,0,0]
	v_pk_fma_f32 v[98:99], v[166:167], v[46:47], v[98:99] op_sel:[1,0,0]
	v_pk_fma_f32 v[114:115], v[170:171], v[46:47], v[114:115] op_sel:[1,0,0]
	v_pk_fma_f32 v[30:31], v[174:175], v[46:47], v[30:31] op_sel:[1,0,0]
	ds_read_b128 v[44:47], v61 offset:36864
	s_waitcnt vmcnt(23)
	v_cvt_pk_bf16_f32 v244, v176, v177
	v_cvt_pk_bf16_f32 v245, v178, v179
	global_store_dwordx2 v[14:15], v[244:245], off offset:3072 sc0 sc1
	v_pk_mul_f32 v[22:23], v[176:177], v[176:177]
	v_pk_fma_f32 v[22:23], v[178:179], v[178:179], v[22:23]
	v_add_f32_e32 v22, v22, v23
	v_add_f32_e32 v240, v240, v22
	s_waitcnt vmcnt(23)
	v_cvt_pk_bf16_f32 v246, v180, v181
	v_cvt_pk_bf16_f32 v247, v182, v183
	global_store_dwordx2 v[16:17], v[246:247], off offset:3072 sc0 sc1
	v_pk_mul_f32 v[22:23], v[180:181], v[180:181]
	v_pk_fma_f32 v[22:23], v[182:183], v[182:183], v[22:23]
	v_add_f32_e32 v22, v22, v23
	v_add_f32_e32 v241, v241, v22
	s_waitcnt vmcnt(23)
	v_cvt_pk_bf16_f32 v248, v184, v185
	v_cvt_pk_bf16_f32 v249, v186, v187
	global_store_dwordx2 v[18:19], v[248:249], off offset:3072 sc0 sc1
	v_pk_mul_f32 v[22:23], v[184:185], v[184:185]
	v_pk_fma_f32 v[22:23], v[186:187], v[186:187], v[22:23]
	v_add_f32_e32 v22, v22, v23
	v_add_f32_e32 v242, v242, v22
	s_waitcnt vmcnt(23)
	v_cvt_pk_bf16_f32 v232, v188, v189
	v_cvt_pk_bf16_f32 v233, v190, v191
	global_store_dwordx2 v[20:21], v[232:233], off offset:3072 sc0 sc1
	v_pk_mul_f32 v[22:23], v[188:189], v[188:189]
	v_pk_fma_f32 v[22:23], v[190:191], v[190:191], v[22:23]
	v_add_f32_e32 v22, v22, v23
	v_add_f32_e32 v243, v243, v22
	s_waitcnt lgkmcnt(7)
	v_pk_fma_f32 v[66:67], v[176:177], v[130:131], v[66:67] op_sel_hi:[0,1,1]
	v_pk_fma_f32 v[82:83], v[180:181], v[130:131], v[82:83] op_sel_hi:[0,1,1]
	v_pk_fma_f32 v[100:101], v[184:185], v[130:131], v[100:101] op_sel_hi:[0,1,1]
	v_pk_fma_f32 v[116:117], v[188:189], v[130:131], v[116:117] op_sel_hi:[0,1,1]
	v_pk_fma_f32 v[68:69], v[176:177], v[132:133], v[68:69] op_sel_hi:[0,1,1]
	v_pk_fma_f32 v[84:85], v[180:181], v[132:133], v[84:85] op_sel_hi:[0,1,1]
	v_pk_fma_f32 v[102:103], v[184:185], v[132:133], v[102:103] op_sel_hi:[0,1,1]
	v_pk_fma_f32 v[118:119], v[188:189], v[132:133], v[118:119] op_sel_hi:[0,1,1]
	ds_read_b128 v[130:133], v58 offset:40960
	s_waitcnt lgkmcnt(7)
	v_pk_fma_f32 v[70:71], v[176:177], v[134:135], v[70:71] op_sel_hi:[0,1,1]
	v_pk_fma_f32 v[86:87], v[180:181], v[134:135], v[86:87] op_sel_hi:[0,1,1]
	v_pk_fma_f32 v[104:105], v[184:185], v[134:135], v[104:105] op_sel_hi:[0,1,1]
	v_pk_fma_f32 v[120:121], v[188:189], v[134:135], v[120:121] op_sel_hi:[0,1,1]
	v_pk_fma_f32 v[72:73], v[176:177], v[136:137], v[72:73] op_sel_hi:[0,1,1]
	v_pk_fma_f32 v[88:89], v[180:181], v[136:137], v[88:89] op_sel_hi:[0,1,1]
	v_pk_fma_f32 v[106:107], v[184:185], v[136:137], v[106:107] op_sel_hi:[0,1,1]
	v_pk_fma_f32 v[122:123], v[188:189], v[136:137], v[122:123] op_sel_hi:[0,1,1]
	ds_read_b128 v[134:137], v59 offset:40960
	s_waitcnt lgkmcnt(7)
	v_pk_fma_f32 v[74:75], v[176:177], v[138:139], v[74:75] op_sel_hi:[0,1,1]
	v_pk_fma_f32 v[90:91], v[180:181], v[138:139], v[90:91] op_sel_hi:[0,1,1]
	v_pk_fma_f32 v[108:109], v[184:185], v[138:139], v[108:109] op_sel_hi:[0,1,1]
	v_pk_fma_f32 v[24:25], v[188:189], v[138:139], v[24:25] op_sel_hi:[0,1,1]
	v_pk_fma_f32 v[76:77], v[176:177], v[140:141], v[76:77] op_sel_hi:[0,1,1]
	v_pk_fma_f32 v[94:95], v[180:181], v[140:141], v[94:95] op_sel_hi:[0,1,1]
	v_pk_fma_f32 v[110:111], v[184:185], v[140:141], v[110:111] op_sel_hi:[0,1,1]
	v_pk_fma_f32 v[26:27], v[188:189], v[140:141], v[26:27] op_sel_hi:[0,1,1]
	ds_read_b128 v[138:141], v60 offset:40960
	s_waitcnt lgkmcnt(7)
	v_pk_fma_f32 v[78:79], v[176:177], v[142:143], v[78:79] op_sel_hi:[0,1,1]
	v_pk_fma_f32 v[96:97], v[180:181], v[142:143], v[96:97] op_sel_hi:[0,1,1]
	v_pk_fma_f32 v[112:113], v[184:185], v[142:143], v[112:113] op_sel_hi:[0,1,1]
	v_pk_fma_f32 v[28:29], v[188:189], v[142:143], v[28:29] op_sel_hi:[0,1,1]
	v_pk_fma_f32 v[80:81], v[176:177], v[144:145], v[80:81] op_sel_hi:[0,1,1]
	v_pk_fma_f32 v[98:99], v[180:181], v[144:145], v[98:99] op_sel_hi:[0,1,1]
	v_pk_fma_f32 v[114:115], v[184:185], v[144:145], v[114:115] op_sel_hi:[0,1,1]
	v_pk_fma_f32 v[30:31], v[188:189], v[144:145], v[30:31] op_sel_hi:[0,1,1]
	ds_read_b128 v[142:145], v61 offset:40960
	s_waitcnt lgkmcnt(7)
	v_pk_fma_f32 v[66:67], v[176:177], v[146:147], v[66:67] op_sel:[1,0,0]
	v_pk_fma_f32 v[82:83], v[180:181], v[146:147], v[82:83] op_sel:[1,0,0]
	v_pk_fma_f32 v[100:101], v[184:185], v[146:147], v[100:101] op_sel:[1,0,0]
	v_pk_fma_f32 v[116:117], v[188:189], v[146:147], v[116:117] op_sel:[1,0,0]
	v_pk_fma_f32 v[68:69], v[176:177], v[148:149], v[68:69] op_sel:[1,0,0]
	v_pk_fma_f32 v[84:85], v[180:181], v[148:149], v[84:85] op_sel:[1,0,0]
	v_pk_fma_f32 v[102:103], v[184:185], v[148:149], v[102:103] op_sel:[1,0,0]
	v_pk_fma_f32 v[118:119], v[188:189], v[148:149], v[118:119] op_sel:[1,0,0]
	ds_read_b128 v[146:149], v58 offset:45056
	s_waitcnt lgkmcnt(7)
	v_pk_fma_f32 v[70:71], v[176:177], v[150:151], v[70:71] op_sel:[1,0,0]
	v_pk_fma_f32 v[86:87], v[180:181], v[150:151], v[86:87] op_sel:[1,0,0]
	v_pk_fma_f32 v[104:105], v[184:185], v[150:151], v[104:105] op_sel:[1,0,0]
	v_pk_fma_f32 v[120:121], v[188:189], v[150:151], v[120:121] op_sel:[1,0,0]
	v_pk_fma_f32 v[72:73], v[176:177], v[152:153], v[72:73] op_sel:[1,0,0]
	v_pk_fma_f32 v[88:89], v[180:181], v[152:153], v[88:89] op_sel:[1,0,0]
	v_pk_fma_f32 v[106:107], v[184:185], v[152:153], v[106:107] op_sel:[1,0,0]
	v_pk_fma_f32 v[122:123], v[188:189], v[152:153], v[122:123] op_sel:[1,0,0]
	ds_read_b128 v[150:153], v59 offset:45056
	s_waitcnt lgkmcnt(7)
	v_pk_fma_f32 v[74:75], v[176:177], v[154:155], v[74:75] op_sel:[1,0,0]
	v_pk_fma_f32 v[90:91], v[180:181], v[154:155], v[90:91] op_sel:[1,0,0]
	v_pk_fma_f32 v[108:109], v[184:185], v[154:155], v[108:109] op_sel:[1,0,0]
	v_pk_fma_f32 v[24:25], v[188:189], v[154:155], v[24:25] op_sel:[1,0,0]
	v_pk_fma_f32 v[76:77], v[176:177], v[156:157], v[76:77] op_sel:[1,0,0]
	v_pk_fma_f32 v[94:95], v[180:181], v[156:157], v[94:95] op_sel:[1,0,0]
	v_pk_fma_f32 v[110:111], v[184:185], v[156:157], v[110:111] op_sel:[1,0,0]
	v_pk_fma_f32 v[26:27], v[188:189], v[156:157], v[26:27] op_sel:[1,0,0]
	ds_read_b128 v[154:157], v60 offset:45056
	s_waitcnt lgkmcnt(7)
	v_pk_fma_f32 v[78:79], v[176:177], v[44:45], v[78:79] op_sel:[1,0,0]
	v_pk_fma_f32 v[96:97], v[180:181], v[44:45], v[96:97] op_sel:[1,0,0]
	v_pk_fma_f32 v[112:113], v[184:185], v[44:45], v[112:113] op_sel:[1,0,0]
	v_pk_fma_f32 v[28:29], v[188:189], v[44:45], v[28:29] op_sel:[1,0,0]
	v_pk_fma_f32 v[80:81], v[176:177], v[46:47], v[80:81] op_sel:[1,0,0]
	v_pk_fma_f32 v[98:99], v[180:181], v[46:47], v[98:99] op_sel:[1,0,0]
	v_pk_fma_f32 v[114:115], v[184:185], v[46:47], v[114:115] op_sel:[1,0,0]
	v_pk_fma_f32 v[30:31], v[188:189], v[46:47], v[30:31] op_sel:[1,0,0]
	ds_read_b128 v[44:47], v61 offset:45056
	s_waitcnt lgkmcnt(7)
	v_pk_fma_f32 v[66:67], v[178:179], v[130:131], v[66:67] op_sel_hi:[0,1,1]
	v_pk_fma_f32 v[82:83], v[182:183], v[130:131], v[82:83] op_sel_hi:[0,1,1]
	v_pk_fma_f32 v[100:101], v[186:187], v[130:131], v[100:101] op_sel_hi:[0,1,1]
	v_pk_fma_f32 v[116:117], v[190:191], v[130:131], v[116:117] op_sel_hi:[0,1,1]
	v_pk_fma_f32 v[68:69], v[178:179], v[132:133], v[68:69] op_sel_hi:[0,1,1]
	v_pk_fma_f32 v[84:85], v[182:183], v[132:133], v[84:85] op_sel_hi:[0,1,1]
	v_pk_fma_f32 v[102:103], v[186:187], v[132:133], v[102:103] op_sel_hi:[0,1,1]
	v_pk_fma_f32 v[118:119], v[190:191], v[132:133], v[118:119] op_sel_hi:[0,1,1]
	ds_read_b128 v[130:133], v58 offset:49152
	s_waitcnt lgkmcnt(7)
	v_pk_fma_f32 v[70:71], v[178:179], v[134:135], v[70:71] op_sel_hi:[0,1,1]
	v_pk_fma_f32 v[86:87], v[182:183], v[134:135], v[86:87] op_sel_hi:[0,1,1]
	v_pk_fma_f32 v[104:105], v[186:187], v[134:135], v[104:105] op_sel_hi:[0,1,1]
	v_pk_fma_f32 v[120:121], v[190:191], v[134:135], v[120:121] op_sel_hi:[0,1,1]
	v_pk_fma_f32 v[72:73], v[178:179], v[136:137], v[72:73] op_sel_hi:[0,1,1]
	v_pk_fma_f32 v[88:89], v[182:183], v[136:137], v[88:89] op_sel_hi:[0,1,1]
	v_pk_fma_f32 v[106:107], v[186:187], v[136:137], v[106:107] op_sel_hi:[0,1,1]
	v_pk_fma_f32 v[122:123], v[190:191], v[136:137], v[122:123] op_sel_hi:[0,1,1]
	ds_read_b128 v[134:137], v59 offset:49152
	s_waitcnt lgkmcnt(7)
	v_pk_fma_f32 v[74:75], v[178:179], v[138:139], v[74:75] op_sel_hi:[0,1,1]
	v_pk_fma_f32 v[90:91], v[182:183], v[138:139], v[90:91] op_sel_hi:[0,1,1]
	v_pk_fma_f32 v[108:109], v[186:187], v[138:139], v[108:109] op_sel_hi:[0,1,1]
	v_pk_fma_f32 v[24:25], v[190:191], v[138:139], v[24:25] op_sel_hi:[0,1,1]
	v_pk_fma_f32 v[76:77], v[178:179], v[140:141], v[76:77] op_sel_hi:[0,1,1]
	v_pk_fma_f32 v[94:95], v[182:183], v[140:141], v[94:95] op_sel_hi:[0,1,1]
	v_pk_fma_f32 v[110:111], v[186:187], v[140:141], v[110:111] op_sel_hi:[0,1,1]
	v_pk_fma_f32 v[26:27], v[190:191], v[140:141], v[26:27] op_sel_hi:[0,1,1]
	ds_read_b128 v[138:141], v60 offset:49152
	s_waitcnt lgkmcnt(7)
	v_pk_fma_f32 v[78:79], v[178:179], v[142:143], v[78:79] op_sel_hi:[0,1,1]
	v_pk_fma_f32 v[96:97], v[182:183], v[142:143], v[96:97] op_sel_hi:[0,1,1]
	v_pk_fma_f32 v[112:113], v[186:187], v[142:143], v[112:113] op_sel_hi:[0,1,1]
	v_pk_fma_f32 v[28:29], v[190:191], v[142:143], v[28:29] op_sel_hi:[0,1,1]
	v_pk_fma_f32 v[80:81], v[178:179], v[144:145], v[80:81] op_sel_hi:[0,1,1]
	v_pk_fma_f32 v[98:99], v[182:183], v[144:145], v[98:99] op_sel_hi:[0,1,1]
	v_pk_fma_f32 v[114:115], v[186:187], v[144:145], v[114:115] op_sel_hi:[0,1,1]
	v_pk_fma_f32 v[30:31], v[190:191], v[144:145], v[30:31] op_sel_hi:[0,1,1]
	ds_read_b128 v[142:145], v61 offset:49152
	s_waitcnt lgkmcnt(7)
	v_pk_fma_f32 v[66:67], v[178:179], v[146:147], v[66:67] op_sel:[1,0,0]
	v_pk_fma_f32 v[82:83], v[182:183], v[146:147], v[82:83] op_sel:[1,0,0]
	v_pk_fma_f32 v[100:101], v[186:187], v[146:147], v[100:101] op_sel:[1,0,0]
	v_pk_fma_f32 v[116:117], v[190:191], v[146:147], v[116:117] op_sel:[1,0,0]
	v_pk_fma_f32 v[68:69], v[178:179], v[148:149], v[68:69] op_sel:[1,0,0]
	v_pk_fma_f32 v[84:85], v[182:183], v[148:149], v[84:85] op_sel:[1,0,0]
	v_pk_fma_f32 v[102:103], v[186:187], v[148:149], v[102:103] op_sel:[1,0,0]
	v_pk_fma_f32 v[118:119], v[190:191], v[148:149], v[118:119] op_sel:[1,0,0]
	ds_read_b128 v[146:149], v58 offset:53248
	s_waitcnt lgkmcnt(7)
	v_pk_fma_f32 v[70:71], v[178:179], v[150:151], v[70:71] op_sel:[1,0,0]
	v_pk_fma_f32 v[86:87], v[182:183], v[150:151], v[86:87] op_sel:[1,0,0]
	v_pk_fma_f32 v[104:105], v[186:187], v[150:151], v[104:105] op_sel:[1,0,0]
	v_pk_fma_f32 v[120:121], v[190:191], v[150:151], v[120:121] op_sel:[1,0,0]
	v_pk_fma_f32 v[72:73], v[178:179], v[152:153], v[72:73] op_sel:[1,0,0]
	v_pk_fma_f32 v[88:89], v[182:183], v[152:153], v[88:89] op_sel:[1,0,0]
	v_pk_fma_f32 v[106:107], v[186:187], v[152:153], v[106:107] op_sel:[1,0,0]
	v_pk_fma_f32 v[122:123], v[190:191], v[152:153], v[122:123] op_sel:[1,0,0]
	ds_read_b128 v[150:153], v59 offset:53248
	s_waitcnt lgkmcnt(7)
	v_pk_fma_f32 v[74:75], v[178:179], v[154:155], v[74:75] op_sel:[1,0,0]
	v_pk_fma_f32 v[90:91], v[182:183], v[154:155], v[90:91] op_sel:[1,0,0]
	v_pk_fma_f32 v[108:109], v[186:187], v[154:155], v[108:109] op_sel:[1,0,0]
	v_pk_fma_f32 v[24:25], v[190:191], v[154:155], v[24:25] op_sel:[1,0,0]
	v_pk_fma_f32 v[76:77], v[178:179], v[156:157], v[76:77] op_sel:[1,0,0]
	v_pk_fma_f32 v[94:95], v[182:183], v[156:157], v[94:95] op_sel:[1,0,0]
	v_pk_fma_f32 v[110:111], v[186:187], v[156:157], v[110:111] op_sel:[1,0,0]
	v_pk_fma_f32 v[26:27], v[190:191], v[156:157], v[26:27] op_sel:[1,0,0]
	ds_read_b128 v[154:157], v60 offset:53248
	s_waitcnt lgkmcnt(7)
	v_pk_fma_f32 v[78:79], v[178:179], v[44:45], v[78:79] op_sel:[1,0,0]
	v_pk_fma_f32 v[96:97], v[182:183], v[44:45], v[96:97] op_sel:[1,0,0]
	v_pk_fma_f32 v[112:113], v[186:187], v[44:45], v[112:113] op_sel:[1,0,0]
	v_pk_fma_f32 v[28:29], v[190:191], v[44:45], v[28:29] op_sel:[1,0,0]
	v_pk_fma_f32 v[80:81], v[178:179], v[46:47], v[80:81] op_sel:[1,0,0]
	v_pk_fma_f32 v[98:99], v[182:183], v[46:47], v[98:99] op_sel:[1,0,0]
	v_pk_fma_f32 v[114:115], v[186:187], v[46:47], v[114:115] op_sel:[1,0,0]
	v_pk_fma_f32 v[30:31], v[190:191], v[46:47], v[30:31] op_sel:[1,0,0]
	ds_read_b128 v[44:47], v61 offset:53248
	s_waitcnt vmcnt(19)
	v_cvt_pk_bf16_f32 v244, v192, v193
	v_cvt_pk_bf16_f32 v245, v194, v195
	global_store_dwordx2 v[14:15], v[244:245], off offset:3584 sc0 sc1
	v_pk_mul_f32 v[22:23], v[192:193], v[192:193]
	v_pk_fma_f32 v[22:23], v[194:195], v[194:195], v[22:23]
	v_add_f32_e32 v22, v22, v23
	v_add_f32_e32 v240, v240, v22
	s_waitcnt vmcnt(19)
	v_cvt_pk_bf16_f32 v246, v196, v197
	v_cvt_pk_bf16_f32 v247, v198, v199
	global_store_dwordx2 v[16:17], v[246:247], off offset:3584 sc0 sc1
	v_pk_mul_f32 v[22:23], v[196:197], v[196:197]
	v_pk_fma_f32 v[22:23], v[198:199], v[198:199], v[22:23]
	v_add_f32_e32 v22, v22, v23
	v_add_f32_e32 v241, v241, v22
	s_waitcnt vmcnt(19)
	v_cvt_pk_bf16_f32 v248, v200, v201
	v_cvt_pk_bf16_f32 v249, v202, v203
	global_store_dwordx2 v[18:19], v[248:249], off offset:3584 sc0 sc1
	v_pk_mul_f32 v[22:23], v[200:201], v[200:201]
	v_pk_fma_f32 v[22:23], v[202:203], v[202:203], v[22:23]
	v_add_f32_e32 v22, v22, v23
	v_add_f32_e32 v242, v242, v22
	s_waitcnt vmcnt(19)
	v_cvt_pk_bf16_f32 v232, v204, v205
	v_cvt_pk_bf16_f32 v233, v206, v207
	global_store_dwordx2 v[20:21], v[232:233], off offset:3584 sc0 sc1
	v_pk_mul_f32 v[22:23], v[204:205], v[204:205]
	v_pk_fma_f32 v[22:23], v[206:207], v[206:207], v[22:23]
	v_add_f32_e32 v22, v22, v23
	v_add_f32_e32 v243, v243, v22
	s_waitcnt lgkmcnt(7)
	v_pk_fma_f32 v[66:67], v[192:193], v[130:131], v[66:67] op_sel_hi:[0,1,1]
	v_pk_fma_f32 v[82:83], v[196:197], v[130:131], v[82:83] op_sel_hi:[0,1,1]
	v_pk_fma_f32 v[100:101], v[200:201], v[130:131], v[100:101] op_sel_hi:[0,1,1]
	v_pk_fma_f32 v[116:117], v[204:205], v[130:131], v[116:117] op_sel_hi:[0,1,1]
	v_pk_fma_f32 v[68:69], v[192:193], v[132:133], v[68:69] op_sel_hi:[0,1,1]
	v_pk_fma_f32 v[84:85], v[196:197], v[132:133], v[84:85] op_sel_hi:[0,1,1]
	v_pk_fma_f32 v[102:103], v[200:201], v[132:133], v[102:103] op_sel_hi:[0,1,1]
	v_pk_fma_f32 v[118:119], v[204:205], v[132:133], v[118:119] op_sel_hi:[0,1,1]
	ds_read_b128 v[130:133], v58 offset:57344
	s_waitcnt lgkmcnt(7)
	v_pk_fma_f32 v[70:71], v[192:193], v[134:135], v[70:71] op_sel_hi:[0,1,1]
	v_pk_fma_f32 v[86:87], v[196:197], v[134:135], v[86:87] op_sel_hi:[0,1,1]
	v_pk_fma_f32 v[104:105], v[200:201], v[134:135], v[104:105] op_sel_hi:[0,1,1]
	v_pk_fma_f32 v[120:121], v[204:205], v[134:135], v[120:121] op_sel_hi:[0,1,1]
	v_pk_fma_f32 v[72:73], v[192:193], v[136:137], v[72:73] op_sel_hi:[0,1,1]
	v_pk_fma_f32 v[88:89], v[196:197], v[136:137], v[88:89] op_sel_hi:[0,1,1]
	v_pk_fma_f32 v[106:107], v[200:201], v[136:137], v[106:107] op_sel_hi:[0,1,1]
	v_pk_fma_f32 v[122:123], v[204:205], v[136:137], v[122:123] op_sel_hi:[0,1,1]
	ds_read_b128 v[134:137], v59 offset:57344
	s_waitcnt lgkmcnt(7)
	v_pk_fma_f32 v[74:75], v[192:193], v[138:139], v[74:75] op_sel_hi:[0,1,1]
	v_pk_fma_f32 v[90:91], v[196:197], v[138:139], v[90:91] op_sel_hi:[0,1,1]
	v_pk_fma_f32 v[108:109], v[200:201], v[138:139], v[108:109] op_sel_hi:[0,1,1]
	v_pk_fma_f32 v[24:25], v[204:205], v[138:139], v[24:25] op_sel_hi:[0,1,1]
	v_pk_fma_f32 v[76:77], v[192:193], v[140:141], v[76:77] op_sel_hi:[0,1,1]
	v_pk_fma_f32 v[94:95], v[196:197], v[140:141], v[94:95] op_sel_hi:[0,1,1]
	v_pk_fma_f32 v[110:111], v[200:201], v[140:141], v[110:111] op_sel_hi:[0,1,1]
	v_pk_fma_f32 v[26:27], v[204:205], v[140:141], v[26:27] op_sel_hi:[0,1,1]
	ds_read_b128 v[138:141], v60 offset:57344
	s_waitcnt lgkmcnt(7)
	v_pk_fma_f32 v[78:79], v[192:193], v[142:143], v[78:79] op_sel_hi:[0,1,1]
	v_pk_fma_f32 v[96:97], v[196:197], v[142:143], v[96:97] op_sel_hi:[0,1,1]
	v_pk_fma_f32 v[112:113], v[200:201], v[142:143], v[112:113] op_sel_hi:[0,1,1]
	v_pk_fma_f32 v[28:29], v[204:205], v[142:143], v[28:29] op_sel_hi:[0,1,1]
	v_pk_fma_f32 v[80:81], v[192:193], v[144:145], v[80:81] op_sel_hi:[0,1,1]
	v_pk_fma_f32 v[98:99], v[196:197], v[144:145], v[98:99] op_sel_hi:[0,1,1]
	v_pk_fma_f32 v[114:115], v[200:201], v[144:145], v[114:115] op_sel_hi:[0,1,1]
	v_pk_fma_f32 v[30:31], v[204:205], v[144:145], v[30:31] op_sel_hi:[0,1,1]
	ds_read_b128 v[142:145], v61 offset:57344
	s_waitcnt lgkmcnt(7)
	v_pk_fma_f32 v[66:67], v[192:193], v[146:147], v[66:67] op_sel:[1,0,0]
	v_pk_fma_f32 v[82:83], v[196:197], v[146:147], v[82:83] op_sel:[1,0,0]
	v_pk_fma_f32 v[100:101], v[200:201], v[146:147], v[100:101] op_sel:[1,0,0]
	v_pk_fma_f32 v[116:117], v[204:205], v[146:147], v[116:117] op_sel:[1,0,0]
	v_pk_fma_f32 v[68:69], v[192:193], v[148:149], v[68:69] op_sel:[1,0,0]
	v_pk_fma_f32 v[84:85], v[196:197], v[148:149], v[84:85] op_sel:[1,0,0]
	v_pk_fma_f32 v[102:103], v[200:201], v[148:149], v[102:103] op_sel:[1,0,0]
	v_pk_fma_f32 v[118:119], v[204:205], v[148:149], v[118:119] op_sel:[1,0,0]
	ds_read_b128 v[146:149], v58 offset:61440
	s_waitcnt lgkmcnt(7)
	v_pk_fma_f32 v[70:71], v[192:193], v[150:151], v[70:71] op_sel:[1,0,0]
	v_pk_fma_f32 v[86:87], v[196:197], v[150:151], v[86:87] op_sel:[1,0,0]
	v_pk_fma_f32 v[104:105], v[200:201], v[150:151], v[104:105] op_sel:[1,0,0]
	v_pk_fma_f32 v[120:121], v[204:205], v[150:151], v[120:121] op_sel:[1,0,0]
	v_pk_fma_f32 v[72:73], v[192:193], v[152:153], v[72:73] op_sel:[1,0,0]
	v_pk_fma_f32 v[88:89], v[196:197], v[152:153], v[88:89] op_sel:[1,0,0]
	v_pk_fma_f32 v[106:107], v[200:201], v[152:153], v[106:107] op_sel:[1,0,0]
	v_pk_fma_f32 v[122:123], v[204:205], v[152:153], v[122:123] op_sel:[1,0,0]
	ds_read_b128 v[150:153], v59 offset:61440
	s_waitcnt lgkmcnt(7)
	v_pk_fma_f32 v[74:75], v[192:193], v[154:155], v[74:75] op_sel:[1,0,0]
	v_pk_fma_f32 v[90:91], v[196:197], v[154:155], v[90:91] op_sel:[1,0,0]
	v_pk_fma_f32 v[108:109], v[200:201], v[154:155], v[108:109] op_sel:[1,0,0]
	v_pk_fma_f32 v[24:25], v[204:205], v[154:155], v[24:25] op_sel:[1,0,0]
	v_pk_fma_f32 v[76:77], v[192:193], v[156:157], v[76:77] op_sel:[1,0,0]
	v_pk_fma_f32 v[94:95], v[196:197], v[156:157], v[94:95] op_sel:[1,0,0]
	v_pk_fma_f32 v[110:111], v[200:201], v[156:157], v[110:111] op_sel:[1,0,0]
	v_pk_fma_f32 v[26:27], v[204:205], v[156:157], v[26:27] op_sel:[1,0,0]
	ds_read_b128 v[154:157], v60 offset:61440
	s_waitcnt lgkmcnt(7)
	v_pk_fma_f32 v[78:79], v[192:193], v[44:45], v[78:79] op_sel:[1,0,0]
	v_pk_fma_f32 v[96:97], v[196:197], v[44:45], v[96:97] op_sel:[1,0,0]
	v_pk_fma_f32 v[112:113], v[200:201], v[44:45], v[112:113] op_sel:[1,0,0]
	v_pk_fma_f32 v[28:29], v[204:205], v[44:45], v[28:29] op_sel:[1,0,0]
	v_pk_fma_f32 v[80:81], v[192:193], v[46:47], v[80:81] op_sel:[1,0,0]
	v_pk_fma_f32 v[98:99], v[196:197], v[46:47], v[98:99] op_sel:[1,0,0]
	v_pk_fma_f32 v[114:115], v[200:201], v[46:47], v[114:115] op_sel:[1,0,0]
	v_pk_fma_f32 v[30:31], v[204:205], v[46:47], v[30:31] op_sel:[1,0,0]
	ds_read_b128 v[44:47], v61 offset:61440
	s_waitcnt lgkmcnt(7)
	v_pk_fma_f32 v[66:67], v[194:195], v[130:131], v[66:67] op_sel_hi:[0,1,1]
	v_pk_fma_f32 v[82:83], v[198:199], v[130:131], v[82:83] op_sel_hi:[0,1,1]
	v_pk_fma_f32 v[100:101], v[202:203], v[130:131], v[100:101] op_sel_hi:[0,1,1]
	v_pk_fma_f32 v[116:117], v[206:207], v[130:131], v[116:117] op_sel_hi:[0,1,1]
	v_pk_fma_f32 v[68:69], v[194:195], v[132:133], v[68:69] op_sel_hi:[0,1,1]
	v_pk_fma_f32 v[84:85], v[198:199], v[132:133], v[84:85] op_sel_hi:[0,1,1]
	v_pk_fma_f32 v[102:103], v[202:203], v[132:133], v[102:103] op_sel_hi:[0,1,1]
	v_pk_fma_f32 v[118:119], v[206:207], v[132:133], v[118:119] op_sel_hi:[0,1,1]
	s_waitcnt lgkmcnt(6)
	v_pk_fma_f32 v[70:71], v[194:195], v[134:135], v[70:71] op_sel_hi:[0,1,1]
	v_pk_fma_f32 v[86:87], v[198:199], v[134:135], v[86:87] op_sel_hi:[0,1,1]
	v_pk_fma_f32 v[104:105], v[202:203], v[134:135], v[104:105] op_sel_hi:[0,1,1]
	v_pk_fma_f32 v[120:121], v[206:207], v[134:135], v[120:121] op_sel_hi:[0,1,1]
	v_pk_fma_f32 v[72:73], v[194:195], v[136:137], v[72:73] op_sel_hi:[0,1,1]
	v_pk_fma_f32 v[88:89], v[198:199], v[136:137], v[88:89] op_sel_hi:[0,1,1]
	v_pk_fma_f32 v[106:107], v[202:203], v[136:137], v[106:107] op_sel_hi:[0,1,1]
	v_pk_fma_f32 v[122:123], v[206:207], v[136:137], v[122:123] op_sel_hi:[0,1,1]
	s_waitcnt lgkmcnt(5)
	v_pk_fma_f32 v[74:75], v[194:195], v[138:139], v[74:75] op_sel_hi:[0,1,1]
	v_pk_fma_f32 v[90:91], v[198:199], v[138:139], v[90:91] op_sel_hi:[0,1,1]
	v_pk_fma_f32 v[108:109], v[202:203], v[138:139], v[108:109] op_sel_hi:[0,1,1]
	v_pk_fma_f32 v[24:25], v[206:207], v[138:139], v[24:25] op_sel_hi:[0,1,1]
	v_pk_fma_f32 v[76:77], v[194:195], v[140:141], v[76:77] op_sel_hi:[0,1,1]
	v_pk_fma_f32 v[94:95], v[198:199], v[140:141], v[94:95] op_sel_hi:[0,1,1]
	v_pk_fma_f32 v[110:111], v[202:203], v[140:141], v[110:111] op_sel_hi:[0,1,1]
	v_pk_fma_f32 v[26:27], v[206:207], v[140:141], v[26:27] op_sel_hi:[0,1,1]
	s_waitcnt lgkmcnt(4)
	v_pk_fma_f32 v[78:79], v[194:195], v[142:143], v[78:79] op_sel_hi:[0,1,1]
	v_pk_fma_f32 v[96:97], v[198:199], v[142:143], v[96:97] op_sel_hi:[0,1,1]
	v_pk_fma_f32 v[112:113], v[202:203], v[142:143], v[112:113] op_sel_hi:[0,1,1]
	v_pk_fma_f32 v[28:29], v[206:207], v[142:143], v[28:29] op_sel_hi:[0,1,1]
	v_pk_fma_f32 v[80:81], v[194:195], v[144:145], v[80:81] op_sel_hi:[0,1,1]
	v_pk_fma_f32 v[98:99], v[198:199], v[144:145], v[98:99] op_sel_hi:[0,1,1]
	v_pk_fma_f32 v[114:115], v[202:203], v[144:145], v[114:115] op_sel_hi:[0,1,1]
	v_pk_fma_f32 v[30:31], v[206:207], v[144:145], v[30:31] op_sel_hi:[0,1,1]
	s_waitcnt lgkmcnt(3)
	v_pk_fma_f32 v[66:67], v[194:195], v[146:147], v[66:67] op_sel:[1,0,0]
	v_pk_fma_f32 v[82:83], v[198:199], v[146:147], v[82:83] op_sel:[1,0,0]
	v_pk_fma_f32 v[100:101], v[202:203], v[146:147], v[100:101] op_sel:[1,0,0]
	v_pk_fma_f32 v[116:117], v[206:207], v[146:147], v[116:117] op_sel:[1,0,0]
	v_pk_fma_f32 v[68:69], v[194:195], v[148:149], v[68:69] op_sel:[1,0,0]
	v_pk_fma_f32 v[84:85], v[198:199], v[148:149], v[84:85] op_sel:[1,0,0]
	v_pk_fma_f32 v[102:103], v[202:203], v[148:149], v[102:103] op_sel:[1,0,0]
	v_pk_fma_f32 v[118:119], v[206:207], v[148:149], v[118:119] op_sel:[1,0,0]
	s_waitcnt lgkmcnt(2)
	v_pk_fma_f32 v[70:71], v[194:195], v[150:151], v[70:71] op_sel:[1,0,0]
	v_pk_fma_f32 v[86:87], v[198:199], v[150:151], v[86:87] op_sel:[1,0,0]
	v_pk_fma_f32 v[104:105], v[202:203], v[150:151], v[104:105] op_sel:[1,0,0]
	v_pk_fma_f32 v[120:121], v[206:207], v[150:151], v[120:121] op_sel:[1,0,0]
	v_pk_fma_f32 v[72:73], v[194:195], v[152:153], v[72:73] op_sel:[1,0,0]
	v_pk_fma_f32 v[88:89], v[198:199], v[152:153], v[88:89] op_sel:[1,0,0]
	v_pk_fma_f32 v[106:107], v[202:203], v[152:153], v[106:107] op_sel:[1,0,0]
	v_pk_fma_f32 v[122:123], v[206:207], v[152:153], v[122:123] op_sel:[1,0,0]
	s_waitcnt lgkmcnt(1)
	v_pk_fma_f32 v[74:75], v[194:195], v[154:155], v[74:75] op_sel:[1,0,0]
	v_pk_fma_f32 v[90:91], v[198:199], v[154:155], v[90:91] op_sel:[1,0,0]
	v_pk_fma_f32 v[108:109], v[202:203], v[154:155], v[108:109] op_sel:[1,0,0]
	v_pk_fma_f32 v[24:25], v[206:207], v[154:155], v[24:25] op_sel:[1,0,0]
	v_pk_fma_f32 v[76:77], v[194:195], v[156:157], v[76:77] op_sel:[1,0,0]
	v_pk_fma_f32 v[94:95], v[198:199], v[156:157], v[94:95] op_sel:[1,0,0]
	v_pk_fma_f32 v[110:111], v[202:203], v[156:157], v[110:111] op_sel:[1,0,0]
	v_pk_fma_f32 v[26:27], v[206:207], v[156:157], v[26:27] op_sel:[1,0,0]
	s_waitcnt lgkmcnt(0)
	v_pk_fma_f32 v[78:79], v[194:195], v[44:45], v[78:79] op_sel:[1,0,0]
	v_pk_fma_f32 v[96:97], v[198:199], v[44:45], v[96:97] op_sel:[1,0,0]
	v_pk_fma_f32 v[112:113], v[202:203], v[44:45], v[112:113] op_sel:[1,0,0]
	v_pk_fma_f32 v[28:29], v[206:207], v[44:45], v[28:29] op_sel:[1,0,0]
	v_pk_fma_f32 v[80:81], v[194:195], v[46:47], v[80:81] op_sel:[1,0,0]
	v_pk_fma_f32 v[98:99], v[198:199], v[46:47], v[98:99] op_sel:[1,0,0]
	v_pk_fma_f32 v[114:115], v[202:203], v[46:47], v[114:115] op_sel:[1,0,0]
	v_pk_fma_f32 v[30:31], v[206:207], v[46:47], v[30:31] op_sel:[1,0,0]
	s_waitcnt lgkmcnt(0)
	ds_bpermute_b32 v160, v48, v240
	ds_bpermute_b32 v161, v48, v241
	ds_bpermute_b32 v162, v48, v242
	ds_bpermute_b32 v163, v48, v243
	s_waitcnt lgkmcnt(0)
	v_add_f32_e32 v240, v240, v160
	v_add_f32_e32 v241, v241, v161
	v_add_f32_e32 v242, v242, v162
	v_add_f32_e32 v243, v243, v163
	ds_bpermute_b32 v160, v49, v240
	ds_bpermute_b32 v161, v49, v241
	ds_bpermute_b32 v162, v49, v242
	ds_bpermute_b32 v163, v49, v243
	s_waitcnt lgkmcnt(0)
	v_add_f32_e32 v240, v240, v160
	v_add_f32_e32 v241, v241, v161
	v_add_f32_e32 v242, v242, v162
	v_add_f32_e32 v243, v243, v163
	ds_bpermute_b32 v160, v50, v240
	ds_bpermute_b32 v161, v50, v241
	ds_bpermute_b32 v162, v50, v242
	ds_bpermute_b32 v163, v50, v243
	s_waitcnt lgkmcnt(0)
	v_add_f32_e32 v240, v240, v160
	v_add_f32_e32 v241, v241, v161
	v_add_f32_e32 v242, v242, v162
	v_add_f32_e32 v243, v243, v163
	ds_bpermute_b32 v160, v51, v240
	ds_bpermute_b32 v161, v51, v241
	ds_bpermute_b32 v162, v51, v242
	ds_bpermute_b32 v163, v51, v243
	s_waitcnt lgkmcnt(0)
	v_add_f32_e32 v240, v240, v160
	v_add_f32_e32 v241, v241, v161
	v_add_f32_e32 v242, v242, v162
	v_add_f32_e32 v243, v243, v163
	ds_bpermute_b32 v160, v52, v240
	ds_bpermute_b32 v161, v52, v241
	ds_bpermute_b32 v162, v52, v242
	ds_bpermute_b32 v163, v52, v243
	s_waitcnt lgkmcnt(0)
	v_add_f32_e32 v240, v240, v160
	v_add_f32_e32 v241, v241, v161
	v_add_f32_e32 v242, v242, v162
	v_add_f32_e32 v243, v243, v163
	ds_bpermute_b32 v160, v53, v240
	ds_bpermute_b32 v161, v53, v241
	ds_bpermute_b32 v162, v53, v242
	ds_bpermute_b32 v163, v53, v243
	s_waitcnt lgkmcnt(0)
	v_add_f32_e32 v240, v240, v160
	v_add_f32_e32 v241, v241, v161
	v_add_f32_e32 v242, v242, v162
	v_add_f32_e32 v243, v243, v163
	v_cndmask_b32_e32 v164, v74, v66, vcc
	v_cndmask_b32_e32 v196, v66, v74, vcc
	ds_bpermute_b32 v196, v53, v196
	v_cndmask_b32_e32 v165, v75, v67, vcc
	v_cndmask_b32_e32 v197, v67, v75, vcc
	ds_bpermute_b32 v197, v53, v197
	v_cndmask_b32_e32 v166, v76, v68, vcc
	v_cndmask_b32_e32 v198, v68, v76, vcc
	ds_bpermute_b32 v198, v53, v198
	v_cndmask_b32_e32 v167, v77, v69, vcc
	v_cndmask_b32_e32 v199, v69, v77, vcc
	ds_bpermute_b32 v199, v53, v199
	v_cndmask_b32_e32 v168, v78, v70, vcc
	v_cndmask_b32_e32 v200, v70, v78, vcc
	ds_bpermute_b32 v200, v53, v200
	v_cndmask_b32_e32 v169, v79, v71, vcc
	v_cndmask_b32_e32 v201, v71, v79, vcc
	ds_bpermute_b32 v201, v53, v201
	v_cndmask_b32_e32 v170, v80, v72, vcc
	v_cndmask_b32_e32 v202, v72, v80, vcc
	ds_bpermute_b32 v202, v53, v202
	v_cndmask_b32_e32 v171, v81, v73, vcc
	v_cndmask_b32_e32 v203, v73, v81, vcc
	ds_bpermute_b32 v203, v53, v203
	v_cndmask_b32_e32 v172, v90, v82, vcc
	v_cndmask_b32_e32 v204, v82, v90, vcc
	ds_bpermute_b32 v204, v53, v204
	v_cndmask_b32_e32 v173, v91, v83, vcc
	v_cndmask_b32_e32 v205, v83, v91, vcc
	ds_bpermute_b32 v205, v53, v205
	v_cndmask_b32_e32 v174, v94, v84, vcc
	v_cndmask_b32_e32 v206, v84, v94, vcc
	ds_bpermute_b32 v206, v53, v206
	v_cndmask_b32_e32 v175, v95, v85, vcc
	v_cndmask_b32_e32 v207, v85, v95, vcc
	ds_bpermute_b32 v207, v53, v207
	v_cndmask_b32_e32 v176, v96, v86, vcc
	v_cndmask_b32_e32 v208, v86, v96, vcc
	ds_bpermute_b32 v208, v53, v208
	v_cndmask_b32_e32 v177, v97, v87, vcc
	v_cndmask_b32_e32 v209, v87, v97, vcc
	ds_bpermute_b32 v209, v53, v209
	v_cndmask_b32_e32 v178, v98, v88, vcc
	v_cndmask_b32_e32 v210, v88, v98, vcc
	ds_bpermute_b32 v210, v53, v210
	v_cndmask_b32_e32 v179, v99, v89, vcc
	v_cndmask_b32_e32 v211, v89, v99, vcc
	ds_bpermute_b32 v211, v53, v211
	v_cndmask_b32_e32 v180, v108, v100, vcc
	v_cndmask_b32_e32 v212, v100, v108, vcc
	ds_bpermute_b32 v212, v53, v212
	v_cndmask_b32_e32 v181, v109, v101, vcc
	v_cndmask_b32_e32 v213, v101, v109, vcc
	ds_bpermute_b32 v213, v53, v213
	v_cndmask_b32_e32 v182, v110, v102, vcc
	v_cndmask_b32_e32 v214, v102, v110, vcc
	ds_bpermute_b32 v214, v53, v214
	v_cndmask_b32_e32 v183, v111, v103, vcc
	v_cndmask_b32_e32 v215, v103, v111, vcc
	ds_bpermute_b32 v215, v53, v215
	v_cndmask_b32_e32 v184, v112, v104, vcc
	v_cndmask_b32_e32 v216, v104, v112, vcc
	ds_bpermute_b32 v216, v53, v216
	v_cndmask_b32_e32 v185, v113, v105, vcc
	v_cndmask_b32_e32 v217, v105, v113, vcc
	ds_bpermute_b32 v217, v53, v217
	v_cndmask_b32_e32 v186, v114, v106, vcc
	v_cndmask_b32_e32 v218, v106, v114, vcc
	ds_bpermute_b32 v218, v53, v218
	v_cndmask_b32_e32 v187, v115, v107, vcc
	v_cndmask_b32_e32 v219, v107, v115, vcc
	ds_bpermute_b32 v219, v53, v219
	v_cndmask_b32_e32 v188, v24, v116, vcc
	v_cndmask_b32_e32 v220, v116, v24, vcc
	ds_bpermute_b32 v220, v53, v220
	v_cndmask_b32_e32 v189, v25, v117, vcc
	v_cndmask_b32_e32 v221, v117, v25, vcc
	ds_bpermute_b32 v221, v53, v221
	v_cndmask_b32_e32 v190, v26, v118, vcc
	v_cndmask_b32_e32 v222, v118, v26, vcc
	ds_bpermute_b32 v222, v53, v222
	v_cndmask_b32_e32 v191, v27, v119, vcc
	v_cndmask_b32_e32 v223, v119, v27, vcc
	ds_bpermute_b32 v223, v53, v223
	v_cndmask_b32_e32 v192, v28, v120, vcc
	v_cndmask_b32_e32 v224, v120, v28, vcc
	ds_bpermute_b32 v224, v53, v224
	v_cndmask_b32_e32 v193, v29, v121, vcc
	v_cndmask_b32_e32 v225, v121, v29, vcc
	ds_bpermute_b32 v225, v53, v225
	v_cndmask_b32_e32 v194, v30, v122, vcc
	v_cndmask_b32_e32 v226, v122, v30, vcc
	ds_bpermute_b32 v226, v53, v226
	v_cndmask_b32_e32 v195, v31, v123, vcc
	v_cndmask_b32_e32 v227, v123, v31, vcc
	ds_bpermute_b32 v227, v53, v227
	s_waitcnt lgkmcnt(0)
	v_add_f32_e32 v164, v164, v196
	v_add_f32_e32 v165, v165, v197
	v_add_f32_e32 v166, v166, v198
	v_add_f32_e32 v167, v167, v199
	v_add_f32_e32 v168, v168, v200
	v_add_f32_e32 v169, v169, v201
	v_add_f32_e32 v170, v170, v202
	v_add_f32_e32 v171, v171, v203
	v_add_f32_e32 v172, v172, v204
	v_add_f32_e32 v173, v173, v205
	v_add_f32_e32 v174, v174, v206
	v_add_f32_e32 v175, v175, v207
	v_add_f32_e32 v176, v176, v208
	v_add_f32_e32 v177, v177, v209
	v_add_f32_e32 v178, v178, v210
	v_add_f32_e32 v179, v179, v211
	v_add_f32_e32 v180, v180, v212
	v_add_f32_e32 v181, v181, v213
	v_add_f32_e32 v182, v182, v214
	v_add_f32_e32 v183, v183, v215
	v_add_f32_e32 v184, v184, v216
	v_add_f32_e32 v185, v185, v217
	v_add_f32_e32 v186, v186, v218
	v_add_f32_e32 v187, v187, v219
	v_add_f32_e32 v188, v188, v220
	v_add_f32_e32 v189, v189, v221
	v_add_f32_e32 v190, v190, v222
	v_add_f32_e32 v191, v191, v223
	v_add_f32_e32 v192, v192, v224
	v_add_f32_e32 v193, v193, v225
	v_add_f32_e32 v194, v194, v226
	v_add_f32_e32 v195, v195, v227
	v_cndmask_b32_e64 v228, v168, v164, s[0:1]
	v_cndmask_b32_e64 v142, v164, v168, s[0:1]
	ds_bpermute_b32 v142, v52, v142
	v_cndmask_b32_e64 v229, v169, v165, s[0:1]
	v_cndmask_b32_e64 v143, v165, v169, s[0:1]
	ds_bpermute_b32 v143, v52, v143
	v_cndmask_b32_e64 v230, v170, v166, s[0:1]
	v_cndmask_b32_e64 v144, v166, v170, s[0:1]
	ds_bpermute_b32 v144, v52, v144
	v_cndmask_b32_e64 v231, v171, v167, s[0:1]
	v_cndmask_b32_e64 v145, v167, v171, s[0:1]
	ds_bpermute_b32 v145, v52, v145
	v_cndmask_b32_e64 v130, v176, v172, s[0:1]
	v_cndmask_b32_e64 v146, v172, v176, s[0:1]
	ds_bpermute_b32 v146, v52, v146
	v_cndmask_b32_e64 v131, v177, v173, s[0:1]
	v_cndmask_b32_e64 v147, v173, v177, s[0:1]
	ds_bpermute_b32 v147, v52, v147
	v_cndmask_b32_e64 v132, v178, v174, s[0:1]
	v_cndmask_b32_e64 v148, v174, v178, s[0:1]
	ds_bpermute_b32 v148, v52, v148
	v_cndmask_b32_e64 v133, v179, v175, s[0:1]
	v_cndmask_b32_e64 v149, v175, v179, s[0:1]
	ds_bpermute_b32 v149, v52, v149
	v_cndmask_b32_e64 v134, v184, v180, s[0:1]
	v_cndmask_b32_e64 v150, v180, v184, s[0:1]
	ds_bpermute_b32 v150, v52, v150
	v_cndmask_b32_e64 v135, v185, v181, s[0:1]
	v_cndmask_b32_e64 v151, v181, v185, s[0:1]
	ds_bpermute_b32 v151, v52, v151
	v_cndmask_b32_e64 v136, v186, v182, s[0:1]
	v_cndmask_b32_e64 v152, v182, v186, s[0:1]
	ds_bpermute_b32 v152, v52, v152
	v_cndmask_b32_e64 v137, v187, v183, s[0:1]
	v_cndmask_b32_e64 v153, v183, v187, s[0:1]
	ds_bpermute_b32 v153, v52, v153
	v_cndmask_b32_e64 v138, v192, v188, s[0:1]
	v_cndmask_b32_e64 v154, v188, v192, s[0:1]
	ds_bpermute_b32 v154, v52, v154
	v_cndmask_b32_e64 v139, v193, v189, s[0:1]
	v_cndmask_b32_e64 v155, v189, v193, s[0:1]
	ds_bpermute_b32 v155, v52, v155
	v_cndmask_b32_e64 v140, v194, v190, s[0:1]
	v_cndmask_b32_e64 v156, v190, v194, s[0:1]
	ds_bpermute_b32 v156, v52, v156
	v_cndmask_b32_e64 v141, v195, v191, s[0:1]
	v_cndmask_b32_e64 v157, v191, v195, s[0:1]
	ds_bpermute_b32 v157, v52, v157
	s_waitcnt lgkmcnt(0)
	v_add_f32_e32 v228, v228, v142
	v_add_f32_e32 v229, v229, v143
	v_add_f32_e32 v230, v230, v144
	v_add_f32_e32 v231, v231, v145
	v_add_f32_e32 v130, v130, v146
	v_add_f32_e32 v131, v131, v147
	v_add_f32_e32 v132, v132, v148
	v_add_f32_e32 v133, v133, v149
	v_add_f32_e32 v134, v134, v150
	v_add_f32_e32 v135, v135, v151
	v_add_f32_e32 v136, v136, v152
	v_add_f32_e32 v137, v137, v153
	v_add_f32_e32 v138, v138, v154
	v_add_f32_e32 v139, v139, v155
	v_add_f32_e32 v140, v140, v156
	v_add_f32_e32 v141, v141, v157
	v_cndmask_b32_e64 v44, v230, v228, s[2:3]
	v_cndmask_b32_e64 v200, v228, v230, s[2:3]
	ds_bpermute_b32 v200, v51, v200
	v_cndmask_b32_e64 v45, v231, v229, s[2:3]
	v_cndmask_b32_e64 v201, v229, v231, s[2:3]
	ds_bpermute_b32 v201, v51, v201
	v_cndmask_b32_e64 v46, v132, v130, s[2:3]
	v_cndmask_b32_e64 v202, v130, v132, s[2:3]
	ds_bpermute_b32 v202, v51, v202
	v_cndmask_b32_e64 v47, v133, v131, s[2:3]
	v_cndmask_b32_e64 v203, v131, v133, s[2:3]
	ds_bpermute_b32 v203, v51, v203
	v_cndmask_b32_e64 v196, v136, v134, s[2:3]
	v_cndmask_b32_e64 v204, v134, v136, s[2:3]
	ds_bpermute_b32 v204, v51, v204
	v_cndmask_b32_e64 v197, v137, v135, s[2:3]
	v_cndmask_b32_e64 v205, v135, v137, s[2:3]
	ds_bpermute_b32 v205, v51, v205
	v_cndmask_b32_e64 v198, v140, v138, s[2:3]
	v_cndmask_b32_e64 v206, v138, v140, s[2:3]
	ds_bpermute_b32 v206, v51, v206
	v_cndmask_b32_e64 v199, v141, v139, s[2:3]
	v_cndmask_b32_e64 v207, v139, v141, s[2:3]
	ds_bpermute_b32 v207, v51, v207
	s_waitcnt lgkmcnt(0)
	v_add_f32_e32 v44, v44, v200
	v_add_f32_e32 v45, v45, v201
	v_add_f32_e32 v46, v46, v202
	v_add_f32_e32 v47, v47, v203
	v_add_f32_e32 v196, v196, v204
	v_add_f32_e32 v197, v197, v205
	v_add_f32_e32 v198, v198, v206
	v_add_f32_e32 v199, v199, v207
	v_cndmask_b32_e64 v208, v45, v44, s[4:5]
	v_cndmask_b32_e64 v212, v44, v45, s[4:5]
	ds_bpermute_b32 v212, v50, v212
	v_cndmask_b32_e64 v209, v47, v46, s[4:5]
	v_cndmask_b32_e64 v213, v46, v47, s[4:5]
	ds_bpermute_b32 v213, v50, v213
	v_cndmask_b32_e64 v210, v197, v196, s[4:5]
	v_cndmask_b32_e64 v214, v196, v197, s[4:5]
	ds_bpermute_b32 v214, v50, v214
	v_cndmask_b32_e64 v211, v199, v198, s[4:5]
	v_cndmask_b32_e64 v215, v198, v199, s[4:5]
	ds_bpermute_b32 v215, v50, v215
	s_waitcnt lgkmcnt(0)
	v_add_f32_e32 v208, v208, v212
	v_add_f32_e32 v209, v209, v213
	v_add_f32_e32 v210, v210, v214
	v_add_f32_e32 v211, v211, v215
	ds_bpermute_b32 v216, v49, v208
	ds_bpermute_b32 v217, v49, v209
	ds_bpermute_b32 v218, v49, v210
	ds_bpermute_b32 v219, v49, v211
	s_waitcnt lgkmcnt(0)
	v_add_f32_e32 v208, v208, v216
	v_add_f32_e32 v209, v209, v217
	v_add_f32_e32 v210, v210, v218
	v_add_f32_e32 v211, v211, v219
	ds_bpermute_b32 v216, v48, v208
	ds_bpermute_b32 v217, v48, v209
	ds_bpermute_b32 v218, v48, v210
	ds_bpermute_b32 v219, v48, v211
	s_waitcnt lgkmcnt(0)
	v_add_f32_e32 v208, v208, v216
	v_add_f32_e32 v209, v209, v217
	v_add_f32_e32 v210, v210, v218
	v_add_f32_e32 v211, v211, v219
	v_fmamk_f32 v224, v240, 0x3a000000, v125
	v_cmp_gt_f32_e64 s[10:11], s13, v224
	v_mul_f32_e32 v225, 0x4b800000, v224
	s_nop 0
	v_cndmask_b32_e64 v225, v224, v225, s[10:11]
	v_rsq_f32_e32 v224, v225
	s_nop 1
	v_mul_f32_e32 v225, 0x45800000, v224
	v_cndmask_b32_e64 v220, v224, v225, s[10:11]
	v_fmamk_f32 v224, v241, 0x3a000000, v125
	v_cmp_gt_f32_e64 s[10:11], s13, v224
	v_mul_f32_e32 v225, 0x4b800000, v224
	s_nop 0
	v_cndmask_b32_e64 v225, v224, v225, s[10:11]
	v_rsq_f32_e32 v224, v225
	s_nop 1
	v_mul_f32_e32 v225, 0x45800000, v224
	v_cndmask_b32_e64 v221, v224, v225, s[10:11]
	v_fmamk_f32 v224, v242, 0x3a000000, v125
	v_cmp_gt_f32_e64 s[10:11], s13, v224
	v_mul_f32_e32 v225, 0x4b800000, v224
	s_nop 0
	v_cndmask_b32_e64 v225, v224, v225, s[10:11]
	v_rsq_f32_e32 v224, v225
	s_nop 1
	v_mul_f32_e32 v225, 0x45800000, v224
	v_cndmask_b32_e64 v222, v224, v225, s[10:11]
	v_fmamk_f32 v224, v243, 0x3a000000, v125
	v_cmp_gt_f32_e64 s[10:11], s13, v224
	v_mul_f32_e32 v225, 0x4b800000, v224
	s_nop 0
	v_cndmask_b32_e64 v225, v224, v225, s[10:11]
	v_rsq_f32_e32 v224, v225
	s_nop 1
	v_mul_f32_e32 v225, 0x45800000, v224
	v_cndmask_b32_e64 v223, v224, v225, s[10:11]
	v_and_b32_e32 v224, 1, v93
	v_cmp_ne_u32_e64 s[24:25], 0, v224
	v_and_b32_e32 v225, 2, v93
	v_cmp_ne_u32_e64 s[26:27], 0, v225
	s_nop 1
	v_cndmask_b32_e64 v226, v208, v209, s[24:25]
	v_cndmask_b32_e64 v142, v210, v211, s[24:25]
	v_cndmask_b32_e64 v226, v226, v142, s[26:27]
	v_cndmask_b32_e64 v227, v220, v221, s[24:25]
	v_cndmask_b32_e64 v142, v222, v223, s[24:25]
	v_cndmask_b32_e64 v227, v227, v142, s[26:27]
	s_waitcnt vmcnt(63)
	v_mov_b32_e32 v1, v253
	v_fmac_f32_e32 v1, v227, v226
	v_cmp_nlt_f32_e64 s[10:11], s31, v1
	s_and_saveexec_b64 s[28:29], s[10:11]
	s_cbranch_execz .Lmy_partb4_sp
	v_mul_f32_e32 v2, 0x3fb8aa3b, v1
	v_rndne_f32_e32 v3, v2
	v_sub_f32_e32 v4, v2, v3
	v_fma_f32 v2, v1, s34, -v2
	v_fmac_f32_e32 v2, 0x32a5705f, v1
	v_add_f32_e32 v2, v4, v2
	v_cvt_i32_f32_e32 v3, v3
	v_exp_f32_e32 v2, v2
	v_cmp_ngt_f32_e64 s[10:11], s35, v1
	v_ldexp_f32 v2, v2, v3
	s_nop 0
	v_cndmask_b32_e64 v2, 0, v2, s[10:11]
	v_cmp_nlt_f32_e64 s[10:11], s36, v1
	s_nop 1
	v_cndmask_b32_e64 v1, v127, v2, s[10:11]
	v_add_f32_e32 v4, 1.0, v1
	v_add_f32_e32 v2, -1.0, v4
	v_sub_f32_e32 v3, v2, v4
	v_add_f32_e32 v3, 1.0, v3
	v_sub_f32_e32 v2, v1, v2
	v_add_f32_e32 v5, v2, v3
	v_frexp_mant_f32_e32 v6, v4
	v_cvt_f64_f32_e32 v[2:3], v4
	v_frexp_exp_i32_f64_e32 v2, v[2:3]
	v_cmp_gt_f32_e64 s[10:11], s38, v6
	s_nop 1
	v_subbrev_co_u32_e64 v10, s[10:11], 0, v2, s[10:11]
	v_sub_u32_e32 v2, 0, v10
	v_ldexp_f32 v3, v4, v2
	v_add_f32_e32 v4, -1.0, v3
	v_add_f32_e32 v6, 1.0, v3
	v_ldexp_f32 v2, v5, v2
	v_add_f32_e32 v5, 1.0, v4
	v_add_f32_e32 v7, -1.0, v6
	v_sub_f32_e32 v5, v3, v5
	v_sub_f32_e32 v3, v3, v7
	v_add_f32_e32 v5, v2, v5
	v_add_f32_e32 v2, v2, v3
	v_add_f32_e32 v11, v6, v2
	v_rcp_f32_e32 v13, v11
	v_sub_f32_e32 v3, v6, v11
	v_add_f32_e32 v12, v2, v3
	v_add_f32_e32 v3, v4, v5
	v_mul_f32_e32 v15, v3, v13
	v_sub_f32_e32 v2, v4, v3
	v_mul_f32_e32 v4, v11, v15
	v_fma_f32 v6, v15, v11, -v4
	v_fmac_f32_e32 v6, v15, v12
	v_add_f32_e32 v14, v5, v2
	v_add_f32_e32 v2, v4, v6
	v_sub_f32_e32 v5, v3, v2
	v_pk_add_f32 v[8:9], v[2:3], v[4:5] neg_lo:[0,1] neg_hi:[0,1]
	v_mov_b32_e32 v7, v2
	v_pk_add_f32 v[2:3], v[8:9], v[6:7] neg_lo:[0,1] neg_hi:[0,1]
	v_cmp_neq_f32_e64 s[10:11], s37, v1
	v_add_f32_e32 v3, v14, v3
	v_add_f32_e32 v2, v2, v3
	v_add_f32_e32 v3, v5, v2
	v_mul_f32_e32 v14, v13, v3
	v_mul_f32_e32 v4, v11, v14
	v_fma_f32 v6, v14, v11, -v4
	v_fmac_f32_e32 v6, v14, v12
	v_sub_f32_e32 v5, v5, v3
	v_add_f32_e32 v11, v2, v5
	v_add_f32_e32 v2, v4, v6
	v_sub_f32_e32 v5, v3, v2
	v_pk_add_f32 v[8:9], v[2:3], v[4:5] neg_lo:[0,1] neg_hi:[0,1]
	v_mov_b32_e32 v7, v2
	v_pk_add_f32 v[2:3], v[8:9], v[6:7] neg_lo:[0,1] neg_hi:[0,1]
	s_nop 0
	v_add_f32_e32 v3, v11, v3
	v_add_f32_e32 v2, v2, v3
	v_add_f32_e32 v3, v15, v14
	v_add_f32_e32 v2, v5, v2
	v_sub_f32_e32 v4, v3, v15
	v_mul_f32_e32 v2, v13, v2
	v_sub_f32_e32 v4, v14, v4
	v_add_f32_e32 v4, v4, v2
	v_add_f32_e32 v6, v3, v4
	v_mul_f32_e32 v7, v6, v6
	v_fmamk_f32 v2, v7, 0x3e9b6dac, v126
	v_fmaak_f32 v43, v7, v2, 0x3f2aaada
	v_cvt_f32_i32_e32 v2, v10
	v_sub_f32_e32 v3, v6, v3
	v_sub_f32_e32 v3, v4, v3
	v_ldexp_f32 v8, v3, 1
	v_mul_f32_e32 v3, v6, v7
	v_ldexp_f32 v5, v6, 1
	v_pk_mul_f32 v[6:7], v[2:3], v[42:43]
	s_nop 0
	v_fma_f32 v4, v2, s39, -v6
	v_fmac_f32_e32 v4, 0xb102e308, v2
	v_pk_add_f32 v[2:3], v[6:7], v[4:5]
	s_nop 0
	v_sub_f32_e32 v5, v3, v5
	v_sub_f32_e32 v5, v7, v5
	v_add_f32_e32 v9, v8, v5
	v_mov_b32_e32 v8, v6
	v_pk_add_f32 v[6:7], v[2:3], v[6:7] neg_lo:[0,1] neg_hi:[0,1]
	v_pk_add_f32 v[10:11], v[2:3], v[8:9]
	v_mov_b32_e32 v5, v2
	v_mov_b32_e32 v7, v11
	v_pk_add_f32 v[12:13], v[4:5], v[6:7] neg_lo:[0,1] neg_hi:[0,1]
	v_pk_add_f32 v[4:5], v[4:5], v[6:7]
	v_mov_b32_e32 v8, v9
	v_pk_add_f32 v[6:7], v[4:5], v[2:3] op_sel:[1,0] op_sel_hi:[0,1] neg_lo:[0,1] neg_hi:[0,1]
	v_pk_add_f32 v[14:15], v[10:11], v[6:7] op_sel_hi:[1,0] neg_lo:[0,1] neg_hi:[0,1]
	v_mov_b32_e32 v10, v11
	v_mov_b32_e32 v11, v5
	v_pk_mov_b32 v[6:7], v[2:3], v[6:7] op_sel:[1,0]
	v_mov_b32_e32 v9, v2
	v_pk_add_f32 v[6:7], v[10:11], v[6:7] neg_lo:[0,1] neg_hi:[0,1]
	v_mov_b32_e32 v14, v12
	v_pk_add_f32 v[2:3], v[8:9], v[6:7] neg_lo:[0,1] neg_hi:[0,1]
	v_mov_b32_e32 v13, v5
	v_pk_add_f32 v[6:7], v[14:15], v[2:3]
	s_nop 0
	v_pk_add_f32 v[8:9], v[6:7], v[6:7] op_sel:[0,1] op_sel_hi:[1,0]
	s_nop 0
	v_pk_add_f32 v[4:5], v[4:5], v[8:9] op_sel:[1,0] op_sel_hi:[0,1]
	v_mov_b32_e32 v7, v4
	v_pk_add_f32 v[10:11], v[6:7], v[12:13] neg_lo:[0,1] neg_hi:[0,1]
	v_mov_b32_e32 v3, v8
	v_sub_f32_e32 v5, v6, v10
	v_pk_add_f32 v[2:3], v[2:3], v[10:11] neg_lo:[0,1] neg_hi:[0,1]
	v_sub_f32_e32 v5, v12, v5
	v_add_f32_e32 v2, v2, v5
	v_add_f32_e32 v2, v2, v3
	v_add_f32_e32 v2, v4, v2
	v_cndmask_b32_e64 v2, v127, v2, s[10:11]
	v_cmp_lt_f32_e64 s[10:11], |v1|, s40
	s_nop 1
	v_cndmask_b32_e64 v1, v2, v1, s[10:11]
.Lmy_partb4_sp:
	s_or_b64 exec, exec, s[28:29]
	v_and_b32_e32 v144, 3, v93
	v_mov_b32_e32 v145, 0
	v_lshlrev_b32_e32 v146, 17, v144
	v_mov_b32_e32 v147, 0
	v_lshl_add_u64 v[146:147], v[36:37], 0, v[146:147]
	v_lshl_add_u64 v[146:147], s[84:85], 0, v[146:147]
	global_store_dword v[146:147], v1, off sc0 sc1
	v_lshlrev_b32_e32 v148, 13, v144
	v_mov_b32_e32 v149, 0
	v_lshl_add_u64 v[148:149], v[34:35], 0, v[148:149]
	v_lshl_add_u64 v[148:149], s[84:85], 0, v[148:149]
	v_cmp_gt_u32_e64 s[10:11], 4, v93
	s_and_saveexec_b64 s[28:29], s[10:11]
	global_store_dword v[148:149], v227, off sc0 sc1
	s_or_b64 exec, exec, s[28:29]

.LBB0_208:
	s_waitcnt lgkmcnt(0)
	global_load_dwordx4 v[14:17], v[2:3], off offset:-4096 nt
	global_load_dwordx4 v[18:21], v[2:3], off offset:-3072 nt
	global_load_dwordx4 v[22:25], v[2:3], off offset:-2048 nt
	global_load_dwordx4 v[26:29], v[2:3], off offset:-1024 nt
	global_load_dwordx4 v[30:33], v[2:3], off nt
	global_load_dwordx4 v[34:37], v[2:3], off offset:1024 nt
	global_load_dwordx4 v[38:41], v[2:3], off offset:2048 nt
	global_load_dwordx4 v[42:45], v[2:3], off offset:3072 nt
	v_lshl_add_u64 v[46:47], s[84:85], 0, v[4:5]
	v_add_co_u32_e64 v46, s[0:1], s13, v46
	s_waitcnt vmcnt(7)
	v_mul_f32_e32 v13, v15, v15
	v_mul_f32_e32 v48, v17, v17
	s_waitcnt vmcnt(6)
	v_mul_f32_e32 v49, v19, v19
	v_mul_f32_e32 v50, v21, v21
	s_waitcnt vmcnt(5)
	v_mul_f32_e32 v51, v23, v23
	v_mul_f32_e32 v52, v25, v25
	v_fmac_f32_e32 v13, v14, v14
	v_fmac_f32_e32 v48, v16, v16
	v_fmac_f32_e32 v49, v18, v18
	v_fmac_f32_e32 v50, v20, v20
	s_waitcnt vmcnt(4)
	v_mul_f32_e32 v53, v27, v27
	v_mul_f32_e32 v54, v29, v29
	v_fmac_f32_e32 v51, v22, v22
	v_fmac_f32_e32 v52, v24, v24
	v_add_f32_e32 v13, v13, v48
	v_add_f32_e32 v48, v49, v50
	s_waitcnt vmcnt(3)
	v_mul_f32_e32 v55, v31, v31
	v_mul_f32_e32 v56, v33, v33
	v_fmac_f32_e32 v53, v26, v26
	v_fmac_f32_e32 v54, v28, v28
	v_add_f32_e32 v49, v51, v52
	v_add_f32_e32 v13, v13, v48
	s_waitcnt vmcnt(2)
	v_mul_f32_e32 v57, v35, v35
	v_mul_f32_e32 v58, v37, v37
	v_fmac_f32_e32 v55, v30, v30
	v_fmac_f32_e32 v56, v32, v32
	v_add_f32_e32 v50, v53, v54
	v_add_f32_e32 v13, v13, v49
	s_waitcnt vmcnt(1)
	v_mul_f32_e32 v59, v39, v39
	v_mul_f32_e32 v60, v41, v41
	v_fmac_f32_e32 v57, v34, v34
	v_fmac_f32_e32 v58, v36, v36
	v_add_f32_e32 v51, v55, v56
	v_add_f32_e32 v13, v13, v50
	s_waitcnt vmcnt(0)
	v_mul_f32_e32 v61, v43, v43
	v_mul_f32_e32 v62, v45, v45
	v_fmac_f32_e32 v59, v38, v38
	v_fmac_f32_e32 v60, v40, v40
	v_add_f32_e32 v52, v57, v58
	v_add_f32_e32 v13, v13, v51
	v_fmac_f32_e32 v61, v42, v42
	v_fmac_f32_e32 v62, v44, v44
	v_add_f32_e32 v53, v59, v60
	v_add_f32_e32 v13, v13, v52
	v_add_f32_e32 v54, v61, v62
	v_add_f32_e32 v13, v13, v53
	v_add_f32_e32 v13, v13, v54
	ds_bpermute_b32 v48, v6, v13
	v_cvt_pk_bf16_f32 v14, v14, v15
	v_cvt_pk_bf16_f32 v15, v16, v17
	v_addc_co_u32_e64 v47, s[0:1], 0, v47, s[0:1]
	s_waitcnt lgkmcnt(0)
	v_add_f32_e32 v13, v13, v48
	ds_bpermute_b32 v16, v7, v13
	global_store_dwordx2 v[46:47], v[14:15], off sc0 sc1
	v_cvt_pk_bf16_f32 v14, v18, v19
	v_cvt_pk_bf16_f32 v15, v20, v21
	global_store_dwordx2 v[46:47], v[14:15], off offset:512 sc0 sc1
	s_waitcnt lgkmcnt(0)
	v_add_f32_e32 v13, v13, v16
	ds_bpermute_b32 v16, v8, v13
	v_cvt_pk_bf16_f32 v14, v22, v23
	v_cvt_pk_bf16_f32 v15, v24, v25
	global_store_dwordx2 v[46:47], v[14:15], off offset:1024 sc0 sc1
	v_cvt_pk_bf16_f32 v14, v26, v27
	s_waitcnt lgkmcnt(0)
	v_add_f32_e32 v13, v13, v16
	ds_bpermute_b32 v16, v9, v13
	v_cvt_pk_bf16_f32 v15, v28, v29
	global_store_dwordx2 v[46:47], v[14:15], off offset:1536 sc0 sc1
	v_cvt_pk_bf16_f32 v14, v30, v31
	v_cvt_pk_bf16_f32 v15, v32, v33
	s_waitcnt lgkmcnt(0)
	v_add_f32_e32 v13, v13, v16
	ds_bpermute_b32 v17, v10, v13
	global_store_dwordx2 v[46:47], v[14:15], off offset:2048 sc0 sc1
	v_cvt_pk_bf16_f32 v14, v34, v35
	v_cvt_pk_bf16_f32 v15, v36, v37
	global_store_dwordx2 v[46:47], v[14:15], off offset:2560 sc0 sc1
	s_waitcnt lgkmcnt(0)
	v_add_f32_e32 v13, v13, v17
	ds_bpermute_b32 v14, v11, v13
	v_cvt_pk_bf16_f32 v16, v38, v39
	v_cvt_pk_bf16_f32 v17, v40, v41
	global_store_dwordx2 v[46:47], v[16:17], off offset:3072 sc0 sc1
	v_cvt_pk_bf16_f32 v16, v42, v43
	v_cvt_pk_bf16_f32 v17, v44, v45
	global_store_dwordx2 v[46:47], v[16:17], off offset:3584 sc0 sc1
	s_and_saveexec_b64 s[14:15], vcc
	s_cbranch_execz .LBB0_207
	s_waitcnt lgkmcnt(0)
	v_add_f32_e32 v13, v13, v14
	v_fmamk_f32 v13, v13, 0x3a000000, v12
	v_mul_f32_e32 v14, 0x4b800000, v13
	v_cmp_gt_f32_e64 s[0:1], s16, v13
	s_nop 1
	v_cndmask_b32_e64 v13, v13, v14, s[0:1]
	v_rsq_f32_e32 v13, v13
	s_nop 0
	v_mul_f32_e32 v14, 0x45800000, v13
	v_cndmask_b32_e64 v13, v13, v14, s[0:1]
	v_lshl_add_u64 v[14:15], s[84:85], 0, v[0:1]
	global_store_dword v[14:15], v13, off sc0 sc1
	s_branch .LBB0_207
